# v136 with low-half workgroups lowering priority after MFMA group 4 instead of 5 (re-tune under guarded barriers)
# speedup vs baseline: 1.0226x; 1.0134x over previous
; #define LWRITE(S, buf) do { bf16_t* sA_ = sbase + (buf) * BUF; bf16_t* sB_ = sA_ + 256 * PITCH; \
;     _Pragma("unroll") for (int i_ = 0; i_ < 4; ++i_) *(u32x4*)(sA_ + (sr + i_ * 64) * PITCH + scv * 8) = ra[S][i_]; \
;     _Pragma("unroll") for (int i_ = 0; i_ < 2; ++i_) *(u32x4*)(sB_ + (sr + i_ * 64) * PITCH + scv * 8) = rb[S][i_]; } while (0)
; template <class Epi>
; DI void gemm_tile(char* smem, const bf16_t* __restrict__ A0, int lda0, int ksplit, const bf16_t* __restrict__ A1, int lda1,
;                   const bf16_t* __restrict__ Bt, int K, int row0, int col0, const Epi& epi, int tid) {
;     ...
;   __syncthreads();
;   {
;     const int last = nk - 1;
;     GLOAD(0, 0);
;     __builtin_amdgcn_sched_barrier(0);
;     GLOAD(1, 1);
;     __builtin_amdgcn_sched_barrier(0);
;     LWRITE(0, 0);
;     __builtin_amdgcn_sched_barrier(0);
;     GLOAD(0, (2 < last ? 2 : last));
;     __builtin_amdgcn_sched_barrier(0);
;     __syncthreads();
;     for (int kt = 0; kt < nk; kt += 2) {
;       LWRITE(1, 1);
;       __builtin_amdgcn_sched_barrier(0);
;       GLOAD(1, (kt + 3 < last ? kt + 3 : last));
;       __builtin_amdgcn_sched_barrier(0);
;       COMPUTE(0);
;       __syncthreads();
;       LWRITE(0, 0);
;       __builtin_amdgcn_sched_barrier(0);
;       GLOAD(0, (kt + 4 < last ? kt + 4 : last));
;       __builtin_amdgcn_sched_barrier(0);
;       COMPUTE(1);
;       __syncthreads();
;     }
.Lg1_kloop:
	s_waitcnt vmcnt(6)
	s_waitcnt lgkmcnt(0)
	s_barrier
	v_add_u32_e32 v232, s31, v230
	v_add_u32_e32 v233, s31, v231
	s_add_u32 s22, s30, s100
	s_setprio 1
	v_mfma_f32_16x16x32_bf16 v[0:3], v[128:131], v[144:147], v[0:3]
	v_mfma_f32_16x16x32_bf16 v[4:7], v[132:135], v[144:147], v[4:7]
	v_mfma_f32_16x16x32_bf16 v[8:11], v[136:139], v[144:147], v[8:11]
	v_mfma_f32_16x16x32_bf16 v[12:15], v[140:143], v[144:147], v[12:15]
	ds_read_b128 v[176:179], v233 offset:0
	ds_read_b128 v[180:183], v233 offset:1024
	s_add_u32 m0, s22, 0
	s_nop 0
	global_load_lds_dwordx4 v224, s[0:1]
	v_mfma_f32_16x16x32_bf16 v[16:19], v[128:131], v[148:151], v[16:19]
	v_mfma_f32_16x16x32_bf16 v[20:23], v[132:135], v[148:151], v[20:23]
	v_mfma_f32_16x16x32_bf16 v[24:27], v[136:139], v[148:151], v[24:27]
	v_mfma_f32_16x16x32_bf16 v[28:31], v[140:143], v[148:151], v[28:31]
	ds_read_b128 v[184:187], v233 offset:2048
	ds_read_b128 v[188:191], v233 offset:3072
	s_add_u32 m0, s22, 4096
	s_nop 0
	global_load_lds_dwordx4 v225, s[0:1]
	v_mfma_f32_16x16x32_bf16 v[32:35], v[128:131], v[152:155], v[32:35]
	v_mfma_f32_16x16x32_bf16 v[36:39], v[132:135], v[152:155], v[36:39]
	v_mfma_f32_16x16x32_bf16 v[40:43], v[136:139], v[152:155], v[40:43]
	v_mfma_f32_16x16x32_bf16 v[44:47], v[140:143], v[152:155], v[44:47]
	ds_read_b128 v[192:195], v232 offset:0
	ds_read_b128 v[196:199], v232 offset:1024
	s_add_u32 m0, s22, 8192
	s_nop 0
	global_load_lds_dwordx4 v226, s[0:1]
	v_mfma_f32_16x16x32_bf16 v[48:51], v[128:131], v[156:159], v[48:51]
	v_mfma_f32_16x16x32_bf16 v[52:55], v[132:135], v[156:159], v[52:55]
	v_mfma_f32_16x16x32_bf16 v[56:59], v[136:139], v[156:159], v[56:59]
	v_mfma_f32_16x16x32_bf16 v[60:63], v[140:143], v[156:159], v[60:63]
	ds_read_b128 v[200:203], v232 offset:2048
	ds_read_b128 v[204:207], v232 offset:3072
	s_add_u32 m0, s22, 12288
	s_nop 0
	global_load_lds_dwordx4 v227, s[0:1]
	v_mfma_f32_16x16x32_bf16 v[64:67], v[128:131], v[160:163], v[64:67]
	v_mfma_f32_16x16x32_bf16 v[68:71], v[132:135], v[160:163], v[68:71]
	v_mfma_f32_16x16x32_bf16 v[72:75], v[136:139], v[160:163], v[72:75]
	v_mfma_f32_16x16x32_bf16 v[76:79], v[140:143], v[160:163], v[76:79]
	ds_read_b128 v[208:211], v232 offset:4096
	s_add_u32 m0, s22, 16384
	s_nop 0
	global_load_lds_dwordx4 v228, s[2:3]
	s_cmp_eq_u32 s21, 0
	s_cbranch_scc0 .Lg1_hi0
	s_setprio 0
.Lg1_hi0:
	v_mfma_f32_16x16x32_bf16 v[80:83], v[128:131], v[164:167], v[80:83]
	v_mfma_f32_16x16x32_bf16 v[84:87], v[132:135], v[164:167], v[84:87]
	v_mfma_f32_16x16x32_bf16 v[88:91], v[136:139], v[164:167], v[88:91]
	v_mfma_f32_16x16x32_bf16 v[92:95], v[140:143], v[164:167], v[92:95]
	ds_read_b128 v[212:215], v232 offset:5120
	s_add_u32 m0, s22, 20480
	s_nop 0
	global_load_lds_dwordx4 v229, s[2:3]
	v_mfma_f32_16x16x32_bf16 v[96:99], v[128:131], v[168:171], v[96:99]
	v_mfma_f32_16x16x32_bf16 v[100:103], v[132:135], v[168:171], v[100:103]
	v_mfma_f32_16x16x32_bf16 v[104:107], v[136:139], v[168:171], v[104:107]
	v_mfma_f32_16x16x32_bf16 v[108:111], v[140:143], v[168:171], v[108:111]
	ds_read_b128 v[216:219], v232 offset:6144
	s_add_u32 s0, s0, 64
	s_addc_u32 s1, s1, 0
	s_add_u32 s2, s2, 64
	s_addc_u32 s3, s3, 0
	s_add_u32 s99, s99, 1
	s_add_u32 s30, s30, 24576
	s_cmp_eq_u32 s30, 73728
	s_cselect_b32 s30, 0, s30
	s_add_u32 s31, s31, 24576
	s_cmp_eq_u32 s31, 73728
	s_cselect_b32 s31, 0, s31
	v_mfma_f32_16x16x32_bf16 v[112:115], v[128:131], v[172:175], v[112:115]
	v_mfma_f32_16x16x32_bf16 v[116:119], v[132:135], v[172:175], v[116:119]
	v_mfma_f32_16x16x32_bf16 v[120:123], v[136:139], v[172:175], v[120:123]
	v_mfma_f32_16x16x32_bf16 v[124:127], v[140:143], v[172:175], v[124:127]
	ds_read_b128 v[220:223], v232 offset:7168
	s_waitcnt vmcnt(6)
	s_waitcnt lgkmcnt(0)
	s_barrier
	v_add_u32_e32 v232, s31, v230
	v_add_u32_e32 v233, s31, v231
	s_add_u32 s22, s30, s100
	s_setprio 1
	v_mfma_f32_16x16x32_bf16 v[0:3], v[176:179], v[192:195], v[0:3]
	v_mfma_f32_16x16x32_bf16 v[4:7], v[180:183], v[192:195], v[4:7]
	v_mfma_f32_16x16x32_bf16 v[8:11], v[184:187], v[192:195], v[8:11]
	v_mfma_f32_16x16x32_bf16 v[12:15], v[188:191], v[192:195], v[12:15]
	ds_read_b128 v[128:131], v233 offset:0
	ds_read_b128 v[132:135], v233 offset:1024
	s_add_u32 m0, s22, 0
	s_nop 0
	global_load_lds_dwordx4 v224, s[0:1]
	v_mfma_f32_16x16x32_bf16 v[16:19], v[176:179], v[196:199], v[16:19]
	v_mfma_f32_16x16x32_bf16 v[20:23], v[180:183], v[196:199], v[20:23]
	v_mfma_f32_16x16x32_bf16 v[24:27], v[184:187], v[196:199], v[24:27]
	v_mfma_f32_16x16x32_bf16 v[28:31], v[188:191], v[196:199], v[28:31]
	ds_read_b128 v[136:139], v233 offset:2048
	ds_read_b128 v[140:143], v233 offset:3072
	s_add_u32 m0, s22, 4096
	s_nop 0
	global_load_lds_dwordx4 v225, s[0:1]
	v_mfma_f32_16x16x32_bf16 v[32:35], v[176:179], v[200:203], v[32:35]
	v_mfma_f32_16x16x32_bf16 v[36:39], v[180:183], v[200:203], v[36:39]
	v_mfma_f32_16x16x32_bf16 v[40:43], v[184:187], v[200:203], v[40:43]
	v_mfma_f32_16x16x32_bf16 v[44:47], v[188:191], v[200:203], v[44:47]
	ds_read_b128 v[144:147], v232 offset:0
	ds_read_b128 v[148:151], v232 offset:1024
	s_add_u32 m0, s22, 8192
	s_nop 0
	global_load_lds_dwordx4 v226, s[0:1]
	v_mfma_f32_16x16x32_bf16 v[48:51], v[176:179], v[204:207], v[48:51]
	v_mfma_f32_16x16x32_bf16 v[52:55], v[180:183], v[204:207], v[52:55]
	v_mfma_f32_16x16x32_bf16 v[56:59], v[184:187], v[204:207], v[56:59]
	v_mfma_f32_16x16x32_bf16 v[60:63], v[188:191], v[204:207], v[60:63]
	ds_read_b128 v[152:155], v232 offset:2048
	ds_read_b128 v[156:159], v232 offset:3072
	s_add_u32 m0, s22, 12288
	s_nop 0
	global_load_lds_dwordx4 v227, s[0:1]
	v_mfma_f32_16x16x32_bf16 v[64:67], v[176:179], v[208:211], v[64:67]
	v_mfma_f32_16x16x32_bf16 v[68:71], v[180:183], v[208:211], v[68:71]
	v_mfma_f32_16x16x32_bf16 v[72:75], v[184:187], v[208:211], v[72:75]
	v_mfma_f32_16x16x32_bf16 v[76:79], v[188:191], v[208:211], v[76:79]
	ds_read_b128 v[160:163], v232 offset:4096
	s_add_u32 m0, s22, 16384
	s_nop 0
	global_load_lds_dwordx4 v228, s[2:3]
	s_cmp_eq_u32 s21, 0
	s_cbranch_scc0 .Lg1_hi1
	s_setprio 0
; #define LWRITE(S, buf) do { bf16_t* sA_ = sbase + (buf) * BUF; bf16_t* sB_ = sA_ + 256 * PITCH; \
;     _Pragma("unroll") for (int i_ = 0; i_ < 4; ++i_) *(u32x4*)(sA_ + (sr + i_ * 64) * PITCH + scv * 8) = ra[S][i_]; \
;     _Pragma("unroll") for (int i_ = 0; i_ < 2; ++i_) *(u32x4*)(sB_ + (sr + i_ * 64) * PITCH + scv * 8) = rb[S][i_]; } while (0)
; template <class Epi>
; DI void gemm_tile(char* smem, const bf16_t* __restrict__ A0, int lda0, int ksplit, const bf16_t* __restrict__ A1, int lda1,
;                   const bf16_t* __restrict__ Bt, int K, int row0, int col0, const Epi& epi, int tid) {
;     ...
;   __syncthreads();
;   {
;     const int last = nk - 1;
;     GLOAD(0, 0);
;     __builtin_amdgcn_sched_barrier(0);
;     GLOAD(1, 1);
;     __builtin_amdgcn_sched_barrier(0);
;     LWRITE(0, 0);
;     __builtin_amdgcn_sched_barrier(0);
;     GLOAD(0, (2 < last ? 2 : last));
;     __builtin_amdgcn_sched_barrier(0);
;     __syncthreads();
;     for (int kt = 0; kt < nk; kt += 2) {
;       LWRITE(1, 1);
;       __builtin_amdgcn_sched_barrier(0);
;       GLOAD(1, (kt + 3 < last ? kt + 3 : last));
;       __builtin_amdgcn_sched_barrier(0);
;       COMPUTE(0);
;       __syncthreads();
;       LWRITE(0, 0);
;       __builtin_amdgcn_sched_barrier(0);
;       GLOAD(0, (kt + 4 < last ? kt + 4 : last));
;       __builtin_amdgcn_sched_barrier(0);
;       COMPUTE(1);
;       __syncthreads();
;     }
.Lg1_hi1:
	v_mfma_f32_16x16x32_bf16 v[80:83], v[176:179], v[212:215], v[80:83]
	v_mfma_f32_16x16x32_bf16 v[84:87], v[180:183], v[212:215], v[84:87]
	v_mfma_f32_16x16x32_bf16 v[88:91], v[184:187], v[212:215], v[88:91]
	v_mfma_f32_16x16x32_bf16 v[92:95], v[188:191], v[212:215], v[92:95]
	ds_read_b128 v[164:167], v232 offset:5120
	s_add_u32 m0, s22, 20480
	s_nop 0
	global_load_lds_dwordx4 v229, s[2:3]
	v_mfma_f32_16x16x32_bf16 v[96:99], v[176:179], v[216:219], v[96:99]
	v_mfma_f32_16x16x32_bf16 v[100:103], v[180:183], v[216:219], v[100:103]
	v_mfma_f32_16x16x32_bf16 v[104:107], v[184:187], v[216:219], v[104:107]
	v_mfma_f32_16x16x32_bf16 v[108:111], v[188:191], v[216:219], v[108:111]
	ds_read_b128 v[168:171], v232 offset:6144
	s_add_u32 s0, s0, 64
	s_addc_u32 s1, s1, 0
	s_add_u32 s2, s2, 64
	s_addc_u32 s3, s3, 0
	s_add_u32 s99, s99, 1
	s_add_u32 s30, s30, 24576
	s_cmp_eq_u32 s30, 73728
	s_cselect_b32 s30, 0, s30
	s_add_u32 s31, s31, 24576
	s_cmp_eq_u32 s31, 73728
	s_cselect_b32 s31, 0, s31
	v_mfma_f32_16x16x32_bf16 v[112:115], v[176:179], v[220:223], v[112:115]
	v_mfma_f32_16x16x32_bf16 v[116:119], v[180:183], v[220:223], v[116:119]
	v_mfma_f32_16x16x32_bf16 v[120:123], v[184:187], v[220:223], v[120:123]
	v_mfma_f32_16x16x32_bf16 v[124:127], v[188:191], v[220:223], v[124:127]
	ds_read_b128 v[172:175], v232 offset:7168
	s_add_u32 s98, s98, 2
	s_cmp_lt_u32 s98, 28
	s_cbranch_scc1 .Lg1_kloop
	s_waitcnt vmcnt(6)
	s_waitcnt lgkmcnt(0)
	s_barrier
	v_add_u32_e32 v232, s31, v230
	v_add_u32_e32 v233, s31, v231
	s_add_u32 s22, s30, s100
	s_setprio 1
	v_mfma_f32_16x16x32_bf16 v[0:3], v[128:131], v[144:147], v[0:3]
	v_mfma_f32_16x16x32_bf16 v[4:7], v[132:135], v[144:147], v[4:7]
	v_mfma_f32_16x16x32_bf16 v[8:11], v[136:139], v[144:147], v[8:11]
	v_mfma_f32_16x16x32_bf16 v[12:15], v[140:143], v[144:147], v[12:15]
	ds_read_b128 v[176:179], v233 offset:0
	ds_read_b128 v[180:183], v233 offset:1024
	s_add_u32 m0, s22, 0
	s_nop 0
	global_load_lds_dwordx4 v224, s[0:1]
	v_mfma_f32_16x16x32_bf16 v[16:19], v[128:131], v[148:151], v[16:19]
	v_mfma_f32_16x16x32_bf16 v[20:23], v[132:135], v[148:151], v[20:23]
	v_mfma_f32_16x16x32_bf16 v[24:27], v[136:139], v[148:151], v[24:27]
	v_mfma_f32_16x16x32_bf16 v[28:31], v[140:143], v[148:151], v[28:31]
	ds_read_b128 v[184:187], v233 offset:2048
	ds_read_b128 v[188:191], v233 offset:3072
	s_add_u32 m0, s22, 4096
	s_nop 0
	global_load_lds_dwordx4 v225, s[0:1]
	v_mfma_f32_16x16x32_bf16 v[32:35], v[128:131], v[152:155], v[32:35]
	v_mfma_f32_16x16x32_bf16 v[36:39], v[132:135], v[152:155], v[36:39]
	v_mfma_f32_16x16x32_bf16 v[40:43], v[136:139], v[152:155], v[40:43]
	v_mfma_f32_16x16x32_bf16 v[44:47], v[140:143], v[152:155], v[44:47]
	ds_read_b128 v[192:195], v232 offset:0
	ds_read_b128 v[196:199], v232 offset:1024
	s_add_u32 m0, s22, 8192
	s_nop 0
	global_load_lds_dwordx4 v226, s[0:1]
	v_mfma_f32_16x16x32_bf16 v[48:51], v[128:131], v[156:159], v[48:51]
	v_mfma_f32_16x16x32_bf16 v[52:55], v[132:135], v[156:159], v[52:55]
	v_mfma_f32_16x16x32_bf16 v[56:59], v[136:139], v[156:159], v[56:59]
	v_mfma_f32_16x16x32_bf16 v[60:63], v[140:143], v[156:159], v[60:63]
	ds_read_b128 v[200:203], v232 offset:2048
	ds_read_b128 v[204:207], v232 offset:3072
	s_add_u32 m0, s22, 12288
	s_nop 0
	global_load_lds_dwordx4 v227, s[0:1]
	v_mfma_f32_16x16x32_bf16 v[64:67], v[128:131], v[160:163], v[64:67]
	v_mfma_f32_16x16x32_bf16 v[68:71], v[132:135], v[160:163], v[68:71]
	v_mfma_f32_16x16x32_bf16 v[72:75], v[136:139], v[160:163], v[72:75]
	v_mfma_f32_16x16x32_bf16 v[76:79], v[140:143], v[160:163], v[76:79]
	ds_read_b128 v[208:211], v232 offset:4096
	s_add_u32 m0, s22, 16384
	s_nop 0
	global_load_lds_dwordx4 v228, s[2:3]
	s_cmp_eq_u32 s21, 0
	s_cbranch_scc0 .Lg1_hi2
	s_setprio 0
.Lg1_hi2:
	v_mfma_f32_16x16x32_bf16 v[80:83], v[128:131], v[164:167], v[80:83]
	v_mfma_f32_16x16x32_bf16 v[84:87], v[132:135], v[164:167], v[84:87]
	v_mfma_f32_16x16x32_bf16 v[88:91], v[136:139], v[164:167], v[88:91]
	v_mfma_f32_16x16x32_bf16 v[92:95], v[140:143], v[164:167], v[92:95]
	ds_read_b128 v[212:215], v232 offset:5120
	s_add_u32 m0, s22, 20480
	s_nop 0
	global_load_lds_dwordx4 v229, s[2:3]
	v_mfma_f32_16x16x32_bf16 v[96:99], v[128:131], v[168:171], v[96:99]
	v_mfma_f32_16x16x32_bf16 v[100:103], v[132:135], v[168:171], v[100:103]
	v_mfma_f32_16x16x32_bf16 v[104:107], v[136:139], v[168:171], v[104:107]
	v_mfma_f32_16x16x32_bf16 v[108:111], v[140:143], v[168:171], v[108:111]
	ds_read_b128 v[216:219], v232 offset:6144
	s_add_u32 s0, s0, 64
	s_addc_u32 s1, s1, 0
	s_add_u32 s2, s2, 64
	s_addc_u32 s3, s3, 0
	s_add_u32 s99, s99, 1
	s_add_u32 s30, s30, 24576
	s_cmp_eq_u32 s30, 73728
	s_cselect_b32 s30, 0, s30
	s_add_u32 s31, s31, 24576
	s_cmp_eq_u32 s31, 73728
	s_cselect_b32 s31, 0, s31
	v_mfma_f32_16x16x32_bf16 v[112:115], v[128:131], v[172:175], v[112:115]
	v_mfma_f32_16x16x32_bf16 v[116:119], v[132:135], v[172:175], v[116:119]
	v_mfma_f32_16x16x32_bf16 v[120:123], v[136:139], v[172:175], v[120:123]
	v_mfma_f32_16x16x32_bf16 v[124:127], v[140:143], v[172:175], v[124:127]
	ds_read_b128 v[220:223], v232 offset:7168
	s_waitcnt vmcnt(6)
	s_waitcnt lgkmcnt(0)
	s_barrier
	v_add_u32_e32 v232, s31, v230
	v_add_u32_e32 v233, s31, v231
	s_setprio 1
	v_mfma_f32_16x16x32_bf16 v[0:3], v[176:179], v[192:195], v[0:3]
	v_mfma_f32_16x16x32_bf16 v[4:7], v[180:183], v[192:195], v[4:7]
	v_mfma_f32_16x16x32_bf16 v[8:11], v[184:187], v[192:195], v[8:11]
	v_mfma_f32_16x16x32_bf16 v[12:15], v[188:191], v[192:195], v[12:15]
	ds_read_b128 v[128:131], v233 offset:0
	ds_read_b128 v[132:135], v233 offset:1024
	v_mfma_f32_16x16x32_bf16 v[16:19], v[176:179], v[196:199], v[16:19]
	v_mfma_f32_16x16x32_bf16 v[20:23], v[180:183], v[196:199], v[20:23]
	v_mfma_f32_16x16x32_bf16 v[24:27], v[184:187], v[196:199], v[24:27]
	v_mfma_f32_16x16x32_bf16 v[28:31], v[188:191], v[196:199], v[28:31]
	ds_read_b128 v[136:139], v233 offset:2048
	ds_read_b128 v[140:143], v233 offset:3072
	v_mfma_f32_16x16x32_bf16 v[32:35], v[176:179], v[200:203], v[32:35]
	v_mfma_f32_16x16x32_bf16 v[36:39], v[180:183], v[200:203], v[36:39]
	v_mfma_f32_16x16x32_bf16 v[40:43], v[184:187], v[200:203], v[40:43]
	v_mfma_f32_16x16x32_bf16 v[44:47], v[188:191], v[200:203], v[44:47]
	ds_read_b128 v[144:147], v232 offset:0
	ds_read_b128 v[148:151], v232 offset:1024
	v_mfma_f32_16x16x32_bf16 v[48:51], v[176:179], v[204:207], v[48:51]
	v_mfma_f32_16x16x32_bf16 v[52:55], v[180:183], v[204:207], v[52:55]
	v_mfma_f32_16x16x32_bf16 v[56:59], v[184:187], v[204:207], v[56:59]
	v_mfma_f32_16x16x32_bf16 v[60:63], v[188:191], v[204:207], v[60:63]
	ds_read_b128 v[152:155], v232 offset:2048
	ds_read_b128 v[156:159], v232 offset:3072
	v_mfma_f32_16x16x32_bf16 v[64:67], v[176:179], v[208:211], v[64:67]
	v_mfma_f32_16x16x32_bf16 v[68:71], v[180:183], v[208:211], v[68:71]
	v_mfma_f32_16x16x32_bf16 v[72:75], v[184:187], v[208:211], v[72:75]
	v_mfma_f32_16x16x32_bf16 v[76:79], v[188:191], v[208:211], v[76:79]
	ds_read_b128 v[160:163], v232 offset:4096
	s_cmp_eq_u32 s21, 0
	s_cbranch_scc0 .Lg1_hi3
	s_setprio 0
; #define LWRITE(S, buf) do { bf16_t* sA_ = sbase + (buf) * BUF; bf16_t* sB_ = sA_ + 256 * PITCH; \
;     _Pragma("unroll") for (int i_ = 0; i_ < 4; ++i_) *(u32x4*)(sA_ + (sr + i_ * 64) * PITCH + scv * 8) = ra[S][i_]; \
;     _Pragma("unroll") for (int i_ = 0; i_ < 2; ++i_) *(u32x4*)(sB_ + (sr + i_ * 64) * PITCH + scv * 8) = rb[S][i_]; } while (0)
; template <class Epi>
; DI void gemm_tile(char* smem, const bf16_t* __restrict__ A0, int lda0, int ksplit, const bf16_t* __restrict__ A1, int lda1,
;                   const bf16_t* __restrict__ Bt, int K, int row0, int col0, const Epi& epi, int tid) {
;     ...
;   __syncthreads();
;   {
;     const int last = nk - 1;
;     GLOAD(0, 0);
;     __builtin_amdgcn_sched_barrier(0);
;     GLOAD(1, 1);
;     __builtin_amdgcn_sched_barrier(0);
;     LWRITE(0, 0);
;     __builtin_amdgcn_sched_barrier(0);
;     GLOAD(0, (2 < last ? 2 : last));
;     __builtin_amdgcn_sched_barrier(0);
;     __syncthreads();
;     for (int kt = 0; kt < nk; kt += 2) {
;       LWRITE(1, 1);
;       __builtin_amdgcn_sched_barrier(0);
;       GLOAD(1, (kt + 3 < last ? kt + 3 : last));
;       __builtin_amdgcn_sched_barrier(0);
;       COMPUTE(0);
;       __syncthreads();
;       LWRITE(0, 0);
;       __builtin_amdgcn_sched_barrier(0);
;       GLOAD(0, (kt + 4 < last ? kt + 4 : last));
;       __builtin_amdgcn_sched_barrier(0);
;       COMPUTE(1);
;       __syncthreads();
;     }
.Lg1_hi3:
	v_mfma_f32_16x16x32_bf16 v[80:83], v[176:179], v[212:215], v[80:83]
	v_mfma_f32_16x16x32_bf16 v[84:87], v[180:183], v[212:215], v[84:87]
	v_mfma_f32_16x16x32_bf16 v[88:91], v[184:187], v[212:215], v[88:91]
	v_mfma_f32_16x16x32_bf16 v[92:95], v[188:191], v[212:215], v[92:95]
	ds_read_b128 v[164:167], v232 offset:5120
	v_mfma_f32_16x16x32_bf16 v[96:99], v[176:179], v[216:219], v[96:99]
	v_mfma_f32_16x16x32_bf16 v[100:103], v[180:183], v[216:219], v[100:103]
	v_mfma_f32_16x16x32_bf16 v[104:107], v[184:187], v[216:219], v[104:107]
	v_mfma_f32_16x16x32_bf16 v[108:111], v[188:191], v[216:219], v[108:111]
	ds_read_b128 v[168:171], v232 offset:6144
	s_add_u32 s31, s31, 24576
	s_cmp_eq_u32 s31, 73728
	s_cselect_b32 s31, 0, s31
	v_mfma_f32_16x16x32_bf16 v[112:115], v[176:179], v[220:223], v[112:115]
	v_mfma_f32_16x16x32_bf16 v[116:119], v[180:183], v[220:223], v[116:119]
	v_mfma_f32_16x16x32_bf16 v[120:123], v[184:187], v[220:223], v[120:123]
	v_mfma_f32_16x16x32_bf16 v[124:127], v[188:191], v[220:223], v[124:127]
	ds_read_b128 v[172:175], v232 offset:7168
	s_waitcnt vmcnt(0)
	s_waitcnt lgkmcnt(0)
	s_barrier
	v_add_u32_e32 v232, s31, v230
	v_add_u32_e32 v233, s31, v231
	s_setprio 1
	v_mfma_f32_16x16x32_bf16 v[0:3], v[128:131], v[144:147], v[0:3]
	v_mfma_f32_16x16x32_bf16 v[4:7], v[132:135], v[144:147], v[4:7]
	v_mfma_f32_16x16x32_bf16 v[8:11], v[136:139], v[144:147], v[8:11]
	v_mfma_f32_16x16x32_bf16 v[12:15], v[140:143], v[144:147], v[12:15]
	ds_read_b128 v[176:179], v233 offset:0
	ds_read_b128 v[180:183], v233 offset:1024
	v_mfma_f32_16x16x32_bf16 v[16:19], v[128:131], v[148:151], v[16:19]
	v_mfma_f32_16x16x32_bf16 v[20:23], v[132:135], v[148:151], v[20:23]
	v_mfma_f32_16x16x32_bf16 v[24:27], v[136:139], v[148:151], v[24:27]
	v_mfma_f32_16x16x32_bf16 v[28:31], v[140:143], v[148:151], v[28:31]
	ds_read_b128 v[184:187], v233 offset:2048
	ds_read_b128 v[188:191], v233 offset:3072
	v_mfma_f32_16x16x32_bf16 v[32:35], v[128:131], v[152:155], v[32:35]
	v_mfma_f32_16x16x32_bf16 v[36:39], v[132:135], v[152:155], v[36:39]
	v_mfma_f32_16x16x32_bf16 v[40:43], v[136:139], v[152:155], v[40:43]
	v_mfma_f32_16x16x32_bf16 v[44:47], v[140:143], v[152:155], v[44:47]
	ds_read_b128 v[192:195], v232 offset:0
	ds_read_b128 v[196:199], v232 offset:1024
	v_mfma_f32_16x16x32_bf16 v[48:51], v[128:131], v[156:159], v[48:51]
	v_mfma_f32_16x16x32_bf16 v[52:55], v[132:135], v[156:159], v[52:55]
	v_mfma_f32_16x16x32_bf16 v[56:59], v[136:139], v[156:159], v[56:59]
	v_mfma_f32_16x16x32_bf16 v[60:63], v[140:143], v[156:159], v[60:63]
	ds_read_b128 v[200:203], v232 offset:2048
	ds_read_b128 v[204:207], v232 offset:3072
	v_mfma_f32_16x16x32_bf16 v[64:67], v[128:131], v[160:163], v[64:67]
	v_mfma_f32_16x16x32_bf16 v[68:71], v[132:135], v[160:163], v[68:71]
	v_mfma_f32_16x16x32_bf16 v[72:75], v[136:139], v[160:163], v[72:75]
	v_mfma_f32_16x16x32_bf16 v[76:79], v[140:143], v[160:163], v[76:79]
	ds_read_b128 v[208:211], v232 offset:4096
	s_cmp_eq_u32 s21, 0
	s_cbranch_scc0 .Lg1_hi4
	s_setprio 0
.Lg1_hi4:
	v_mfma_f32_16x16x32_bf16 v[80:83], v[128:131], v[164:167], v[80:83]
	v_mfma_f32_16x16x32_bf16 v[84:87], v[132:135], v[164:167], v[84:87]
	v_mfma_f32_16x16x32_bf16 v[88:91], v[136:139], v[164:167], v[88:91]
	v_mfma_f32_16x16x32_bf16 v[92:95], v[140:143], v[164:167], v[92:95]
	ds_read_b128 v[212:215], v232 offset:5120
	v_mfma_f32_16x16x32_bf16 v[96:99], v[128:131], v[168:171], v[96:99]
	v_mfma_f32_16x16x32_bf16 v[100:103], v[132:135], v[168:171], v[100:103]
	v_mfma_f32_16x16x32_bf16 v[104:107], v[136:139], v[168:171], v[104:107]
	v_mfma_f32_16x16x32_bf16 v[108:111], v[140:143], v[168:171], v[108:111]
	ds_read_b128 v[216:219], v232 offset:6144
	s_add_u32 s31, s31, 24576
	s_cmp_eq_u32 s31, 73728
	s_cselect_b32 s31, 0, s31
	v_mfma_f32_16x16x32_bf16 v[112:115], v[128:131], v[172:175], v[112:115]
	v_mfma_f32_16x16x32_bf16 v[116:119], v[132:135], v[172:175], v[116:119]
	v_mfma_f32_16x16x32_bf16 v[120:123], v[136:139], v[172:175], v[120:123]
	v_mfma_f32_16x16x32_bf16 v[124:127], v[140:143], v[172:175], v[124:127]
	ds_read_b128 v[220:223], v232 offset:7168
	s_waitcnt lgkmcnt(0)
	s_barrier
	s_setprio 1
	v_mfma_f32_16x16x32_bf16 v[0:3], v[176:179], v[192:195], v[0:3]
	v_mfma_f32_16x16x32_bf16 v[4:7], v[180:183], v[192:195], v[4:7]
	v_mfma_f32_16x16x32_bf16 v[8:11], v[184:187], v[192:195], v[8:11]
	v_mfma_f32_16x16x32_bf16 v[12:15], v[188:191], v[192:195], v[12:15]
	v_mfma_f32_16x16x32_bf16 v[16:19], v[176:179], v[196:199], v[16:19]
	v_mfma_f32_16x16x32_bf16 v[20:23], v[180:183], v[196:199], v[20:23]
	v_mfma_f32_16x16x32_bf16 v[24:27], v[184:187], v[196:199], v[24:27]
	v_mfma_f32_16x16x32_bf16 v[28:31], v[188:191], v[196:199], v[28:31]
	v_mfma_f32_16x16x32_bf16 v[32:35], v[176:179], v[200:203], v[32:35]
	v_mfma_f32_16x16x32_bf16 v[36:39], v[180:183], v[200:203], v[36:39]
	v_mfma_f32_16x16x32_bf16 v[40:43], v[184:187], v[200:203], v[40:43]
	v_mfma_f32_16x16x32_bf16 v[44:47], v[188:191], v[200:203], v[44:47]
	v_mfma_f32_16x16x32_bf16 v[48:51], v[176:179], v[204:207], v[48:51]
	v_mfma_f32_16x16x32_bf16 v[52:55], v[180:183], v[204:207], v[52:55]
	v_mfma_f32_16x16x32_bf16 v[56:59], v[184:187], v[204:207], v[56:59]
	v_mfma_f32_16x16x32_bf16 v[60:63], v[188:191], v[204:207], v[60:63]
	v_mfma_f32_16x16x32_bf16 v[64:67], v[176:179], v[208:211], v[64:67]
	v_mfma_f32_16x16x32_bf16 v[68:71], v[180:183], v[208:211], v[68:71]
	v_mfma_f32_16x16x32_bf16 v[72:75], v[184:187], v[208:211], v[72:75]
	v_mfma_f32_16x16x32_bf16 v[76:79], v[188:191], v[208:211], v[76:79]
	s_cmp_eq_u32 s21, 0
	s_cbranch_scc0 .Lg1_hi5
	s_setprio 0
.Lg1_hi5:
	v_mfma_f32_16x16x32_bf16 v[80:83], v[176:179], v[212:215], v[80:83]
	v_mfma_f32_16x16x32_bf16 v[84:87], v[180:183], v[212:215], v[84:87]
	v_mfma_f32_16x16x32_bf16 v[88:91], v[184:187], v[212:215], v[88:91]
	v_mfma_f32_16x16x32_bf16 v[92:95], v[188:191], v[212:215], v[92:95]
	v_mfma_f32_16x16x32_bf16 v[96:99], v[176:179], v[216:219], v[96:99]
	v_mfma_f32_16x16x32_bf16 v[100:103], v[180:183], v[216:219], v[100:103]
	v_mfma_f32_16x16x32_bf16 v[104:107], v[184:187], v[216:219], v[104:107]
	v_mfma_f32_16x16x32_bf16 v[108:111], v[188:191], v[216:219], v[108:111]
	v_mfma_f32_16x16x32_bf16 v[112:115], v[176:179], v[220:223], v[112:115]
	v_mfma_f32_16x16x32_bf16 v[116:119], v[180:183], v[220:223], v[116:119]
	v_mfma_f32_16x16x32_bf16 v[120:123], v[184:187], v[220:223], v[120:123]
	v_mfma_f32_16x16x32_bf16 v[124:127], v[188:191], v[220:223], v[124:127]
	s_branch .Lg1_epi

; #define LWRITE(S, buf) do { bf16_t* sA_ = sbase + (buf) * BUF; bf16_t* sB_ = sA_ + 256 * PITCH; \
;     _Pragma("unroll") for (int i_ = 0; i_ < 4; ++i_) *(u32x4*)(sA_ + (sr + i_ * 64) * PITCH + scv * 8) = ra[S][i_]; \
;     _Pragma("unroll") for (int i_ = 0; i_ < 2; ++i_) *(u32x4*)(sB_ + (sr + i_ * 64) * PITCH + scv * 8) = rb[S][i_]; } while (0)
; template <class Epi>
; DI void gemm_tile(char* smem, const bf16_t* __restrict__ A0, int lda0, int ksplit, const bf16_t* __restrict__ A1, int lda1,
;                   const bf16_t* __restrict__ Bt, int K, int row0, int col0, const Epi& epi, int tid) {
;     ...
;   f32x4 acc[8][4];
; #pragma unroll
;   for (int m = 0; m < 8; ++m)
; #pragma unroll
;     for (int n = 0; n < 4; ++n) acc[m][n] = (f32x4){0.f, 0.f, 0.f, 0.f};
;   u32x4 ra[2][4], rb[2][2];
;   const int nk = K / BK;
;   const int sr = tid >> 2, scv = tid & 3;
;     ...
;   __syncthreads();
;   {
;     const int last = nk - 1;
;     GLOAD(0, 0);
;     __builtin_amdgcn_sched_barrier(0);
;     GLOAD(1, 1);
;     __builtin_amdgcn_sched_barrier(0);
;     LWRITE(0, 0);
;     __builtin_amdgcn_sched_barrier(0);
;     GLOAD(0, (2 < last ? 2 : last));
;     __builtin_amdgcn_sched_barrier(0);
;     __syncthreads();
; template <class Epi>
; DI void gemm_phase(char* smem, const bf16_t* A0, int lda0, int ksplit, const bf16_t* A1, int lda1, const bf16_t* Bt, int K, int nN, const Epi& epi, int tid) {
;     ...
;     const int x = blockIdx.x & 7, l = blockIdx.x >> 3, L = G >> 3, per = 8 * nN, tot = 2 * per;
;     for (int q = l; q < tot; q += L) { const int rgl = q / per, rem = q % per, ct = rem >> 3, rt = (x * 2 + rgl) * 8 + (rem & 7);
;       gemm_tile(smem, A0, lda0, ksplit, A1, lda1, Bt, K, rt * 256, ct * 128, epi, tid); }
.Lg3a_tile:
	s_cmpk_ge_u32 s15, 64
	s_cbranch_scc1 .Lg3a_done
	s_cmpk_ge_u32 s15, 32
	s_cselect_b32 s27, 1, 0
	s_cselect_b32 s26, 32, 0
	s_sub_u32 s26, s15, s26
	s_add_u32 s27, s27, s101
	s_lshl_b32 s27, s27, 3
	s_and_b32 s29, s26, 7
	s_add_u32 s29, s29, s27
	s_lshl_b32 s29, s29, 8
	s_lshr_b32 s28, s26, 3
	s_lshl_b32 s28, s28, 7
	s_mul_i32 s27, s29, 512
	s_add_u32 s27, s27, 0x1ea00000
	s_add_u32 s0, s92, s27
	s_addc_u32 s1, s93, 0
	s_mul_i32 s27, s28, 128
	s_add_u32 s27, s27, 0x34a0000
	s_add_u32 s2, s92, s27
	s_addc_u32 s3, s93, 0
	s_waitcnt lgkmcnt(0)
	s_barrier
	s_mov_b32 s99, 0
	s_mov_b32 s30, 0
	s_add_u32 s26, s30, s100
	s_add_u32 m0, s26, 0
	s_nop 0
	global_load_lds_dwordx4 v224, s[0:1]
	s_add_u32 m0, s26, 4096
	s_nop 0
	global_load_lds_dwordx4 v225, s[0:1]
	s_add_u32 m0, s26, 8192
	s_nop 0
	global_load_lds_dwordx4 v226, s[0:1]
	s_add_u32 m0, s26, 12288
	s_nop 0
	global_load_lds_dwordx4 v227, s[0:1]
	s_add_u32 m0, s26, 16384
	s_nop 0
	global_load_lds_dwordx4 v228, s[2:3]
	s_add_u32 m0, s26, 20480
	s_nop 0
	global_load_lds_dwordx4 v229, s[2:3]
	s_add_u32 s0, s0, 64
	s_addc_u32 s1, s1, 0
	s_add_u32 s2, s2, 64
	s_addc_u32 s3, s3, 0
	s_add_u32 s99, s99, 1
	s_add_u32 s30, s30, 24576
	s_cmp_eq_u32 s30, 73728
	s_cselect_b32 s30, 0, s30
	s_add_u32 s26, s30, s100
	s_add_u32 m0, s26, 0
	s_nop 0
	global_load_lds_dwordx4 v224, s[0:1]
	s_add_u32 m0, s26, 4096
	s_nop 0
	global_load_lds_dwordx4 v225, s[0:1]
	s_add_u32 m0, s26, 8192
	s_nop 0
	global_load_lds_dwordx4 v226, s[0:1]
	s_add_u32 m0, s26, 12288
	s_nop 0
	global_load_lds_dwordx4 v227, s[0:1]
	s_add_u32 m0, s26, 16384
	s_nop 0
	global_load_lds_dwordx4 v228, s[2:3]
	s_add_u32 m0, s26, 20480
	s_nop 0
	global_load_lds_dwordx4 v229, s[2:3]
	s_add_u32 s0, s0, 64
	s_addc_u32 s1, s1, 0
	s_add_u32 s2, s2, 64
	s_addc_u32 s3, s3, 0
	s_add_u32 s99, s99, 1
	s_add_u32 s30, s30, 24576
	s_cmp_eq_u32 s30, 73728
	s_cselect_b32 s30, 0, s30
	v_mov_b32_e32 v0, 0
	v_mov_b32_e32 v1, 0
	v_mov_b32_e32 v2, 0
	v_mov_b32_e32 v3, 0
	v_mov_b32_e32 v4, 0
	v_mov_b32_e32 v5, 0
	v_mov_b32_e32 v6, 0
	v_mov_b32_e32 v7, 0
	v_mov_b32_e32 v8, 0
	v_mov_b32_e32 v9, 0
	v_mov_b32_e32 v10, 0
	v_mov_b32_e32 v11, 0
	v_mov_b32_e32 v12, 0
	v_mov_b32_e32 v13, 0
	v_mov_b32_e32 v14, 0
	v_mov_b32_e32 v15, 0
	v_mov_b32_e32 v16, 0
	v_mov_b32_e32 v17, 0
	v_mov_b32_e32 v18, 0
	v_mov_b32_e32 v19, 0
	v_mov_b32_e32 v20, 0
	v_mov_b32_e32 v21, 0
	v_mov_b32_e32 v22, 0
	v_mov_b32_e32 v23, 0
	v_mov_b32_e32 v24, 0
	v_mov_b32_e32 v25, 0
	v_mov_b32_e32 v26, 0
	v_mov_b32_e32 v27, 0
	v_mov_b32_e32 v28, 0
	v_mov_b32_e32 v29, 0
	v_mov_b32_e32 v30, 0
	v_mov_b32_e32 v31, 0
	v_mov_b32_e32 v32, 0
	v_mov_b32_e32 v33, 0
	v_mov_b32_e32 v34, 0
	v_mov_b32_e32 v35, 0
	v_mov_b32_e32 v36, 0
	v_mov_b32_e32 v37, 0
	v_mov_b32_e32 v38, 0
	v_mov_b32_e32 v39, 0
	v_mov_b32_e32 v40, 0
	v_mov_b32_e32 v41, 0
	v_mov_b32_e32 v42, 0
	v_mov_b32_e32 v43, 0
	v_mov_b32_e32 v44, 0
	v_mov_b32_e32 v45, 0
	v_mov_b32_e32 v46, 0
	v_mov_b32_e32 v47, 0
	v_mov_b32_e32 v48, 0
	v_mov_b32_e32 v49, 0
	v_mov_b32_e32 v50, 0
	v_mov_b32_e32 v51, 0
	v_mov_b32_e32 v52, 0
	v_mov_b32_e32 v53, 0
	v_mov_b32_e32 v54, 0
	v_mov_b32_e32 v55, 0
	v_mov_b32_e32 v56, 0
	v_mov_b32_e32 v57, 0
	v_mov_b32_e32 v58, 0
	v_mov_b32_e32 v59, 0
	v_mov_b32_e32 v60, 0
	v_mov_b32_e32 v61, 0
	v_mov_b32_e32 v62, 0
	v_mov_b32_e32 v63, 0
	v_mov_b32_e32 v64, 0
	v_mov_b32_e32 v65, 0
	v_mov_b32_e32 v66, 0
	v_mov_b32_e32 v67, 0
	v_mov_b32_e32 v68, 0
	v_mov_b32_e32 v69, 0
	v_mov_b32_e32 v70, 0
	v_mov_b32_e32 v71, 0
	v_mov_b32_e32 v72, 0
	v_mov_b32_e32 v73, 0
	v_mov_b32_e32 v74, 0
	v_mov_b32_e32 v75, 0
	v_mov_b32_e32 v76, 0
	v_mov_b32_e32 v77, 0
	v_mov_b32_e32 v78, 0
	v_mov_b32_e32 v79, 0
	v_mov_b32_e32 v80, 0
	v_mov_b32_e32 v81, 0
	v_mov_b32_e32 v82, 0
	v_mov_b32_e32 v83, 0
	v_mov_b32_e32 v84, 0
	v_mov_b32_e32 v85, 0
	v_mov_b32_e32 v86, 0
	v_mov_b32_e32 v87, 0
	v_mov_b32_e32 v88, 0
	v_mov_b32_e32 v89, 0
	v_mov_b32_e32 v90, 0
	v_mov_b32_e32 v91, 0
	v_mov_b32_e32 v92, 0
	v_mov_b32_e32 v93, 0
	v_mov_b32_e32 v94, 0
	v_mov_b32_e32 v95, 0
	v_mov_b32_e32 v96, 0
	v_mov_b32_e32 v97, 0
	v_mov_b32_e32 v98, 0
	v_mov_b32_e32 v99, 0
	v_mov_b32_e32 v100, 0
	v_mov_b32_e32 v101, 0
	v_mov_b32_e32 v102, 0
	v_mov_b32_e32 v103, 0
	v_mov_b32_e32 v104, 0
	v_mov_b32_e32 v105, 0
	v_mov_b32_e32 v106, 0
	v_mov_b32_e32 v107, 0
	v_mov_b32_e32 v108, 0
	v_mov_b32_e32 v109, 0
	v_mov_b32_e32 v110, 0
	v_mov_b32_e32 v111, 0
	v_mov_b32_e32 v112, 0
	v_mov_b32_e32 v113, 0
	v_mov_b32_e32 v114, 0
	v_mov_b32_e32 v115, 0
	v_mov_b32_e32 v116, 0
	v_mov_b32_e32 v117, 0
	v_mov_b32_e32 v118, 0
	v_mov_b32_e32 v119, 0
	v_mov_b32_e32 v120, 0
	v_mov_b32_e32 v121, 0
	v_mov_b32_e32 v122, 0
	v_mov_b32_e32 v123, 0
	v_mov_b32_e32 v124, 0
	v_mov_b32_e32 v125, 0
	v_mov_b32_e32 v126, 0
	v_mov_b32_e32 v127, 0
	s_mov_b32 s98, 0
	s_mov_b32 s31, 24576
	s_waitcnt vmcnt(6)
	s_barrier
; #define LWRITE(S, buf) do { bf16_t* sA_ = sbase + (buf) * BUF; bf16_t* sB_ = sA_ + 256 * PITCH; \
;     _Pragma("unroll") for (int i_ = 0; i_ < 4; ++i_) *(u32x4*)(sA_ + (sr + i_ * 64) * PITCH + scv * 8) = ra[S][i_]; \
;     _Pragma("unroll") for (int i_ = 0; i_ < 2; ++i_) *(u32x4*)(sB_ + (sr + i_ * 64) * PITCH + scv * 8) = rb[S][i_]; } while (0)
; template <class Epi>
; DI void gemm_tile(char* smem, const bf16_t* __restrict__ A0, int lda0, int ksplit, const bf16_t* __restrict__ A1, int lda1,
;                   const bf16_t* __restrict__ Bt, int K, int row0, int col0, const Epi& epi, int tid) {
;     ...
;   __syncthreads();
;   {
;     const int last = nk - 1;
;     GLOAD(0, 0);
;     __builtin_amdgcn_sched_barrier(0);
;     GLOAD(1, 1);
;     __builtin_amdgcn_sched_barrier(0);
;     LWRITE(0, 0);
;     __builtin_amdgcn_sched_barrier(0);
;     GLOAD(0, (2 < last ? 2 : last));
;     __builtin_amdgcn_sched_barrier(0);
;     __syncthreads();
;     for (int kt = 0; kt < nk; kt += 2) {
;       LWRITE(1, 1);
;       __builtin_amdgcn_sched_barrier(0);
;       GLOAD(1, (kt + 3 < last ? kt + 3 : last));
;       __builtin_amdgcn_sched_barrier(0);
;       COMPUTE(0);
;       __syncthreads();
;       LWRITE(0, 0);
;       __builtin_amdgcn_sched_barrier(0);
;       GLOAD(0, (kt + 4 < last ? kt + 4 : last));
;       __builtin_amdgcn_sched_barrier(0);
;       COMPUTE(1);
;       __syncthreads();
;     }
	ds_read_b128 v[128:131], v231 offset:0
	ds_read_b128 v[132:135], v231 offset:1024
	ds_read_b128 v[136:139], v231 offset:2048
	ds_read_b128 v[140:143], v231 offset:3072
	ds_read_b128 v[144:147], v230 offset:0
	ds_read_b128 v[148:151], v230 offset:1024
	ds_read_b128 v[152:155], v230 offset:2048
	ds_read_b128 v[156:159], v230 offset:3072
	ds_read_b128 v[160:163], v230 offset:4096
	ds_read_b128 v[164:167], v230 offset:5120
	ds_read_b128 v[168:171], v230 offset:6144
	ds_read_b128 v[172:175], v230 offset:7168
	s_waitcnt vmcnt(0)
	s_waitcnt lgkmcnt(0)
	s_barrier
	v_add_u32_e32 v232, s31, v230
	v_add_u32_e32 v233, s31, v231
	s_setprio 1
	v_mfma_f32_16x16x32_bf16 v[0:3], v[128:131], v[144:147], v[0:3]
	v_mfma_f32_16x16x32_bf16 v[4:7], v[132:135], v[144:147], v[4:7]
	v_mfma_f32_16x16x32_bf16 v[8:11], v[136:139], v[144:147], v[8:11]
	v_mfma_f32_16x16x32_bf16 v[12:15], v[140:143], v[144:147], v[12:15]
	ds_read_b128 v[176:179], v233 offset:0
	ds_read_b128 v[180:183], v233 offset:1024
	v_mfma_f32_16x16x32_bf16 v[16:19], v[128:131], v[148:151], v[16:19]
	v_mfma_f32_16x16x32_bf16 v[20:23], v[132:135], v[148:151], v[20:23]
	v_mfma_f32_16x16x32_bf16 v[24:27], v[136:139], v[148:151], v[24:27]
	v_mfma_f32_16x16x32_bf16 v[28:31], v[140:143], v[148:151], v[28:31]
	ds_read_b128 v[184:187], v233 offset:2048
	ds_read_b128 v[188:191], v233 offset:3072
	v_mfma_f32_16x16x32_bf16 v[32:35], v[128:131], v[152:155], v[32:35]
	v_mfma_f32_16x16x32_bf16 v[36:39], v[132:135], v[152:155], v[36:39]
	v_mfma_f32_16x16x32_bf16 v[40:43], v[136:139], v[152:155], v[40:43]
	v_mfma_f32_16x16x32_bf16 v[44:47], v[140:143], v[152:155], v[44:47]
	ds_read_b128 v[192:195], v232 offset:0
	ds_read_b128 v[196:199], v232 offset:1024
	v_mfma_f32_16x16x32_bf16 v[48:51], v[128:131], v[156:159], v[48:51]
	v_mfma_f32_16x16x32_bf16 v[52:55], v[132:135], v[156:159], v[52:55]
	v_mfma_f32_16x16x32_bf16 v[56:59], v[136:139], v[156:159], v[56:59]
	v_mfma_f32_16x16x32_bf16 v[60:63], v[140:143], v[156:159], v[60:63]
	ds_read_b128 v[200:203], v232 offset:2048
	ds_read_b128 v[204:207], v232 offset:3072
	v_mfma_f32_16x16x32_bf16 v[64:67], v[128:131], v[160:163], v[64:67]
	v_mfma_f32_16x16x32_bf16 v[68:71], v[132:135], v[160:163], v[68:71]
	v_mfma_f32_16x16x32_bf16 v[72:75], v[136:139], v[160:163], v[72:75]
	v_mfma_f32_16x16x32_bf16 v[76:79], v[140:143], v[160:163], v[76:79]
	ds_read_b128 v[208:211], v232 offset:4096
	s_cmp_eq_u32 s25, 0
	s_cbranch_scc0 .Lg3a_hi0
	s_setprio 0
.Lg3a_hi0:
	v_mfma_f32_16x16x32_bf16 v[80:83], v[128:131], v[164:167], v[80:83]
	v_mfma_f32_16x16x32_bf16 v[84:87], v[132:135], v[164:167], v[84:87]
	v_mfma_f32_16x16x32_bf16 v[88:91], v[136:139], v[164:167], v[88:91]
	v_mfma_f32_16x16x32_bf16 v[92:95], v[140:143], v[164:167], v[92:95]
	ds_read_b128 v[212:215], v232 offset:5120
	v_mfma_f32_16x16x32_bf16 v[96:99], v[128:131], v[168:171], v[96:99]
	v_mfma_f32_16x16x32_bf16 v[100:103], v[132:135], v[168:171], v[100:103]
	v_mfma_f32_16x16x32_bf16 v[104:107], v[136:139], v[168:171], v[104:107]
	v_mfma_f32_16x16x32_bf16 v[108:111], v[140:143], v[168:171], v[108:111]
	ds_read_b128 v[216:219], v232 offset:6144
	s_add_u32 s31, s31, 24576
	s_cmp_eq_u32 s31, 73728
	s_cselect_b32 s31, 0, s31
	v_mfma_f32_16x16x32_bf16 v[112:115], v[128:131], v[172:175], v[112:115]
	v_mfma_f32_16x16x32_bf16 v[116:119], v[132:135], v[172:175], v[116:119]
	v_mfma_f32_16x16x32_bf16 v[120:123], v[136:139], v[172:175], v[120:123]
	v_mfma_f32_16x16x32_bf16 v[124:127], v[140:143], v[172:175], v[124:127]
	ds_read_b128 v[220:223], v232 offset:7168
	s_waitcnt lgkmcnt(0)
	s_barrier
	s_setprio 1
	v_mfma_f32_16x16x32_bf16 v[0:3], v[176:179], v[192:195], v[0:3]
	v_mfma_f32_16x16x32_bf16 v[4:7], v[180:183], v[192:195], v[4:7]
	v_mfma_f32_16x16x32_bf16 v[8:11], v[184:187], v[192:195], v[8:11]
	v_mfma_f32_16x16x32_bf16 v[12:15], v[188:191], v[192:195], v[12:15]
	v_mfma_f32_16x16x32_bf16 v[16:19], v[176:179], v[196:199], v[16:19]
	v_mfma_f32_16x16x32_bf16 v[20:23], v[180:183], v[196:199], v[20:23]
	v_mfma_f32_16x16x32_bf16 v[24:27], v[184:187], v[196:199], v[24:27]
	v_mfma_f32_16x16x32_bf16 v[28:31], v[188:191], v[196:199], v[28:31]
	v_mfma_f32_16x16x32_bf16 v[32:35], v[176:179], v[200:203], v[32:35]
	v_mfma_f32_16x16x32_bf16 v[36:39], v[180:183], v[200:203], v[36:39]
	v_mfma_f32_16x16x32_bf16 v[40:43], v[184:187], v[200:203], v[40:43]
	v_mfma_f32_16x16x32_bf16 v[44:47], v[188:191], v[200:203], v[44:47]
	v_mfma_f32_16x16x32_bf16 v[48:51], v[176:179], v[204:207], v[48:51]
	v_mfma_f32_16x16x32_bf16 v[52:55], v[180:183], v[204:207], v[52:55]
	v_mfma_f32_16x16x32_bf16 v[56:59], v[184:187], v[204:207], v[56:59]
	v_mfma_f32_16x16x32_bf16 v[60:63], v[188:191], v[204:207], v[60:63]
	v_mfma_f32_16x16x32_bf16 v[64:67], v[176:179], v[208:211], v[64:67]
	v_mfma_f32_16x16x32_bf16 v[68:71], v[180:183], v[208:211], v[68:71]
	v_mfma_f32_16x16x32_bf16 v[72:75], v[184:187], v[208:211], v[72:75]
	v_mfma_f32_16x16x32_bf16 v[76:79], v[188:191], v[208:211], v[76:79]
	s_cmp_eq_u32 s25, 0
	s_cbranch_scc0 .Lg3a_hi1
	s_setprio 0

; #define LWRITE(S, buf) do { bf16_t* sA_ = sbase + (buf) * BUF; bf16_t* sB_ = sA_ + 256 * PITCH; \
;     _Pragma("unroll") for (int i_ = 0; i_ < 4; ++i_) *(u32x4*)(sA_ + (sr + i_ * 64) * PITCH + scv * 8) = ra[S][i_]; \
;     _Pragma("unroll") for (int i_ = 0; i_ < 2; ++i_) *(u32x4*)(sB_ + (sr + i_ * 64) * PITCH + scv * 8) = rb[S][i_]; } while (0)
; template <class Epi>
; DI void gemm_tile(char* smem, const bf16_t* __restrict__ A0, int lda0, int ksplit, const bf16_t* __restrict__ A1, int lda1,
;                   const bf16_t* __restrict__ Bt, int K, int row0, int col0, const Epi& epi, int tid) {
;     ...
;   f32x4 acc[8][4];
; #pragma unroll
;   for (int m = 0; m < 8; ++m)
; #pragma unroll
;     for (int n = 0; n < 4; ++n) acc[m][n] = (f32x4){0.f, 0.f, 0.f, 0.f};
;   u32x4 ra[2][4], rb[2][2];
;   const int nk = K / BK;
;   const int sr = tid >> 2, scv = tid & 3;
;     ...
;   __syncthreads();
;   {
;     const int last = nk - 1;
;     GLOAD(0, 0);
;     __builtin_amdgcn_sched_barrier(0);
;     GLOAD(1, 1);
;     __builtin_amdgcn_sched_barrier(0);
;     LWRITE(0, 0);
;     __builtin_amdgcn_sched_barrier(0);
;     GLOAD(0, (2 < last ? 2 : last));
;     __builtin_amdgcn_sched_barrier(0);
;     __syncthreads();
; template <class Epi>
; DI void gemm_phase(char* smem, const bf16_t* A0, int lda0, int ksplit, const bf16_t* A1, int lda1, const bf16_t* Bt, int K, int nN, const Epi& epi, int tid) {
;     ...
;     const int x = blockIdx.x & 7, l = blockIdx.x >> 3, L = G >> 3, per = 8 * nN, tot = 2 * per;
;     for (int q = l; q < tot; q += L) { const int rgl = q / per, rem = q % per, ct = rem >> 3, rt = (x * 2 + rgl) * 8 + (rem & 7);
;       gemm_tile(smem, A0, lda0, ksplit, A1, lda1, Bt, K, rt * 256, ct * 128, epi, tid); }
.Lg3b_tile:
	s_cmpk_ge_u32 s15, 64
	s_cbranch_scc1 .Lg3b_done
	s_cmpk_ge_u32 s15, 32
	s_cselect_b32 s27, 1, 0
	s_cselect_b32 s26, 32, 0
	s_sub_u32 s26, s15, s26
	s_add_u32 s27, s27, s101
	s_lshl_b32 s27, s27, 3
	s_and_b32 s29, s26, 7
	s_add_u32 s29, s29, s27
	s_lshl_b32 s29, s29, 8
	s_lshr_b32 s28, s26, 3
	s_lshl_b32 s28, s28, 7
	s_mul_i32 s27, s29, 512
	s_add_u32 s27, s27, 0x1ea00000
	s_add_u32 s0, s92, s27
	s_addc_u32 s1, s93, 0
	s_mul_i32 s27, s28, 128
	s_add_u32 s27, s27, 0x34b0000
	s_add_u32 s2, s92, s27
	s_addc_u32 s3, s93, 0
	s_waitcnt lgkmcnt(0)
	s_barrier
	s_mov_b32 s99, 0
	s_mov_b32 s30, 0
	s_add_u32 s26, s30, s100
	s_add_u32 m0, s26, 0
	s_nop 0
	global_load_lds_dwordx4 v224, s[0:1]
	s_add_u32 m0, s26, 4096
	s_nop 0
	global_load_lds_dwordx4 v225, s[0:1]
	s_add_u32 m0, s26, 8192
	s_nop 0
	global_load_lds_dwordx4 v226, s[0:1]
	s_add_u32 m0, s26, 12288
	s_nop 0
	global_load_lds_dwordx4 v227, s[0:1]
	s_add_u32 m0, s26, 16384
	s_nop 0
	global_load_lds_dwordx4 v228, s[2:3]
	s_add_u32 m0, s26, 20480
	s_nop 0
	global_load_lds_dwordx4 v229, s[2:3]
	s_add_u32 s0, s0, 64
	s_addc_u32 s1, s1, 0
	s_add_u32 s2, s2, 64
	s_addc_u32 s3, s3, 0
	s_add_u32 s99, s99, 1
	s_add_u32 s30, s30, 24576
	s_cmp_eq_u32 s30, 73728
	s_cselect_b32 s30, 0, s30
	s_add_u32 s26, s30, s100
	s_add_u32 m0, s26, 0
	s_nop 0
	global_load_lds_dwordx4 v224, s[0:1]
	s_add_u32 m0, s26, 4096
	s_nop 0
	global_load_lds_dwordx4 v225, s[0:1]
	s_add_u32 m0, s26, 8192
	s_nop 0
	global_load_lds_dwordx4 v226, s[0:1]
	s_add_u32 m0, s26, 12288
	s_nop 0
	global_load_lds_dwordx4 v227, s[0:1]
	s_add_u32 m0, s26, 16384
	s_nop 0
	global_load_lds_dwordx4 v228, s[2:3]
	s_add_u32 m0, s26, 20480
	s_nop 0
	global_load_lds_dwordx4 v229, s[2:3]
	s_add_u32 s0, s0, 64
	s_addc_u32 s1, s1, 0
	s_add_u32 s2, s2, 64
	s_addc_u32 s3, s3, 0
	s_add_u32 s99, s99, 1
	s_add_u32 s30, s30, 24576
	s_cmp_eq_u32 s30, 73728
	s_cselect_b32 s30, 0, s30
	v_mov_b32_e32 v0, 0
	v_mov_b32_e32 v1, 0
	v_mov_b32_e32 v2, 0
	v_mov_b32_e32 v3, 0
	v_mov_b32_e32 v4, 0
	v_mov_b32_e32 v5, 0
	v_mov_b32_e32 v6, 0
	v_mov_b32_e32 v7, 0
	v_mov_b32_e32 v8, 0
	v_mov_b32_e32 v9, 0
	v_mov_b32_e32 v10, 0
	v_mov_b32_e32 v11, 0
	v_mov_b32_e32 v12, 0
	v_mov_b32_e32 v13, 0
	v_mov_b32_e32 v14, 0
	v_mov_b32_e32 v15, 0
	v_mov_b32_e32 v16, 0
	v_mov_b32_e32 v17, 0
	v_mov_b32_e32 v18, 0
	v_mov_b32_e32 v19, 0
	v_mov_b32_e32 v20, 0
	v_mov_b32_e32 v21, 0
	v_mov_b32_e32 v22, 0
	v_mov_b32_e32 v23, 0
	v_mov_b32_e32 v24, 0
	v_mov_b32_e32 v25, 0
	v_mov_b32_e32 v26, 0
	v_mov_b32_e32 v27, 0
	v_mov_b32_e32 v28, 0
	v_mov_b32_e32 v29, 0
	v_mov_b32_e32 v30, 0
	v_mov_b32_e32 v31, 0
	v_mov_b32_e32 v32, 0
	v_mov_b32_e32 v33, 0
	v_mov_b32_e32 v34, 0
	v_mov_b32_e32 v35, 0
	v_mov_b32_e32 v36, 0
	v_mov_b32_e32 v37, 0
	v_mov_b32_e32 v38, 0
	v_mov_b32_e32 v39, 0
	v_mov_b32_e32 v40, 0
	v_mov_b32_e32 v41, 0
	v_mov_b32_e32 v42, 0
	v_mov_b32_e32 v43, 0
	v_mov_b32_e32 v44, 0
	v_mov_b32_e32 v45, 0
	v_mov_b32_e32 v46, 0
	v_mov_b32_e32 v47, 0
	v_mov_b32_e32 v48, 0
	v_mov_b32_e32 v49, 0
	v_mov_b32_e32 v50, 0
	v_mov_b32_e32 v51, 0
	v_mov_b32_e32 v52, 0
	v_mov_b32_e32 v53, 0
	v_mov_b32_e32 v54, 0
	v_mov_b32_e32 v55, 0
	v_mov_b32_e32 v56, 0
	v_mov_b32_e32 v57, 0
	v_mov_b32_e32 v58, 0
	v_mov_b32_e32 v59, 0
	v_mov_b32_e32 v60, 0
	v_mov_b32_e32 v61, 0
	v_mov_b32_e32 v62, 0
	v_mov_b32_e32 v63, 0
	v_mov_b32_e32 v64, 0
	v_mov_b32_e32 v65, 0
	v_mov_b32_e32 v66, 0
	v_mov_b32_e32 v67, 0
	v_mov_b32_e32 v68, 0
	v_mov_b32_e32 v69, 0
	v_mov_b32_e32 v70, 0
	v_mov_b32_e32 v71, 0
	v_mov_b32_e32 v72, 0
	v_mov_b32_e32 v73, 0
	v_mov_b32_e32 v74, 0
	v_mov_b32_e32 v75, 0
	v_mov_b32_e32 v76, 0
	v_mov_b32_e32 v77, 0
	v_mov_b32_e32 v78, 0
	v_mov_b32_e32 v79, 0
	v_mov_b32_e32 v80, 0
	v_mov_b32_e32 v81, 0
	v_mov_b32_e32 v82, 0
	v_mov_b32_e32 v83, 0
	v_mov_b32_e32 v84, 0
	v_mov_b32_e32 v85, 0
	v_mov_b32_e32 v86, 0
	v_mov_b32_e32 v87, 0
	v_mov_b32_e32 v88, 0
	v_mov_b32_e32 v89, 0
	v_mov_b32_e32 v90, 0
	v_mov_b32_e32 v91, 0
	v_mov_b32_e32 v92, 0
	v_mov_b32_e32 v93, 0
	v_mov_b32_e32 v94, 0
	v_mov_b32_e32 v95, 0
	v_mov_b32_e32 v96, 0
	v_mov_b32_e32 v97, 0
	v_mov_b32_e32 v98, 0
	v_mov_b32_e32 v99, 0
	v_mov_b32_e32 v100, 0
	v_mov_b32_e32 v101, 0
	v_mov_b32_e32 v102, 0
	v_mov_b32_e32 v103, 0
	v_mov_b32_e32 v104, 0
	v_mov_b32_e32 v105, 0
	v_mov_b32_e32 v106, 0
	v_mov_b32_e32 v107, 0
	v_mov_b32_e32 v108, 0
	v_mov_b32_e32 v109, 0
	v_mov_b32_e32 v110, 0
	v_mov_b32_e32 v111, 0
	v_mov_b32_e32 v112, 0
	v_mov_b32_e32 v113, 0
	v_mov_b32_e32 v114, 0
	v_mov_b32_e32 v115, 0
	v_mov_b32_e32 v116, 0
	v_mov_b32_e32 v117, 0
	v_mov_b32_e32 v118, 0
	v_mov_b32_e32 v119, 0
	v_mov_b32_e32 v120, 0
	v_mov_b32_e32 v121, 0
	v_mov_b32_e32 v122, 0
	v_mov_b32_e32 v123, 0
	v_mov_b32_e32 v124, 0
	v_mov_b32_e32 v125, 0
	v_mov_b32_e32 v126, 0
	v_mov_b32_e32 v127, 0
	s_mov_b32 s98, 0
	s_mov_b32 s31, 24576
	s_waitcnt vmcnt(6)
	s_barrier
; #define LWRITE(S, buf) do { bf16_t* sA_ = sbase + (buf) * BUF; bf16_t* sB_ = sA_ + 256 * PITCH; \
;     _Pragma("unroll") for (int i_ = 0; i_ < 4; ++i_) *(u32x4*)(sA_ + (sr + i_ * 64) * PITCH + scv * 8) = ra[S][i_]; \
;     _Pragma("unroll") for (int i_ = 0; i_ < 2; ++i_) *(u32x4*)(sB_ + (sr + i_ * 64) * PITCH + scv * 8) = rb[S][i_]; } while (0)
; template <class Epi>
; DI void gemm_tile(char* smem, const bf16_t* __restrict__ A0, int lda0, int ksplit, const bf16_t* __restrict__ A1, int lda1,
;                   const bf16_t* __restrict__ Bt, int K, int row0, int col0, const Epi& epi, int tid) {
;     ...
;   __syncthreads();
;   {
;     const int last = nk - 1;
;     GLOAD(0, 0);
;     __builtin_amdgcn_sched_barrier(0);
;     GLOAD(1, 1);
;     __builtin_amdgcn_sched_barrier(0);
;     LWRITE(0, 0);
;     __builtin_amdgcn_sched_barrier(0);
;     GLOAD(0, (2 < last ? 2 : last));
;     __builtin_amdgcn_sched_barrier(0);
;     __syncthreads();
;     for (int kt = 0; kt < nk; kt += 2) {
;       LWRITE(1, 1);
;       __builtin_amdgcn_sched_barrier(0);
;       GLOAD(1, (kt + 3 < last ? kt + 3 : last));
;       __builtin_amdgcn_sched_barrier(0);
;       COMPUTE(0);
;       __syncthreads();
;       LWRITE(0, 0);
;       __builtin_amdgcn_sched_barrier(0);
;       GLOAD(0, (kt + 4 < last ? kt + 4 : last));
;       __builtin_amdgcn_sched_barrier(0);
;       COMPUTE(1);
;       __syncthreads();
;     }
	ds_read_b128 v[128:131], v231 offset:0
	ds_read_b128 v[132:135], v231 offset:1024
	ds_read_b128 v[136:139], v231 offset:2048
	ds_read_b128 v[140:143], v231 offset:3072
	ds_read_b128 v[144:147], v230 offset:0
	ds_read_b128 v[148:151], v230 offset:1024
	ds_read_b128 v[152:155], v230 offset:2048
	ds_read_b128 v[156:159], v230 offset:3072
	ds_read_b128 v[160:163], v230 offset:4096
	ds_read_b128 v[164:167], v230 offset:5120
	ds_read_b128 v[168:171], v230 offset:6144
	ds_read_b128 v[172:175], v230 offset:7168
	s_waitcnt vmcnt(0)
	s_waitcnt lgkmcnt(0)
	s_barrier
	v_add_u32_e32 v232, s31, v230
	v_add_u32_e32 v233, s31, v231
	s_setprio 1
	v_mfma_f32_16x16x32_bf16 v[0:3], v[128:131], v[144:147], v[0:3]
	v_mfma_f32_16x16x32_bf16 v[4:7], v[132:135], v[144:147], v[4:7]
	v_mfma_f32_16x16x32_bf16 v[8:11], v[136:139], v[144:147], v[8:11]
	v_mfma_f32_16x16x32_bf16 v[12:15], v[140:143], v[144:147], v[12:15]
	ds_read_b128 v[176:179], v233 offset:0
	ds_read_b128 v[180:183], v233 offset:1024
	v_mfma_f32_16x16x32_bf16 v[16:19], v[128:131], v[148:151], v[16:19]
	v_mfma_f32_16x16x32_bf16 v[20:23], v[132:135], v[148:151], v[20:23]
	v_mfma_f32_16x16x32_bf16 v[24:27], v[136:139], v[148:151], v[24:27]
	v_mfma_f32_16x16x32_bf16 v[28:31], v[140:143], v[148:151], v[28:31]
	ds_read_b128 v[184:187], v233 offset:2048
	ds_read_b128 v[188:191], v233 offset:3072
	v_mfma_f32_16x16x32_bf16 v[32:35], v[128:131], v[152:155], v[32:35]
	v_mfma_f32_16x16x32_bf16 v[36:39], v[132:135], v[152:155], v[36:39]
	v_mfma_f32_16x16x32_bf16 v[40:43], v[136:139], v[152:155], v[40:43]
	v_mfma_f32_16x16x32_bf16 v[44:47], v[140:143], v[152:155], v[44:47]
	ds_read_b128 v[192:195], v232 offset:0
	ds_read_b128 v[196:199], v232 offset:1024
	v_mfma_f32_16x16x32_bf16 v[48:51], v[128:131], v[156:159], v[48:51]
	v_mfma_f32_16x16x32_bf16 v[52:55], v[132:135], v[156:159], v[52:55]
	v_mfma_f32_16x16x32_bf16 v[56:59], v[136:139], v[156:159], v[56:59]
	v_mfma_f32_16x16x32_bf16 v[60:63], v[140:143], v[156:159], v[60:63]
	ds_read_b128 v[200:203], v232 offset:2048
	ds_read_b128 v[204:207], v232 offset:3072
	v_mfma_f32_16x16x32_bf16 v[64:67], v[128:131], v[160:163], v[64:67]
	v_mfma_f32_16x16x32_bf16 v[68:71], v[132:135], v[160:163], v[68:71]
	v_mfma_f32_16x16x32_bf16 v[72:75], v[136:139], v[160:163], v[72:75]
	v_mfma_f32_16x16x32_bf16 v[76:79], v[140:143], v[160:163], v[76:79]
	ds_read_b128 v[208:211], v232 offset:4096
	s_cmp_eq_u32 s25, 0
	s_cbranch_scc0 .Lg3b_hi0
	s_setprio 0

; #define LWRITE(S, buf) do { bf16_t* sA_ = sbase + (buf) * BUF; bf16_t* sB_ = sA_ + 256 * PITCH; \
;     _Pragma("unroll") for (int i_ = 0; i_ < 4; ++i_) *(u32x4*)(sA_ + (sr + i_ * 64) * PITCH + scv * 8) = ra[S][i_]; \
;     _Pragma("unroll") for (int i_ = 0; i_ < 2; ++i_) *(u32x4*)(sB_ + (sr + i_ * 64) * PITCH + scv * 8) = rb[S][i_]; } while (0)
; template <class Epi>
; DI void gemm_tile(char* smem, const bf16_t* __restrict__ A0, int lda0, int ksplit, const bf16_t* __restrict__ A1, int lda1,
;                   const bf16_t* __restrict__ Bt, int K, int row0, int col0, const Epi& epi, int tid) {
;     ...
;   f32x4 acc[8][4];
; #pragma unroll
;   for (int m = 0; m < 8; ++m)
; #pragma unroll
;     for (int n = 0; n < 4; ++n) acc[m][n] = (f32x4){0.f, 0.f, 0.f, 0.f};
;   u32x4 ra[2][4], rb[2][2];
;   const int nk = K / BK;
;   const int sr = tid >> 2, scv = tid & 3;
;     ...
;   __syncthreads();
;   {
;     const int last = nk - 1;
;     GLOAD(0, 0);
;     __builtin_amdgcn_sched_barrier(0);
;     GLOAD(1, 1);
;     __builtin_amdgcn_sched_barrier(0);
;     LWRITE(0, 0);
;     __builtin_amdgcn_sched_barrier(0);
;     GLOAD(0, (2 < last ? 2 : last));
;     __builtin_amdgcn_sched_barrier(0);
;     __syncthreads();
; template <class Epi>
; DI void gemm_phase(char* smem, const bf16_t* A0, int lda0, int ksplit, const bf16_t* A1, int lda1, const bf16_t* Bt, int K, int nN, const Epi& epi, int tid) {
;     ...
;     const int x = blockIdx.x & 7, l = blockIdx.x >> 3, L = G >> 3, per = 8 * nN, tot = 2 * per;
;     for (int q = l; q < tot; q += L) { const int rgl = q / per, rem = q % per, ct = rem >> 3, rt = (x * 2 + rgl) * 8 + (rem & 7);
;       gemm_tile(smem, A0, lda0, ksplit, A1, lda1, Bt, K, rt * 256, ct * 128, epi, tid); }
.Lg3c_tile:
	s_cmpk_ge_u32 s15, 64
	s_cbranch_scc1 .Lg3c_done
	s_cmpk_ge_u32 s15, 32
	s_cselect_b32 s27, 1, 0
	s_cselect_b32 s26, 32, 0
	s_sub_u32 s26, s15, s26
	s_add_u32 s27, s27, s101
	s_lshl_b32 s27, s27, 3
	s_and_b32 s29, s26, 7
	s_add_u32 s29, s29, s27
	s_lshl_b32 s29, s29, 8
	s_lshr_b32 s28, s26, 3
	s_lshl_b32 s28, s28, 7
	s_mul_i32 s27, s29, 512
	s_add_u32 s27, s27, 0x1ea00080
	s_add_u32 s0, s92, s27
	s_addc_u32 s1, s93, 0
	s_mul_i32 s27, s28, 128
	s_add_u32 s27, s27, 0x34c0000
	s_add_u32 s2, s92, s27
	s_addc_u32 s3, s93, 0
	s_waitcnt lgkmcnt(0)
	s_barrier
	s_mov_b32 s99, 0
	s_mov_b32 s30, 0
	s_add_u32 s26, s30, s100
	s_add_u32 m0, s26, 0
	s_nop 0
	global_load_lds_dwordx4 v224, s[0:1]
	s_add_u32 m0, s26, 4096
	s_nop 0
	global_load_lds_dwordx4 v225, s[0:1]
	s_add_u32 m0, s26, 8192
	s_nop 0
	global_load_lds_dwordx4 v226, s[0:1]
	s_add_u32 m0, s26, 12288
	s_nop 0
	global_load_lds_dwordx4 v227, s[0:1]
	s_add_u32 m0, s26, 16384
	s_nop 0
	global_load_lds_dwordx4 v228, s[2:3]
	s_add_u32 m0, s26, 20480
	s_nop 0
	global_load_lds_dwordx4 v229, s[2:3]
	s_add_u32 s0, s0, 64
	s_addc_u32 s1, s1, 0
	s_add_u32 s2, s2, 64
	s_addc_u32 s3, s3, 0
	s_add_u32 s99, s99, 1
	s_add_u32 s30, s30, 24576
	s_cmp_eq_u32 s30, 73728
	s_cselect_b32 s30, 0, s30
	s_add_u32 s26, s30, s100
	s_add_u32 m0, s26, 0
	s_nop 0
	global_load_lds_dwordx4 v224, s[0:1]
	s_add_u32 m0, s26, 4096
	s_nop 0
	global_load_lds_dwordx4 v225, s[0:1]
	s_add_u32 m0, s26, 8192
	s_nop 0
	global_load_lds_dwordx4 v226, s[0:1]
	s_add_u32 m0, s26, 12288
	s_nop 0
	global_load_lds_dwordx4 v227, s[0:1]
	s_add_u32 m0, s26, 16384
	s_nop 0
	global_load_lds_dwordx4 v228, s[2:3]
	s_add_u32 m0, s26, 20480
	s_nop 0
	global_load_lds_dwordx4 v229, s[2:3]
	s_add_u32 s0, s0, 64
	s_addc_u32 s1, s1, 0
	s_add_u32 s2, s2, 64
	s_addc_u32 s3, s3, 0
	s_add_u32 s99, s99, 1
	s_add_u32 s30, s30, 24576
	s_cmp_eq_u32 s30, 73728
	s_cselect_b32 s30, 0, s30
	v_mov_b32_e32 v0, 0
	v_mov_b32_e32 v1, 0
	v_mov_b32_e32 v2, 0
	v_mov_b32_e32 v3, 0
	v_mov_b32_e32 v4, 0
	v_mov_b32_e32 v5, 0
	v_mov_b32_e32 v6, 0
	v_mov_b32_e32 v7, 0
	v_mov_b32_e32 v8, 0
	v_mov_b32_e32 v9, 0
	v_mov_b32_e32 v10, 0
	v_mov_b32_e32 v11, 0
	v_mov_b32_e32 v12, 0
	v_mov_b32_e32 v13, 0
	v_mov_b32_e32 v14, 0
	v_mov_b32_e32 v15, 0
	v_mov_b32_e32 v16, 0
	v_mov_b32_e32 v17, 0
	v_mov_b32_e32 v18, 0
	v_mov_b32_e32 v19, 0
	v_mov_b32_e32 v20, 0
	v_mov_b32_e32 v21, 0
	v_mov_b32_e32 v22, 0
	v_mov_b32_e32 v23, 0
	v_mov_b32_e32 v24, 0
	v_mov_b32_e32 v25, 0
	v_mov_b32_e32 v26, 0
	v_mov_b32_e32 v27, 0
	v_mov_b32_e32 v28, 0
	v_mov_b32_e32 v29, 0
	v_mov_b32_e32 v30, 0
	v_mov_b32_e32 v31, 0
	v_mov_b32_e32 v32, 0
	v_mov_b32_e32 v33, 0
	v_mov_b32_e32 v34, 0
	v_mov_b32_e32 v35, 0
	v_mov_b32_e32 v36, 0
	v_mov_b32_e32 v37, 0
	v_mov_b32_e32 v38, 0
	v_mov_b32_e32 v39, 0
	v_mov_b32_e32 v40, 0
	v_mov_b32_e32 v41, 0
	v_mov_b32_e32 v42, 0
	v_mov_b32_e32 v43, 0
	v_mov_b32_e32 v44, 0
	v_mov_b32_e32 v45, 0
	v_mov_b32_e32 v46, 0
	v_mov_b32_e32 v47, 0
	v_mov_b32_e32 v48, 0
	v_mov_b32_e32 v49, 0
	v_mov_b32_e32 v50, 0
	v_mov_b32_e32 v51, 0
	v_mov_b32_e32 v52, 0
	v_mov_b32_e32 v53, 0
	v_mov_b32_e32 v54, 0
	v_mov_b32_e32 v55, 0
	v_mov_b32_e32 v56, 0
	v_mov_b32_e32 v57, 0
	v_mov_b32_e32 v58, 0
	v_mov_b32_e32 v59, 0
	v_mov_b32_e32 v60, 0
	v_mov_b32_e32 v61, 0
	v_mov_b32_e32 v62, 0
	v_mov_b32_e32 v63, 0
	v_mov_b32_e32 v64, 0
	v_mov_b32_e32 v65, 0
	v_mov_b32_e32 v66, 0
	v_mov_b32_e32 v67, 0
	v_mov_b32_e32 v68, 0
	v_mov_b32_e32 v69, 0
	v_mov_b32_e32 v70, 0
	v_mov_b32_e32 v71, 0
	v_mov_b32_e32 v72, 0
	v_mov_b32_e32 v73, 0
	v_mov_b32_e32 v74, 0
	v_mov_b32_e32 v75, 0
	v_mov_b32_e32 v76, 0
	v_mov_b32_e32 v77, 0
	v_mov_b32_e32 v78, 0
	v_mov_b32_e32 v79, 0
	v_mov_b32_e32 v80, 0
	v_mov_b32_e32 v81, 0
	v_mov_b32_e32 v82, 0
	v_mov_b32_e32 v83, 0
	v_mov_b32_e32 v84, 0
	v_mov_b32_e32 v85, 0
	v_mov_b32_e32 v86, 0
	v_mov_b32_e32 v87, 0
	v_mov_b32_e32 v88, 0
	v_mov_b32_e32 v89, 0
	v_mov_b32_e32 v90, 0
	v_mov_b32_e32 v91, 0
	v_mov_b32_e32 v92, 0
	v_mov_b32_e32 v93, 0
	v_mov_b32_e32 v94, 0
	v_mov_b32_e32 v95, 0
	v_mov_b32_e32 v96, 0
	v_mov_b32_e32 v97, 0
	v_mov_b32_e32 v98, 0
	v_mov_b32_e32 v99, 0
	v_mov_b32_e32 v100, 0
	v_mov_b32_e32 v101, 0
	v_mov_b32_e32 v102, 0
	v_mov_b32_e32 v103, 0
	v_mov_b32_e32 v104, 0
	v_mov_b32_e32 v105, 0
	v_mov_b32_e32 v106, 0
	v_mov_b32_e32 v107, 0
	v_mov_b32_e32 v108, 0
	v_mov_b32_e32 v109, 0
	v_mov_b32_e32 v110, 0
	v_mov_b32_e32 v111, 0
	v_mov_b32_e32 v112, 0
	v_mov_b32_e32 v113, 0
	v_mov_b32_e32 v114, 0
	v_mov_b32_e32 v115, 0
	v_mov_b32_e32 v116, 0
	v_mov_b32_e32 v117, 0
	v_mov_b32_e32 v118, 0
	v_mov_b32_e32 v119, 0
	v_mov_b32_e32 v120, 0
	v_mov_b32_e32 v121, 0
	v_mov_b32_e32 v122, 0
	v_mov_b32_e32 v123, 0
	v_mov_b32_e32 v124, 0
	v_mov_b32_e32 v125, 0
	v_mov_b32_e32 v126, 0
	v_mov_b32_e32 v127, 0
	s_mov_b32 s98, 0
	s_mov_b32 s31, 24576
	s_waitcnt vmcnt(6)
	s_barrier
; #define LWRITE(S, buf) do { bf16_t* sA_ = sbase + (buf) * BUF; bf16_t* sB_ = sA_ + 256 * PITCH; \
;     _Pragma("unroll") for (int i_ = 0; i_ < 4; ++i_) *(u32x4*)(sA_ + (sr + i_ * 64) * PITCH + scv * 8) = ra[S][i_]; \
;     _Pragma("unroll") for (int i_ = 0; i_ < 2; ++i_) *(u32x4*)(sB_ + (sr + i_ * 64) * PITCH + scv * 8) = rb[S][i_]; } while (0)
; template <class Epi>
; DI void gemm_tile(char* smem, const bf16_t* __restrict__ A0, int lda0, int ksplit, const bf16_t* __restrict__ A1, int lda1,
;                   const bf16_t* __restrict__ Bt, int K, int row0, int col0, const Epi& epi, int tid) {
;     ...
;   __syncthreads();
;   {
;     const int last = nk - 1;
;     GLOAD(0, 0);
;     __builtin_amdgcn_sched_barrier(0);
;     GLOAD(1, 1);
;     __builtin_amdgcn_sched_barrier(0);
;     LWRITE(0, 0);
;     __builtin_amdgcn_sched_barrier(0);
;     GLOAD(0, (2 < last ? 2 : last));
;     __builtin_amdgcn_sched_barrier(0);
;     __syncthreads();
;     for (int kt = 0; kt < nk; kt += 2) {
;       LWRITE(1, 1);
;       __builtin_amdgcn_sched_barrier(0);
;       GLOAD(1, (kt + 3 < last ? kt + 3 : last));
;       __builtin_amdgcn_sched_barrier(0);
;       COMPUTE(0);
;       __syncthreads();
;       LWRITE(0, 0);
;       __builtin_amdgcn_sched_barrier(0);
;       GLOAD(0, (kt + 4 < last ? kt + 4 : last));
;       __builtin_amdgcn_sched_barrier(0);
;       COMPUTE(1);
;       __syncthreads();
;     }
	ds_read_b128 v[128:131], v231 offset:0
	ds_read_b128 v[132:135], v231 offset:1024
	ds_read_b128 v[136:139], v231 offset:2048
	ds_read_b128 v[140:143], v231 offset:3072
	ds_read_b128 v[144:147], v230 offset:0
	ds_read_b128 v[148:151], v230 offset:1024
	ds_read_b128 v[152:155], v230 offset:2048
	ds_read_b128 v[156:159], v230 offset:3072
	ds_read_b128 v[160:163], v230 offset:4096
	ds_read_b128 v[164:167], v230 offset:5120
	ds_read_b128 v[168:171], v230 offset:6144
	ds_read_b128 v[172:175], v230 offset:7168
	s_waitcnt vmcnt(0)
	s_waitcnt lgkmcnt(0)
	s_barrier
	v_add_u32_e32 v232, s31, v230
	v_add_u32_e32 v233, s31, v231
	s_setprio 1
	v_mfma_f32_16x16x32_bf16 v[0:3], v[128:131], v[144:147], v[0:3]
	v_mfma_f32_16x16x32_bf16 v[4:7], v[132:135], v[144:147], v[4:7]
	v_mfma_f32_16x16x32_bf16 v[8:11], v[136:139], v[144:147], v[8:11]
	v_mfma_f32_16x16x32_bf16 v[12:15], v[140:143], v[144:147], v[12:15]
	ds_read_b128 v[176:179], v233 offset:0
	ds_read_b128 v[180:183], v233 offset:1024
	v_mfma_f32_16x16x32_bf16 v[16:19], v[128:131], v[148:151], v[16:19]
	v_mfma_f32_16x16x32_bf16 v[20:23], v[132:135], v[148:151], v[20:23]
	v_mfma_f32_16x16x32_bf16 v[24:27], v[136:139], v[148:151], v[24:27]
	v_mfma_f32_16x16x32_bf16 v[28:31], v[140:143], v[148:151], v[28:31]
	ds_read_b128 v[184:187], v233 offset:2048
	ds_read_b128 v[188:191], v233 offset:3072
	v_mfma_f32_16x16x32_bf16 v[32:35], v[128:131], v[152:155], v[32:35]
	v_mfma_f32_16x16x32_bf16 v[36:39], v[132:135], v[152:155], v[36:39]
	v_mfma_f32_16x16x32_bf16 v[40:43], v[136:139], v[152:155], v[40:43]
	v_mfma_f32_16x16x32_bf16 v[44:47], v[140:143], v[152:155], v[44:47]
	ds_read_b128 v[192:195], v232 offset:0
	ds_read_b128 v[196:199], v232 offset:1024
	v_mfma_f32_16x16x32_bf16 v[48:51], v[128:131], v[156:159], v[48:51]
	v_mfma_f32_16x16x32_bf16 v[52:55], v[132:135], v[156:159], v[52:55]
	v_mfma_f32_16x16x32_bf16 v[56:59], v[136:139], v[156:159], v[56:59]
	v_mfma_f32_16x16x32_bf16 v[60:63], v[140:143], v[156:159], v[60:63]
	ds_read_b128 v[200:203], v232 offset:2048
	ds_read_b128 v[204:207], v232 offset:3072
	v_mfma_f32_16x16x32_bf16 v[64:67], v[128:131], v[160:163], v[64:67]
	v_mfma_f32_16x16x32_bf16 v[68:71], v[132:135], v[160:163], v[68:71]
	v_mfma_f32_16x16x32_bf16 v[72:75], v[136:139], v[160:163], v[72:75]
	v_mfma_f32_16x16x32_bf16 v[76:79], v[140:143], v[160:163], v[76:79]
	ds_read_b128 v[208:211], v232 offset:4096
	s_cmp_eq_u32 s25, 0
	s_cbranch_scc0 .Lg3c_hi0
	s_setprio 0

; #define LWRITE(S, buf) do { bf16_t* sA_ = sbase + (buf) * BUF; bf16_t* sB_ = sA_ + 256 * PITCH; \
;     _Pragma("unroll") for (int i_ = 0; i_ < 4; ++i_) *(u32x4*)(sA_ + (sr + i_ * 64) * PITCH + scv * 8) = ra[S][i_]; \
;     _Pragma("unroll") for (int i_ = 0; i_ < 2; ++i_) *(u32x4*)(sB_ + (sr + i_ * 64) * PITCH + scv * 8) = rb[S][i_]; } while (0)
; template <class Epi>
; DI void gemm_tile(char* smem, const bf16_t* __restrict__ A0, int lda0, int ksplit, const bf16_t* __restrict__ A1, int lda1,
;                   const bf16_t* __restrict__ Bt, int K, int row0, int col0, const Epi& epi, int tid) {
;     ...
;   f32x4 acc[8][4];
; #pragma unroll
;   for (int m = 0; m < 8; ++m)
; #pragma unroll
;     for (int n = 0; n < 4; ++n) acc[m][n] = (f32x4){0.f, 0.f, 0.f, 0.f};
;   u32x4 ra[2][4], rb[2][2];
;   const int nk = K / BK;
;   const int sr = tid >> 2, scv = tid & 3;
;     ...
;   __syncthreads();
;   {
;     const int last = nk - 1;
;     GLOAD(0, 0);
;     __builtin_amdgcn_sched_barrier(0);
;     GLOAD(1, 1);
;     __builtin_amdgcn_sched_barrier(0);
;     LWRITE(0, 0);
;     __builtin_amdgcn_sched_barrier(0);
;     GLOAD(0, (2 < last ? 2 : last));
;     __builtin_amdgcn_sched_barrier(0);
;     __syncthreads();
; template <class Epi>
; DI void gemm_phase(char* smem, const bf16_t* A0, int lda0, int ksplit, const bf16_t* A1, int lda1, const bf16_t* Bt, int K, int nN, const Epi& epi, int tid) {
;     ...
;     const int x = blockIdx.x & 7, l = blockIdx.x >> 3, L = G >> 3, per = 8 * nN, tot = 2 * per;
;     for (int q = l; q < tot; q += L) { const int rgl = q / per, rem = q % per, ct = rem >> 3, rt = (x * 2 + rgl) * 8 + (rem & 7);
;       gemm_tile(smem, A0, lda0, ksplit, A1, lda1, Bt, K, rt * 256, ct * 128, epi, tid); }
.Lg3d_tile:
	s_cmpk_ge_u32 s15, 64
	s_cbranch_scc1 .Lg3d_done
	s_cmpk_ge_u32 s15, 32
	s_cselect_b32 s27, 1, 0
	s_cselect_b32 s26, 32, 0
	s_sub_u32 s26, s15, s26
	s_add_u32 s27, s27, s101
	s_lshl_b32 s27, s27, 3
	s_and_b32 s29, s26, 7
	s_add_u32 s29, s29, s27
	s_lshl_b32 s29, s29, 8
	s_lshr_b32 s28, s26, 3
	s_lshl_b32 s28, s28, 7
	s_mul_i32 s27, s29, 512
	s_add_u32 s27, s27, 0x1ea00100
	s_add_u32 s0, s92, s27
	s_addc_u32 s1, s93, 0
	s_mul_i32 s27, s28, 256
	s_add_u32 s27, s27, 0x3480000
	s_add_u32 s2, s92, s27
	s_addc_u32 s3, s93, 0
	s_waitcnt lgkmcnt(0)
	s_barrier
	s_mov_b32 s99, 0
	s_mov_b32 s30, 0
	s_add_u32 s26, s30, s100
	s_add_u32 m0, s26, 0
	s_nop 0
	global_load_lds_dwordx4 v224, s[0:1]
	s_add_u32 m0, s26, 4096
	s_nop 0
	global_load_lds_dwordx4 v225, s[0:1]
	s_add_u32 m0, s26, 8192
	s_nop 0
	global_load_lds_dwordx4 v226, s[0:1]
	s_add_u32 m0, s26, 12288
	s_nop 0
	global_load_lds_dwordx4 v227, s[0:1]
	s_add_u32 m0, s26, 16384
	s_nop 0
	global_load_lds_dwordx4 v228, s[2:3]
	s_add_u32 m0, s26, 20480
	s_nop 0
	global_load_lds_dwordx4 v229, s[2:3]
	s_add_u32 s0, s0, 64
	s_addc_u32 s1, s1, 0
	s_add_u32 s2, s2, 64
	s_addc_u32 s3, s3, 0
	s_add_u32 s99, s99, 1
	s_add_u32 s30, s30, 24576
	s_cmp_eq_u32 s30, 73728
	s_cselect_b32 s30, 0, s30
	s_add_u32 s26, s30, s100
	s_add_u32 m0, s26, 0
	s_nop 0
	global_load_lds_dwordx4 v224, s[0:1]
	s_add_u32 m0, s26, 4096
	s_nop 0
	global_load_lds_dwordx4 v225, s[0:1]
	s_add_u32 m0, s26, 8192
	s_nop 0
	global_load_lds_dwordx4 v226, s[0:1]
	s_add_u32 m0, s26, 12288
	s_nop 0
	global_load_lds_dwordx4 v227, s[0:1]
	s_add_u32 m0, s26, 16384
	s_nop 0
	global_load_lds_dwordx4 v228, s[2:3]
	s_add_u32 m0, s26, 20480
	s_nop 0
	global_load_lds_dwordx4 v229, s[2:3]
	s_add_u32 s0, s0, 64
	s_addc_u32 s1, s1, 0
	s_add_u32 s2, s2, 64
	s_addc_u32 s3, s3, 0
	s_add_u32 s99, s99, 1
	s_add_u32 s30, s30, 24576
	s_cmp_eq_u32 s30, 73728
	s_cselect_b32 s30, 0, s30
	s_add_u32 s26, s30, s100
	s_add_u32 m0, s26, 0
	s_nop 0
	global_load_lds_dwordx4 v224, s[0:1]
	s_add_u32 m0, s26, 4096
	s_nop 0
	global_load_lds_dwordx4 v225, s[0:1]
	s_add_u32 m0, s26, 8192
	s_nop 0
	global_load_lds_dwordx4 v226, s[0:1]
	s_add_u32 m0, s26, 12288
	s_nop 0
	global_load_lds_dwordx4 v227, s[0:1]
	s_add_u32 m0, s26, 16384
	s_nop 0
	global_load_lds_dwordx4 v228, s[2:3]
	s_add_u32 m0, s26, 20480
	s_nop 0
	global_load_lds_dwordx4 v229, s[2:3]
	s_add_u32 s0, s0, 64
	s_addc_u32 s1, s1, 0
	s_add_u32 s2, s2, 64
	s_addc_u32 s3, s3, 0
	s_add_u32 s99, s99, 1
	s_add_u32 s30, s30, 24576
	s_cmp_eq_u32 s30, 73728
	s_cselect_b32 s30, 0, s30
	v_mov_b32_e32 v0, 0
	v_mov_b32_e32 v1, 0
	v_mov_b32_e32 v2, 0
	v_mov_b32_e32 v3, 0
	v_mov_b32_e32 v4, 0
	v_mov_b32_e32 v5, 0
	v_mov_b32_e32 v6, 0
	v_mov_b32_e32 v7, 0
	v_mov_b32_e32 v8, 0
	v_mov_b32_e32 v9, 0
	v_mov_b32_e32 v10, 0
	v_mov_b32_e32 v11, 0
	v_mov_b32_e32 v12, 0
	v_mov_b32_e32 v13, 0
	v_mov_b32_e32 v14, 0
	v_mov_b32_e32 v15, 0
	v_mov_b32_e32 v16, 0
	v_mov_b32_e32 v17, 0
	v_mov_b32_e32 v18, 0
	v_mov_b32_e32 v19, 0
	v_mov_b32_e32 v20, 0
	v_mov_b32_e32 v21, 0
	v_mov_b32_e32 v22, 0
	v_mov_b32_e32 v23, 0
	v_mov_b32_e32 v24, 0
	v_mov_b32_e32 v25, 0
	v_mov_b32_e32 v26, 0
	v_mov_b32_e32 v27, 0
	v_mov_b32_e32 v28, 0
	v_mov_b32_e32 v29, 0
	v_mov_b32_e32 v30, 0
	v_mov_b32_e32 v31, 0
	v_mov_b32_e32 v32, 0
	v_mov_b32_e32 v33, 0
	v_mov_b32_e32 v34, 0
	v_mov_b32_e32 v35, 0
	v_mov_b32_e32 v36, 0
	v_mov_b32_e32 v37, 0
	v_mov_b32_e32 v38, 0
	v_mov_b32_e32 v39, 0
	v_mov_b32_e32 v40, 0
	v_mov_b32_e32 v41, 0
	v_mov_b32_e32 v42, 0
	v_mov_b32_e32 v43, 0
	v_mov_b32_e32 v44, 0
	v_mov_b32_e32 v45, 0
	v_mov_b32_e32 v46, 0
	v_mov_b32_e32 v47, 0
	v_mov_b32_e32 v48, 0
	v_mov_b32_e32 v49, 0
	v_mov_b32_e32 v50, 0
	v_mov_b32_e32 v51, 0
	v_mov_b32_e32 v52, 0
	v_mov_b32_e32 v53, 0
	v_mov_b32_e32 v54, 0
	v_mov_b32_e32 v55, 0
	v_mov_b32_e32 v56, 0
	v_mov_b32_e32 v57, 0
	v_mov_b32_e32 v58, 0
	v_mov_b32_e32 v59, 0
	v_mov_b32_e32 v60, 0
	v_mov_b32_e32 v61, 0
	v_mov_b32_e32 v62, 0
	v_mov_b32_e32 v63, 0
	v_mov_b32_e32 v64, 0
	v_mov_b32_e32 v65, 0
	v_mov_b32_e32 v66, 0
	v_mov_b32_e32 v67, 0
	v_mov_b32_e32 v68, 0
	v_mov_b32_e32 v69, 0
	v_mov_b32_e32 v70, 0
	v_mov_b32_e32 v71, 0
	v_mov_b32_e32 v72, 0
	v_mov_b32_e32 v73, 0
	v_mov_b32_e32 v74, 0
	v_mov_b32_e32 v75, 0
	v_mov_b32_e32 v76, 0
	v_mov_b32_e32 v77, 0
	v_mov_b32_e32 v78, 0
	v_mov_b32_e32 v79, 0
	v_mov_b32_e32 v80, 0
	v_mov_b32_e32 v81, 0
	v_mov_b32_e32 v82, 0
	v_mov_b32_e32 v83, 0
	v_mov_b32_e32 v84, 0
	v_mov_b32_e32 v85, 0
	v_mov_b32_e32 v86, 0
	v_mov_b32_e32 v87, 0
	v_mov_b32_e32 v88, 0
	v_mov_b32_e32 v89, 0
	v_mov_b32_e32 v90, 0
	v_mov_b32_e32 v91, 0
	v_mov_b32_e32 v92, 0
	v_mov_b32_e32 v93, 0
	v_mov_b32_e32 v94, 0
	v_mov_b32_e32 v95, 0
	v_mov_b32_e32 v96, 0
	v_mov_b32_e32 v97, 0
	v_mov_b32_e32 v98, 0
	v_mov_b32_e32 v99, 0
	v_mov_b32_e32 v100, 0
	v_mov_b32_e32 v101, 0
	v_mov_b32_e32 v102, 0
	v_mov_b32_e32 v103, 0
	v_mov_b32_e32 v104, 0
	v_mov_b32_e32 v105, 0
	v_mov_b32_e32 v106, 0
	v_mov_b32_e32 v107, 0
	v_mov_b32_e32 v108, 0
	v_mov_b32_e32 v109, 0
	v_mov_b32_e32 v110, 0
	v_mov_b32_e32 v111, 0
	v_mov_b32_e32 v112, 0
	v_mov_b32_e32 v113, 0
	v_mov_b32_e32 v114, 0
	v_mov_b32_e32 v115, 0
	v_mov_b32_e32 v116, 0
	v_mov_b32_e32 v117, 0
	v_mov_b32_e32 v118, 0
	v_mov_b32_e32 v119, 0
	v_mov_b32_e32 v120, 0
	v_mov_b32_e32 v121, 0
	v_mov_b32_e32 v122, 0
	v_mov_b32_e32 v123, 0
	v_mov_b32_e32 v124, 0
	v_mov_b32_e32 v125, 0
	v_mov_b32_e32 v126, 0
	v_mov_b32_e32 v127, 0
	s_mov_b32 s98, 0
	s_mov_b32 s31, 24576
	s_waitcnt vmcnt(12)
	s_barrier
; #define LWRITE(S, buf) do { bf16_t* sA_ = sbase + (buf) * BUF; bf16_t* sB_ = sA_ + 256 * PITCH; \
;     _Pragma("unroll") for (int i_ = 0; i_ < 4; ++i_) *(u32x4*)(sA_ + (sr + i_ * 64) * PITCH + scv * 8) = ra[S][i_]; \
;     _Pragma("unroll") for (int i_ = 0; i_ < 2; ++i_) *(u32x4*)(sB_ + (sr + i_ * 64) * PITCH + scv * 8) = rb[S][i_]; } while (0)
; template <class Epi>
; DI void gemm_tile(char* smem, const bf16_t* __restrict__ A0, int lda0, int ksplit, const bf16_t* __restrict__ A1, int lda1,
;                   const bf16_t* __restrict__ Bt, int K, int row0, int col0, const Epi& epi, int tid) {
;     ...
;   __syncthreads();
;   {
;     const int last = nk - 1;
;     GLOAD(0, 0);
;     __builtin_amdgcn_sched_barrier(0);
;     GLOAD(1, 1);
;     __builtin_amdgcn_sched_barrier(0);
;     LWRITE(0, 0);
;     __builtin_amdgcn_sched_barrier(0);
;     GLOAD(0, (2 < last ? 2 : last));
;     __builtin_amdgcn_sched_barrier(0);
;     __syncthreads();
;     for (int kt = 0; kt < nk; kt += 2) {
;       LWRITE(1, 1);
;       __builtin_amdgcn_sched_barrier(0);
;       GLOAD(1, (kt + 3 < last ? kt + 3 : last));
;       __builtin_amdgcn_sched_barrier(0);
;       COMPUTE(0);
;       __syncthreads();
;       LWRITE(0, 0);
;       __builtin_amdgcn_sched_barrier(0);
;       GLOAD(0, (kt + 4 < last ? kt + 4 : last));
;       __builtin_amdgcn_sched_barrier(0);
;       COMPUTE(1);
;       __syncthreads();
;     }
	ds_read_b128 v[128:131], v231 offset:0
	ds_read_b128 v[132:135], v231 offset:1024
	ds_read_b128 v[136:139], v231 offset:2048
	ds_read_b128 v[140:143], v231 offset:3072
	ds_read_b128 v[144:147], v230 offset:0
	ds_read_b128 v[148:151], v230 offset:1024
	ds_read_b128 v[152:155], v230 offset:2048
	ds_read_b128 v[156:159], v230 offset:3072
	ds_read_b128 v[160:163], v230 offset:4096
	ds_read_b128 v[164:167], v230 offset:5120
	ds_read_b128 v[168:171], v230 offset:6144
	ds_read_b128 v[172:175], v230 offset:7168
	s_waitcnt vmcnt(6)
	s_waitcnt lgkmcnt(0)
	s_barrier
	v_add_u32_e32 v232, s31, v230
	v_add_u32_e32 v233, s31, v231
	s_add_u32 s26, s30, s100
	s_setprio 1
	v_mfma_f32_16x16x32_bf16 v[0:3], v[128:131], v[144:147], v[0:3]
	v_mfma_f32_16x16x32_bf16 v[4:7], v[132:135], v[144:147], v[4:7]
	v_mfma_f32_16x16x32_bf16 v[8:11], v[136:139], v[144:147], v[8:11]
	v_mfma_f32_16x16x32_bf16 v[12:15], v[140:143], v[144:147], v[12:15]
	ds_read_b128 v[176:179], v233 offset:0
	ds_read_b128 v[180:183], v233 offset:1024
	s_add_u32 m0, s26, 0
	s_nop 0
	global_load_lds_dwordx4 v224, s[0:1]
	v_mfma_f32_16x16x32_bf16 v[16:19], v[128:131], v[148:151], v[16:19]
	v_mfma_f32_16x16x32_bf16 v[20:23], v[132:135], v[148:151], v[20:23]
	v_mfma_f32_16x16x32_bf16 v[24:27], v[136:139], v[148:151], v[24:27]
	v_mfma_f32_16x16x32_bf16 v[28:31], v[140:143], v[148:151], v[28:31]
	ds_read_b128 v[184:187], v233 offset:2048
	ds_read_b128 v[188:191], v233 offset:3072
	s_add_u32 m0, s26, 4096
	s_nop 0
	global_load_lds_dwordx4 v225, s[0:1]
	v_mfma_f32_16x16x32_bf16 v[32:35], v[128:131], v[152:155], v[32:35]
	v_mfma_f32_16x16x32_bf16 v[36:39], v[132:135], v[152:155], v[36:39]
	v_mfma_f32_16x16x32_bf16 v[40:43], v[136:139], v[152:155], v[40:43]
	v_mfma_f32_16x16x32_bf16 v[44:47], v[140:143], v[152:155], v[44:47]
	ds_read_b128 v[192:195], v232 offset:0
	ds_read_b128 v[196:199], v232 offset:1024
	s_add_u32 m0, s26, 8192
	s_nop 0
	global_load_lds_dwordx4 v226, s[0:1]
	v_mfma_f32_16x16x32_bf16 v[48:51], v[128:131], v[156:159], v[48:51]
	v_mfma_f32_16x16x32_bf16 v[52:55], v[132:135], v[156:159], v[52:55]
	v_mfma_f32_16x16x32_bf16 v[56:59], v[136:139], v[156:159], v[56:59]
	v_mfma_f32_16x16x32_bf16 v[60:63], v[140:143], v[156:159], v[60:63]
	ds_read_b128 v[200:203], v232 offset:2048
	ds_read_b128 v[204:207], v232 offset:3072
	s_add_u32 m0, s26, 12288
	s_nop 0
	global_load_lds_dwordx4 v227, s[0:1]
	v_mfma_f32_16x16x32_bf16 v[64:67], v[128:131], v[160:163], v[64:67]
	v_mfma_f32_16x16x32_bf16 v[68:71], v[132:135], v[160:163], v[68:71]
	v_mfma_f32_16x16x32_bf16 v[72:75], v[136:139], v[160:163], v[72:75]
	v_mfma_f32_16x16x32_bf16 v[76:79], v[140:143], v[160:163], v[76:79]
	ds_read_b128 v[208:211], v232 offset:4096
	s_add_u32 m0, s26, 16384
	s_nop 0
	global_load_lds_dwordx4 v228, s[2:3]
	s_cmp_eq_u32 s25, 0
	s_cbranch_scc0 .Lg3d_hi0
	s_setprio 0
.Lg3d_hi0:
	v_mfma_f32_16x16x32_bf16 v[80:83], v[128:131], v[164:167], v[80:83]
	v_mfma_f32_16x16x32_bf16 v[84:87], v[132:135], v[164:167], v[84:87]
	v_mfma_f32_16x16x32_bf16 v[88:91], v[136:139], v[164:167], v[88:91]
	v_mfma_f32_16x16x32_bf16 v[92:95], v[140:143], v[164:167], v[92:95]
	ds_read_b128 v[212:215], v232 offset:5120
	s_add_u32 m0, s26, 20480
	s_nop 0
	global_load_lds_dwordx4 v229, s[2:3]
	v_mfma_f32_16x16x32_bf16 v[96:99], v[128:131], v[168:171], v[96:99]
	v_mfma_f32_16x16x32_bf16 v[100:103], v[132:135], v[168:171], v[100:103]
	v_mfma_f32_16x16x32_bf16 v[104:107], v[136:139], v[168:171], v[104:107]
	v_mfma_f32_16x16x32_bf16 v[108:111], v[140:143], v[168:171], v[108:111]
	ds_read_b128 v[216:219], v232 offset:6144
	s_add_u32 s0, s0, 64
	s_addc_u32 s1, s1, 0
	s_add_u32 s2, s2, 64
	s_addc_u32 s3, s3, 0
	s_add_u32 s99, s99, 1
	s_add_u32 s30, s30, 24576
	s_cmp_eq_u32 s30, 73728
	s_cselect_b32 s30, 0, s30
	s_add_u32 s31, s31, 24576
	s_cmp_eq_u32 s31, 73728
	s_cselect_b32 s31, 0, s31
	v_mfma_f32_16x16x32_bf16 v[112:115], v[128:131], v[172:175], v[112:115]
	v_mfma_f32_16x16x32_bf16 v[116:119], v[132:135], v[172:175], v[116:119]
	v_mfma_f32_16x16x32_bf16 v[120:123], v[136:139], v[172:175], v[120:123]
	v_mfma_f32_16x16x32_bf16 v[124:127], v[140:143], v[172:175], v[124:127]
	ds_read_b128 v[220:223], v232 offset:7168
	s_waitcnt vmcnt(6)
	s_waitcnt lgkmcnt(0)
	s_barrier
	v_add_u32_e32 v232, s31, v230
	v_add_u32_e32 v233, s31, v231
	s_setprio 1
	v_mfma_f32_16x16x32_bf16 v[0:3], v[176:179], v[192:195], v[0:3]
	v_mfma_f32_16x16x32_bf16 v[4:7], v[180:183], v[192:195], v[4:7]
	v_mfma_f32_16x16x32_bf16 v[8:11], v[184:187], v[192:195], v[8:11]
	v_mfma_f32_16x16x32_bf16 v[12:15], v[188:191], v[192:195], v[12:15]
	ds_read_b128 v[128:131], v233 offset:0
	ds_read_b128 v[132:135], v233 offset:1024
	v_mfma_f32_16x16x32_bf16 v[16:19], v[176:179], v[196:199], v[16:19]
	v_mfma_f32_16x16x32_bf16 v[20:23], v[180:183], v[196:199], v[20:23]
	v_mfma_f32_16x16x32_bf16 v[24:27], v[184:187], v[196:199], v[24:27]
	v_mfma_f32_16x16x32_bf16 v[28:31], v[188:191], v[196:199], v[28:31]
	ds_read_b128 v[136:139], v233 offset:2048
	ds_read_b128 v[140:143], v233 offset:3072
	v_mfma_f32_16x16x32_bf16 v[32:35], v[176:179], v[200:203], v[32:35]
	v_mfma_f32_16x16x32_bf16 v[36:39], v[180:183], v[200:203], v[36:39]
	v_mfma_f32_16x16x32_bf16 v[40:43], v[184:187], v[200:203], v[40:43]
	v_mfma_f32_16x16x32_bf16 v[44:47], v[188:191], v[200:203], v[44:47]
	ds_read_b128 v[144:147], v232 offset:0
	ds_read_b128 v[148:151], v232 offset:1024
	v_mfma_f32_16x16x32_bf16 v[48:51], v[176:179], v[204:207], v[48:51]
	v_mfma_f32_16x16x32_bf16 v[52:55], v[180:183], v[204:207], v[52:55]
	v_mfma_f32_16x16x32_bf16 v[56:59], v[184:187], v[204:207], v[56:59]
	v_mfma_f32_16x16x32_bf16 v[60:63], v[188:191], v[204:207], v[60:63]
	ds_read_b128 v[152:155], v232 offset:2048
	ds_read_b128 v[156:159], v232 offset:3072
	v_mfma_f32_16x16x32_bf16 v[64:67], v[176:179], v[208:211], v[64:67]
	v_mfma_f32_16x16x32_bf16 v[68:71], v[180:183], v[208:211], v[68:71]
	v_mfma_f32_16x16x32_bf16 v[72:75], v[184:187], v[208:211], v[72:75]
	v_mfma_f32_16x16x32_bf16 v[76:79], v[188:191], v[208:211], v[76:79]
	ds_read_b128 v[160:163], v232 offset:4096
	s_cmp_eq_u32 s25, 0
	s_cbranch_scc0 .Lg3d_hi1
	s_setprio 0
; #define LWRITE(S, buf) do { bf16_t* sA_ = sbase + (buf) * BUF; bf16_t* sB_ = sA_ + 256 * PITCH; \
;     _Pragma("unroll") for (int i_ = 0; i_ < 4; ++i_) *(u32x4*)(sA_ + (sr + i_ * 64) * PITCH + scv * 8) = ra[S][i_]; \
;     _Pragma("unroll") for (int i_ = 0; i_ < 2; ++i_) *(u32x4*)(sB_ + (sr + i_ * 64) * PITCH + scv * 8) = rb[S][i_]; } while (0)
; template <class Epi>
; DI void gemm_tile(char* smem, const bf16_t* __restrict__ A0, int lda0, int ksplit, const bf16_t* __restrict__ A1, int lda1,
;                   const bf16_t* __restrict__ Bt, int K, int row0, int col0, const Epi& epi, int tid) {
;     ...
;   __syncthreads();
;   {
;     const int last = nk - 1;
;     GLOAD(0, 0);
;     __builtin_amdgcn_sched_barrier(0);
;     GLOAD(1, 1);
;     __builtin_amdgcn_sched_barrier(0);
;     LWRITE(0, 0);
;     __builtin_amdgcn_sched_barrier(0);
;     GLOAD(0, (2 < last ? 2 : last));
;     __builtin_amdgcn_sched_barrier(0);
;     __syncthreads();
;     for (int kt = 0; kt < nk; kt += 2) {
;       LWRITE(1, 1);
;       __builtin_amdgcn_sched_barrier(0);
;       GLOAD(1, (kt + 3 < last ? kt + 3 : last));
;       __builtin_amdgcn_sched_barrier(0);
;       COMPUTE(0);
;       __syncthreads();
;       LWRITE(0, 0);
;       __builtin_amdgcn_sched_barrier(0);
;       GLOAD(0, (kt + 4 < last ? kt + 4 : last));
;       __builtin_amdgcn_sched_barrier(0);
;       COMPUTE(1);
;       __syncthreads();
;     }
.Lg3d_hi1:
	v_mfma_f32_16x16x32_bf16 v[80:83], v[176:179], v[212:215], v[80:83]
	v_mfma_f32_16x16x32_bf16 v[84:87], v[180:183], v[212:215], v[84:87]
	v_mfma_f32_16x16x32_bf16 v[88:91], v[184:187], v[212:215], v[88:91]
	v_mfma_f32_16x16x32_bf16 v[92:95], v[188:191], v[212:215], v[92:95]
	ds_read_b128 v[164:167], v232 offset:5120
	v_mfma_f32_16x16x32_bf16 v[96:99], v[176:179], v[216:219], v[96:99]
	v_mfma_f32_16x16x32_bf16 v[100:103], v[180:183], v[216:219], v[100:103]
	v_mfma_f32_16x16x32_bf16 v[104:107], v[184:187], v[216:219], v[104:107]
	v_mfma_f32_16x16x32_bf16 v[108:111], v[188:191], v[216:219], v[108:111]
	ds_read_b128 v[168:171], v232 offset:6144
	s_add_u32 s31, s31, 24576
	s_cmp_eq_u32 s31, 73728
	s_cselect_b32 s31, 0, s31
	v_mfma_f32_16x16x32_bf16 v[112:115], v[176:179], v[220:223], v[112:115]
	v_mfma_f32_16x16x32_bf16 v[116:119], v[180:183], v[220:223], v[116:119]
	v_mfma_f32_16x16x32_bf16 v[120:123], v[184:187], v[220:223], v[120:123]
	v_mfma_f32_16x16x32_bf16 v[124:127], v[188:191], v[220:223], v[124:127]
	ds_read_b128 v[172:175], v232 offset:7168
	s_waitcnt vmcnt(0)
	s_waitcnt lgkmcnt(0)
	s_barrier
	v_add_u32_e32 v232, s31, v230
	v_add_u32_e32 v233, s31, v231
	s_setprio 1
	v_mfma_f32_16x16x32_bf16 v[0:3], v[128:131], v[144:147], v[0:3]
	v_mfma_f32_16x16x32_bf16 v[4:7], v[132:135], v[144:147], v[4:7]
	v_mfma_f32_16x16x32_bf16 v[8:11], v[136:139], v[144:147], v[8:11]
	v_mfma_f32_16x16x32_bf16 v[12:15], v[140:143], v[144:147], v[12:15]
	ds_read_b128 v[176:179], v233 offset:0
	ds_read_b128 v[180:183], v233 offset:1024
	v_mfma_f32_16x16x32_bf16 v[16:19], v[128:131], v[148:151], v[16:19]
	v_mfma_f32_16x16x32_bf16 v[20:23], v[132:135], v[148:151], v[20:23]
	v_mfma_f32_16x16x32_bf16 v[24:27], v[136:139], v[148:151], v[24:27]
	v_mfma_f32_16x16x32_bf16 v[28:31], v[140:143], v[148:151], v[28:31]
	ds_read_b128 v[184:187], v233 offset:2048
	ds_read_b128 v[188:191], v233 offset:3072
	v_mfma_f32_16x16x32_bf16 v[32:35], v[128:131], v[152:155], v[32:35]
	v_mfma_f32_16x16x32_bf16 v[36:39], v[132:135], v[152:155], v[36:39]
	v_mfma_f32_16x16x32_bf16 v[40:43], v[136:139], v[152:155], v[40:43]
	v_mfma_f32_16x16x32_bf16 v[44:47], v[140:143], v[152:155], v[44:47]
	ds_read_b128 v[192:195], v232 offset:0
	ds_read_b128 v[196:199], v232 offset:1024
	v_mfma_f32_16x16x32_bf16 v[48:51], v[128:131], v[156:159], v[48:51]
	v_mfma_f32_16x16x32_bf16 v[52:55], v[132:135], v[156:159], v[52:55]
	v_mfma_f32_16x16x32_bf16 v[56:59], v[136:139], v[156:159], v[56:59]
	v_mfma_f32_16x16x32_bf16 v[60:63], v[140:143], v[156:159], v[60:63]
	ds_read_b128 v[200:203], v232 offset:2048
	ds_read_b128 v[204:207], v232 offset:3072
	v_mfma_f32_16x16x32_bf16 v[64:67], v[128:131], v[160:163], v[64:67]
	v_mfma_f32_16x16x32_bf16 v[68:71], v[132:135], v[160:163], v[68:71]
	v_mfma_f32_16x16x32_bf16 v[72:75], v[136:139], v[160:163], v[72:75]
	v_mfma_f32_16x16x32_bf16 v[76:79], v[140:143], v[160:163], v[76:79]
	ds_read_b128 v[208:211], v232 offset:4096
	s_cmp_eq_u32 s25, 0
	s_cbranch_scc0 .Lg3d_hi2
	s_setprio 0

; #define LWRITE(S, buf) do { bf16_t* sA_ = sbase + (buf) * BUF; bf16_t* sB_ = sA_ + 256 * PITCH; \
;     _Pragma("unroll") for (int i_ = 0; i_ < 4; ++i_) *(u32x4*)(sA_ + (sr + i_ * 64) * PITCH + scv * 8) = ra[S][i_]; \
;     _Pragma("unroll") for (int i_ = 0; i_ < 2; ++i_) *(u32x4*)(sB_ + (sr + i_ * 64) * PITCH + scv * 8) = rb[S][i_]; } while (0)
; template <class Epi>
; DI void gemm_tile(char* smem, const bf16_t* __restrict__ A0, int lda0, int ksplit, const bf16_t* __restrict__ A1, int lda1,
;                   const bf16_t* __restrict__ Bt, int K, int row0, int col0, const Epi& epi, int tid) {
;     ...
;   __syncthreads();
;   {
;     const int last = nk - 1;
;     GLOAD(0, 0);
;     __builtin_amdgcn_sched_barrier(0);
;     GLOAD(1, 1);
;     __builtin_amdgcn_sched_barrier(0);
;     LWRITE(0, 0);
;     __builtin_amdgcn_sched_barrier(0);
;     GLOAD(0, (2 < last ? 2 : last));
;     __builtin_amdgcn_sched_barrier(0);
;     __syncthreads();
;     for (int kt = 0; kt < nk; kt += 2) {
;       LWRITE(1, 1);
;       __builtin_amdgcn_sched_barrier(0);
;       GLOAD(1, (kt + 3 < last ? kt + 3 : last));
;       __builtin_amdgcn_sched_barrier(0);
;       COMPUTE(0);
;       __syncthreads();
;       LWRITE(0, 0);
;       __builtin_amdgcn_sched_barrier(0);
;       GLOAD(0, (kt + 4 < last ? kt + 4 : last));
;       __builtin_amdgcn_sched_barrier(0);
;       COMPUTE(1);
;       __syncthreads();
;     }
.Lg6_swb0:
	s_waitcnt vmcnt(6)
	s_waitcnt lgkmcnt(0)
	s_barrier
	v_add_u32_e32 v232, s100, v230
	v_add_u32_e32 v233, s100, v231
	s_add_u32 s19, s99, s13
	s_setprio 1
	v_mfma_f32_16x16x32_bf16 v[0:3], v[128:131], v[144:147], v[0:3]
	v_mfma_f32_16x16x32_bf16 v[4:7], v[132:135], v[144:147], v[4:7]
	v_mfma_f32_16x16x32_bf16 v[8:11], v[136:139], v[144:147], v[8:11]
	v_mfma_f32_16x16x32_bf16 v[12:15], v[140:143], v[144:147], v[12:15]
	ds_read_b128 v[176:179], v233 offset:0
	ds_read_b128 v[180:183], v233 offset:1024
	s_add_u32 m0, s19, 0
	s_nop 0
	global_load_lds_dwordx4 v224, s[0:1]
	v_mfma_f32_16x16x32_bf16 v[16:19], v[128:131], v[148:151], v[16:19]
	v_mfma_f32_16x16x32_bf16 v[20:23], v[132:135], v[148:151], v[20:23]
	v_mfma_f32_16x16x32_bf16 v[24:27], v[136:139], v[148:151], v[24:27]
	v_mfma_f32_16x16x32_bf16 v[28:31], v[140:143], v[148:151], v[28:31]
	ds_read_b128 v[184:187], v233 offset:2048
	ds_read_b128 v[188:191], v233 offset:3072
	s_add_u32 m0, s19, 4096
	s_nop 0
	global_load_lds_dwordx4 v225, s[0:1]
	v_mfma_f32_16x16x32_bf16 v[32:35], v[128:131], v[152:155], v[32:35]
	v_mfma_f32_16x16x32_bf16 v[36:39], v[132:135], v[152:155], v[36:39]
	v_mfma_f32_16x16x32_bf16 v[40:43], v[136:139], v[152:155], v[40:43]
	v_mfma_f32_16x16x32_bf16 v[44:47], v[140:143], v[152:155], v[44:47]
	ds_read_b128 v[192:195], v232 offset:0
	ds_read_b128 v[196:199], v232 offset:1024
	s_add_u32 m0, s19, 8192
	s_nop 0
	global_load_lds_dwordx4 v226, s[0:1]
	v_mfma_f32_16x16x32_bf16 v[48:51], v[128:131], v[156:159], v[48:51]
	v_mfma_f32_16x16x32_bf16 v[52:55], v[132:135], v[156:159], v[52:55]
	v_mfma_f32_16x16x32_bf16 v[56:59], v[136:139], v[156:159], v[56:59]
	v_mfma_f32_16x16x32_bf16 v[60:63], v[140:143], v[156:159], v[60:63]
	ds_read_b128 v[200:203], v232 offset:2048
	ds_read_b128 v[204:207], v232 offset:3072
	s_add_u32 m0, s19, 12288
	s_nop 0
	global_load_lds_dwordx4 v227, s[0:1]
	v_mfma_f32_16x16x32_bf16 v[64:67], v[128:131], v[160:163], v[64:67]
	v_mfma_f32_16x16x32_bf16 v[68:71], v[132:135], v[160:163], v[68:71]
	v_mfma_f32_16x16x32_bf16 v[72:75], v[136:139], v[160:163], v[72:75]
	v_mfma_f32_16x16x32_bf16 v[76:79], v[140:143], v[160:163], v[76:79]
	ds_read_b128 v[208:211], v232 offset:4096
	s_add_u32 m0, s19, 16384
	s_nop 0
	global_load_lds_dwordx4 v228, s[2:3]
	s_cmp_eq_u32 s18, 0
	s_cbranch_scc0 .Lg6_hi0
	s_setprio 0
.Lg6_hi0:
	v_mfma_f32_16x16x32_bf16 v[80:83], v[128:131], v[164:167], v[80:83]
	v_mfma_f32_16x16x32_bf16 v[84:87], v[132:135], v[164:167], v[84:87]
	v_mfma_f32_16x16x32_bf16 v[88:91], v[136:139], v[164:167], v[88:91]
	v_mfma_f32_16x16x32_bf16 v[92:95], v[140:143], v[164:167], v[92:95]
	ds_read_b128 v[212:215], v232 offset:5120
	s_add_u32 m0, s19, 20480
	s_nop 0
	global_load_lds_dwordx4 v229, s[2:3]
	v_mfma_f32_16x16x32_bf16 v[96:99], v[128:131], v[168:171], v[96:99]
	v_mfma_f32_16x16x32_bf16 v[100:103], v[132:135], v[168:171], v[100:103]
	v_mfma_f32_16x16x32_bf16 v[104:107], v[136:139], v[168:171], v[104:107]
	v_mfma_f32_16x16x32_bf16 v[108:111], v[140:143], v[168:171], v[108:111]
	ds_read_b128 v[216:219], v232 offset:6144
	s_add_u32 s0, s0, 64
	s_addc_u32 s1, s1, 0
	s_add_u32 s2, s2, 64
	s_addc_u32 s3, s3, 0
	s_add_u32 s22, s22, 1
	s_add_u32 s99, s99, 24576
	s_cmp_eq_u32 s99, 73728
	s_cselect_b32 s99, 0, s99
	s_add_u32 s100, s100, 24576
	s_cmp_eq_u32 s100, 73728
	s_cselect_b32 s100, 0, s100
	v_mfma_f32_16x16x32_bf16 v[112:115], v[128:131], v[172:175], v[112:115]
	v_mfma_f32_16x16x32_bf16 v[116:119], v[132:135], v[172:175], v[116:119]
	v_mfma_f32_16x16x32_bf16 v[120:123], v[136:139], v[172:175], v[120:123]
	v_mfma_f32_16x16x32_bf16 v[124:127], v[140:143], v[172:175], v[124:127]
	ds_read_b128 v[220:223], v232 offset:7168
	s_cmp_eq_u32 s22, 16
	s_cbranch_scc1 .Lg6_sw1
; #define LWRITE(S, buf) do { bf16_t* sA_ = sbase + (buf) * BUF; bf16_t* sB_ = sA_ + 256 * PITCH; \
;     _Pragma("unroll") for (int i_ = 0; i_ < 4; ++i_) *(u32x4*)(sA_ + (sr + i_ * 64) * PITCH + scv * 8) = ra[S][i_]; \
;     _Pragma("unroll") for (int i_ = 0; i_ < 2; ++i_) *(u32x4*)(sB_ + (sr + i_ * 64) * PITCH + scv * 8) = rb[S][i_]; } while (0)
; template <class Epi>
; DI void gemm_tile(char* smem, const bf16_t* __restrict__ A0, int lda0, int ksplit, const bf16_t* __restrict__ A1, int lda1,
;                   const bf16_t* __restrict__ Bt, int K, int row0, int col0, const Epi& epi, int tid) {
;     ...
;   __syncthreads();
;   {
;     const int last = nk - 1;
;     GLOAD(0, 0);
;     __builtin_amdgcn_sched_barrier(0);
;     GLOAD(1, 1);
;     __builtin_amdgcn_sched_barrier(0);
;     LWRITE(0, 0);
;     __builtin_amdgcn_sched_barrier(0);
;     GLOAD(0, (2 < last ? 2 : last));
;     __builtin_amdgcn_sched_barrier(0);
;     __syncthreads();
;     for (int kt = 0; kt < nk; kt += 2) {
;       LWRITE(1, 1);
;       __builtin_amdgcn_sched_barrier(0);
;       GLOAD(1, (kt + 3 < last ? kt + 3 : last));
;       __builtin_amdgcn_sched_barrier(0);
;       COMPUTE(0);
;       __syncthreads();
;       LWRITE(0, 0);
;       __builtin_amdgcn_sched_barrier(0);
;       GLOAD(0, (kt + 4 < last ? kt + 4 : last));
;       __builtin_amdgcn_sched_barrier(0);
;       COMPUTE(1);
;       __syncthreads();
;     }
.Lg6_swb1:
	s_waitcnt vmcnt(6)
	s_waitcnt lgkmcnt(0)
	s_barrier
	v_add_u32_e32 v232, s100, v230
	v_add_u32_e32 v233, s100, v231
	s_add_u32 s19, s99, s13
	s_setprio 1
	v_mfma_f32_16x16x32_bf16 v[0:3], v[176:179], v[192:195], v[0:3]
	v_mfma_f32_16x16x32_bf16 v[4:7], v[180:183], v[192:195], v[4:7]
	v_mfma_f32_16x16x32_bf16 v[8:11], v[184:187], v[192:195], v[8:11]
	v_mfma_f32_16x16x32_bf16 v[12:15], v[188:191], v[192:195], v[12:15]
	ds_read_b128 v[128:131], v233 offset:0
	ds_read_b128 v[132:135], v233 offset:1024
	s_add_u32 m0, s19, 0
	s_nop 0
	global_load_lds_dwordx4 v224, s[0:1]
	v_mfma_f32_16x16x32_bf16 v[16:19], v[176:179], v[196:199], v[16:19]
	v_mfma_f32_16x16x32_bf16 v[20:23], v[180:183], v[196:199], v[20:23]
	v_mfma_f32_16x16x32_bf16 v[24:27], v[184:187], v[196:199], v[24:27]
	v_mfma_f32_16x16x32_bf16 v[28:31], v[188:191], v[196:199], v[28:31]
	ds_read_b128 v[136:139], v233 offset:2048
	ds_read_b128 v[140:143], v233 offset:3072
	s_add_u32 m0, s19, 4096
	s_nop 0
	global_load_lds_dwordx4 v225, s[0:1]
	v_mfma_f32_16x16x32_bf16 v[32:35], v[176:179], v[200:203], v[32:35]
	v_mfma_f32_16x16x32_bf16 v[36:39], v[180:183], v[200:203], v[36:39]
	v_mfma_f32_16x16x32_bf16 v[40:43], v[184:187], v[200:203], v[40:43]
	v_mfma_f32_16x16x32_bf16 v[44:47], v[188:191], v[200:203], v[44:47]
	ds_read_b128 v[144:147], v232 offset:0
	ds_read_b128 v[148:151], v232 offset:1024
	s_add_u32 m0, s19, 8192
	s_nop 0
	global_load_lds_dwordx4 v226, s[0:1]
	v_mfma_f32_16x16x32_bf16 v[48:51], v[176:179], v[204:207], v[48:51]
	v_mfma_f32_16x16x32_bf16 v[52:55], v[180:183], v[204:207], v[52:55]
	v_mfma_f32_16x16x32_bf16 v[56:59], v[184:187], v[204:207], v[56:59]
	v_mfma_f32_16x16x32_bf16 v[60:63], v[188:191], v[204:207], v[60:63]
	ds_read_b128 v[152:155], v232 offset:2048
	ds_read_b128 v[156:159], v232 offset:3072
	s_add_u32 m0, s19, 12288
	s_nop 0
	global_load_lds_dwordx4 v227, s[0:1]
	v_mfma_f32_16x16x32_bf16 v[64:67], v[176:179], v[208:211], v[64:67]
	v_mfma_f32_16x16x32_bf16 v[68:71], v[180:183], v[208:211], v[68:71]
	v_mfma_f32_16x16x32_bf16 v[72:75], v[184:187], v[208:211], v[72:75]
	v_mfma_f32_16x16x32_bf16 v[76:79], v[188:191], v[208:211], v[76:79]
	ds_read_b128 v[160:163], v232 offset:4096
	s_add_u32 m0, s19, 16384
	s_nop 0
	global_load_lds_dwordx4 v228, s[2:3]
	s_cmp_eq_u32 s18, 0
	s_cbranch_scc0 .Lg6_hi1
	s_setprio 0
.Lg6_hi1:
	v_mfma_f32_16x16x32_bf16 v[80:83], v[176:179], v[212:215], v[80:83]
	v_mfma_f32_16x16x32_bf16 v[84:87], v[180:183], v[212:215], v[84:87]
	v_mfma_f32_16x16x32_bf16 v[88:91], v[184:187], v[212:215], v[88:91]
	v_mfma_f32_16x16x32_bf16 v[92:95], v[188:191], v[212:215], v[92:95]
	ds_read_b128 v[164:167], v232 offset:5120
	s_add_u32 m0, s19, 20480
	s_nop 0
	global_load_lds_dwordx4 v229, s[2:3]
	v_mfma_f32_16x16x32_bf16 v[96:99], v[176:179], v[216:219], v[96:99]
	v_mfma_f32_16x16x32_bf16 v[100:103], v[180:183], v[216:219], v[100:103]
	v_mfma_f32_16x16x32_bf16 v[104:107], v[184:187], v[216:219], v[104:107]
	v_mfma_f32_16x16x32_bf16 v[108:111], v[188:191], v[216:219], v[108:111]
	ds_read_b128 v[168:171], v232 offset:6144
	s_add_u32 s0, s0, 64
	s_addc_u32 s1, s1, 0
	s_add_u32 s2, s2, 64
	s_addc_u32 s3, s3, 0
	s_add_u32 s22, s22, 1
	s_add_u32 s99, s99, 24576
	s_cmp_eq_u32 s99, 73728
	s_cselect_b32 s99, 0, s99
	s_add_u32 s100, s100, 24576
	s_cmp_eq_u32 s100, 73728
	s_cselect_b32 s100, 0, s100
	v_mfma_f32_16x16x32_bf16 v[112:115], v[176:179], v[220:223], v[112:115]
	v_mfma_f32_16x16x32_bf16 v[116:119], v[180:183], v[220:223], v[116:119]
	v_mfma_f32_16x16x32_bf16 v[120:123], v[184:187], v[220:223], v[120:123]
	v_mfma_f32_16x16x32_bf16 v[124:127], v[188:191], v[220:223], v[124:127]
	ds_read_b128 v[172:175], v232 offset:7168
	s_add_u32 s101, s101, 2
	s_cmp_lt_u32 s101, 44
	s_cbranch_scc1 .Lg6_kloop
	s_cmp_eq_u32 s22, 16
	s_cbranch_scc1 .Lg6_sw2

; #define LWRITE(S, buf) do { bf16_t* sA_ = sbase + (buf) * BUF; bf16_t* sB_ = sA_ + 256 * PITCH; \
;     _Pragma("unroll") for (int i_ = 0; i_ < 4; ++i_) *(u32x4*)(sA_ + (sr + i_ * 64) * PITCH + scv * 8) = ra[S][i_]; \
;     _Pragma("unroll") for (int i_ = 0; i_ < 2; ++i_) *(u32x4*)(sB_ + (sr + i_ * 64) * PITCH + scv * 8) = rb[S][i_]; } while (0)
; template <class Epi>
; DI void gemm_tile(char* smem, const bf16_t* __restrict__ A0, int lda0, int ksplit, const bf16_t* __restrict__ A1, int lda1,
;                   const bf16_t* __restrict__ Bt, int K, int row0, int col0, const Epi& epi, int tid) {
;     ...
;   __syncthreads();
;   {
;     const int last = nk - 1;
;     GLOAD(0, 0);
;     __builtin_amdgcn_sched_barrier(0);
;     GLOAD(1, 1);
;     __builtin_amdgcn_sched_barrier(0);
;     LWRITE(0, 0);
;     __builtin_amdgcn_sched_barrier(0);
;     GLOAD(0, (2 < last ? 2 : last));
;     __builtin_amdgcn_sched_barrier(0);
;     __syncthreads();
;     for (int kt = 0; kt < nk; kt += 2) {
;       LWRITE(1, 1);
;       __builtin_amdgcn_sched_barrier(0);
;       GLOAD(1, (kt + 3 < last ? kt + 3 : last));
;       __builtin_amdgcn_sched_barrier(0);
;       COMPUTE(0);
;       __syncthreads();
;       LWRITE(0, 0);
;       __builtin_amdgcn_sched_barrier(0);
;       GLOAD(0, (kt + 4 < last ? kt + 4 : last));
;       __builtin_amdgcn_sched_barrier(0);
;       COMPUTE(1);
;       __syncthreads();
;     }
.Lg6_hi2:
	v_mfma_f32_16x16x32_bf16 v[80:83], v[128:131], v[164:167], v[80:83]
	v_mfma_f32_16x16x32_bf16 v[84:87], v[132:135], v[164:167], v[84:87]
	v_mfma_f32_16x16x32_bf16 v[88:91], v[136:139], v[164:167], v[88:91]
	v_mfma_f32_16x16x32_bf16 v[92:95], v[140:143], v[164:167], v[92:95]
	ds_read_b128 v[212:215], v232 offset:5120
	s_add_u32 m0, s19, 20480
	s_nop 0
	global_load_lds_dwordx4 v229, s[2:3]
	v_mfma_f32_16x16x32_bf16 v[96:99], v[128:131], v[168:171], v[96:99]
	v_mfma_f32_16x16x32_bf16 v[100:103], v[132:135], v[168:171], v[100:103]
	v_mfma_f32_16x16x32_bf16 v[104:107], v[136:139], v[168:171], v[104:107]
	v_mfma_f32_16x16x32_bf16 v[108:111], v[140:143], v[168:171], v[108:111]
	ds_read_b128 v[216:219], v232 offset:6144
	s_add_u32 s0, s0, 64
	s_addc_u32 s1, s1, 0
	s_add_u32 s2, s2, 64
	s_addc_u32 s3, s3, 0
	s_add_u32 s22, s22, 1
	s_add_u32 s99, s99, 24576
	s_cmp_eq_u32 s99, 73728
	s_cselect_b32 s99, 0, s99
	s_add_u32 s100, s100, 24576
	s_cmp_eq_u32 s100, 73728
	s_cselect_b32 s100, 0, s100
	v_mfma_f32_16x16x32_bf16 v[112:115], v[128:131], v[172:175], v[112:115]
	v_mfma_f32_16x16x32_bf16 v[116:119], v[132:135], v[172:175], v[116:119]
	v_mfma_f32_16x16x32_bf16 v[120:123], v[136:139], v[172:175], v[120:123]
	v_mfma_f32_16x16x32_bf16 v[124:127], v[140:143], v[172:175], v[124:127]
	ds_read_b128 v[220:223], v232 offset:7168
	s_waitcnt vmcnt(6)
	s_waitcnt lgkmcnt(0)
	s_barrier
	v_add_u32_e32 v232, s100, v230
	v_add_u32_e32 v233, s100, v231
	s_setprio 1
	v_mfma_f32_16x16x32_bf16 v[0:3], v[176:179], v[192:195], v[0:3]
	v_mfma_f32_16x16x32_bf16 v[4:7], v[180:183], v[192:195], v[4:7]
	v_mfma_f32_16x16x32_bf16 v[8:11], v[184:187], v[192:195], v[8:11]
	v_mfma_f32_16x16x32_bf16 v[12:15], v[188:191], v[192:195], v[12:15]
	ds_read_b128 v[128:131], v233 offset:0
	ds_read_b128 v[132:135], v233 offset:1024
	v_mfma_f32_16x16x32_bf16 v[16:19], v[176:179], v[196:199], v[16:19]
	v_mfma_f32_16x16x32_bf16 v[20:23], v[180:183], v[196:199], v[20:23]
	v_mfma_f32_16x16x32_bf16 v[24:27], v[184:187], v[196:199], v[24:27]
	v_mfma_f32_16x16x32_bf16 v[28:31], v[188:191], v[196:199], v[28:31]
	ds_read_b128 v[136:139], v233 offset:2048
	ds_read_b128 v[140:143], v233 offset:3072
	v_mfma_f32_16x16x32_bf16 v[32:35], v[176:179], v[200:203], v[32:35]
	v_mfma_f32_16x16x32_bf16 v[36:39], v[180:183], v[200:203], v[36:39]
	v_mfma_f32_16x16x32_bf16 v[40:43], v[184:187], v[200:203], v[40:43]
	v_mfma_f32_16x16x32_bf16 v[44:47], v[188:191], v[200:203], v[44:47]
	ds_read_b128 v[144:147], v232 offset:0
	ds_read_b128 v[148:151], v232 offset:1024
	v_mfma_f32_16x16x32_bf16 v[48:51], v[176:179], v[204:207], v[48:51]
	v_mfma_f32_16x16x32_bf16 v[52:55], v[180:183], v[204:207], v[52:55]
	v_mfma_f32_16x16x32_bf16 v[56:59], v[184:187], v[204:207], v[56:59]
	v_mfma_f32_16x16x32_bf16 v[60:63], v[188:191], v[204:207], v[60:63]
	ds_read_b128 v[152:155], v232 offset:2048
	ds_read_b128 v[156:159], v232 offset:3072
	v_mfma_f32_16x16x32_bf16 v[64:67], v[176:179], v[208:211], v[64:67]
	v_mfma_f32_16x16x32_bf16 v[68:71], v[180:183], v[208:211], v[68:71]
	v_mfma_f32_16x16x32_bf16 v[72:75], v[184:187], v[208:211], v[72:75]
	v_mfma_f32_16x16x32_bf16 v[76:79], v[188:191], v[208:211], v[76:79]
	ds_read_b128 v[160:163], v232 offset:4096
	s_cmp_eq_u32 s18, 0
	s_cbranch_scc0 .Lg6_hi3
	s_setprio 0
; #define LWRITE(S, buf) do { bf16_t* sA_ = sbase + (buf) * BUF; bf16_t* sB_ = sA_ + 256 * PITCH; \
;     _Pragma("unroll") for (int i_ = 0; i_ < 4; ++i_) *(u32x4*)(sA_ + (sr + i_ * 64) * PITCH + scv * 8) = ra[S][i_]; \
;     _Pragma("unroll") for (int i_ = 0; i_ < 2; ++i_) *(u32x4*)(sB_ + (sr + i_ * 64) * PITCH + scv * 8) = rb[S][i_]; } while (0)
; template <class Epi>
; DI void gemm_tile(char* smem, const bf16_t* __restrict__ A0, int lda0, int ksplit, const bf16_t* __restrict__ A1, int lda1,
;                   const bf16_t* __restrict__ Bt, int K, int row0, int col0, const Epi& epi, int tid) {
;     ...
;   __syncthreads();
;   {
;     const int last = nk - 1;
;     GLOAD(0, 0);
;     __builtin_amdgcn_sched_barrier(0);
;     GLOAD(1, 1);
;     __builtin_amdgcn_sched_barrier(0);
;     LWRITE(0, 0);
;     __builtin_amdgcn_sched_barrier(0);
;     GLOAD(0, (2 < last ? 2 : last));
;     __builtin_amdgcn_sched_barrier(0);
;     __syncthreads();
;     for (int kt = 0; kt < nk; kt += 2) {
;       LWRITE(1, 1);
;       __builtin_amdgcn_sched_barrier(0);
;       GLOAD(1, (kt + 3 < last ? kt + 3 : last));
;       __builtin_amdgcn_sched_barrier(0);
;       COMPUTE(0);
;       __syncthreads();
;       LWRITE(0, 0);
;       __builtin_amdgcn_sched_barrier(0);
;       GLOAD(0, (kt + 4 < last ? kt + 4 : last));
;       __builtin_amdgcn_sched_barrier(0);
;       COMPUTE(1);
;       __syncthreads();
;     }
.Lg6_hi3:
	v_mfma_f32_16x16x32_bf16 v[80:83], v[176:179], v[212:215], v[80:83]
	v_mfma_f32_16x16x32_bf16 v[84:87], v[180:183], v[212:215], v[84:87]
	v_mfma_f32_16x16x32_bf16 v[88:91], v[184:187], v[212:215], v[88:91]
	v_mfma_f32_16x16x32_bf16 v[92:95], v[188:191], v[212:215], v[92:95]
	ds_read_b128 v[164:167], v232 offset:5120
	v_mfma_f32_16x16x32_bf16 v[96:99], v[176:179], v[216:219], v[96:99]
	v_mfma_f32_16x16x32_bf16 v[100:103], v[180:183], v[216:219], v[100:103]
	v_mfma_f32_16x16x32_bf16 v[104:107], v[184:187], v[216:219], v[104:107]
	v_mfma_f32_16x16x32_bf16 v[108:111], v[188:191], v[216:219], v[108:111]
	ds_read_b128 v[168:171], v232 offset:6144
	s_add_u32 s100, s100, 24576
	s_cmp_eq_u32 s100, 73728
	s_cselect_b32 s100, 0, s100
	v_mfma_f32_16x16x32_bf16 v[112:115], v[176:179], v[220:223], v[112:115]
	v_mfma_f32_16x16x32_bf16 v[116:119], v[180:183], v[220:223], v[116:119]
	v_mfma_f32_16x16x32_bf16 v[120:123], v[184:187], v[220:223], v[120:123]
	v_mfma_f32_16x16x32_bf16 v[124:127], v[188:191], v[220:223], v[124:127]
	ds_read_b128 v[172:175], v232 offset:7168
	s_waitcnt vmcnt(0)
	s_waitcnt lgkmcnt(0)
	s_barrier
	v_add_u32_e32 v232, s100, v230
	v_add_u32_e32 v233, s100, v231
	s_setprio 1
	v_mfma_f32_16x16x32_bf16 v[0:3], v[128:131], v[144:147], v[0:3]
	v_mfma_f32_16x16x32_bf16 v[4:7], v[132:135], v[144:147], v[4:7]
	v_mfma_f32_16x16x32_bf16 v[8:11], v[136:139], v[144:147], v[8:11]
	v_mfma_f32_16x16x32_bf16 v[12:15], v[140:143], v[144:147], v[12:15]
	ds_read_b128 v[176:179], v233 offset:0
	ds_read_b128 v[180:183], v233 offset:1024
	v_mfma_f32_16x16x32_bf16 v[16:19], v[128:131], v[148:151], v[16:19]
	v_mfma_f32_16x16x32_bf16 v[20:23], v[132:135], v[148:151], v[20:23]
	v_mfma_f32_16x16x32_bf16 v[24:27], v[136:139], v[148:151], v[24:27]
	v_mfma_f32_16x16x32_bf16 v[28:31], v[140:143], v[148:151], v[28:31]
	ds_read_b128 v[184:187], v233 offset:2048
	ds_read_b128 v[188:191], v233 offset:3072
	v_mfma_f32_16x16x32_bf16 v[32:35], v[128:131], v[152:155], v[32:35]
	v_mfma_f32_16x16x32_bf16 v[36:39], v[132:135], v[152:155], v[36:39]
	v_mfma_f32_16x16x32_bf16 v[40:43], v[136:139], v[152:155], v[40:43]
	v_mfma_f32_16x16x32_bf16 v[44:47], v[140:143], v[152:155], v[44:47]
	ds_read_b128 v[192:195], v232 offset:0
	ds_read_b128 v[196:199], v232 offset:1024
	v_mfma_f32_16x16x32_bf16 v[48:51], v[128:131], v[156:159], v[48:51]
	v_mfma_f32_16x16x32_bf16 v[52:55], v[132:135], v[156:159], v[52:55]
	v_mfma_f32_16x16x32_bf16 v[56:59], v[136:139], v[156:159], v[56:59]
	v_mfma_f32_16x16x32_bf16 v[60:63], v[140:143], v[156:159], v[60:63]
	ds_read_b128 v[200:203], v232 offset:2048
	ds_read_b128 v[204:207], v232 offset:3072
	v_mfma_f32_16x16x32_bf16 v[64:67], v[128:131], v[160:163], v[64:67]
	v_mfma_f32_16x16x32_bf16 v[68:71], v[132:135], v[160:163], v[68:71]
	v_mfma_f32_16x16x32_bf16 v[72:75], v[136:139], v[160:163], v[72:75]
	v_mfma_f32_16x16x32_bf16 v[76:79], v[140:143], v[160:163], v[76:79]
	ds_read_b128 v[208:211], v232 offset:4096
	s_cmp_eq_u32 s18, 0
	s_cbranch_scc0 .Lg6_hi4
	s_setprio 0
.Lg6_hi4:
	v_mfma_f32_16x16x32_bf16 v[80:83], v[128:131], v[164:167], v[80:83]
	v_mfma_f32_16x16x32_bf16 v[84:87], v[132:135], v[164:167], v[84:87]
	v_mfma_f32_16x16x32_bf16 v[88:91], v[136:139], v[164:167], v[88:91]
	v_mfma_f32_16x16x32_bf16 v[92:95], v[140:143], v[164:167], v[92:95]
	ds_read_b128 v[212:215], v232 offset:5120
	v_mfma_f32_16x16x32_bf16 v[96:99], v[128:131], v[168:171], v[96:99]
	v_mfma_f32_16x16x32_bf16 v[100:103], v[132:135], v[168:171], v[100:103]
	v_mfma_f32_16x16x32_bf16 v[104:107], v[136:139], v[168:171], v[104:107]
	v_mfma_f32_16x16x32_bf16 v[108:111], v[140:143], v[168:171], v[108:111]
	ds_read_b128 v[216:219], v232 offset:6144
	s_add_u32 s100, s100, 24576
	s_cmp_eq_u32 s100, 73728
	s_cselect_b32 s100, 0, s100
	v_mfma_f32_16x16x32_bf16 v[112:115], v[128:131], v[172:175], v[112:115]
	v_mfma_f32_16x16x32_bf16 v[116:119], v[132:135], v[172:175], v[116:119]
	v_mfma_f32_16x16x32_bf16 v[120:123], v[136:139], v[172:175], v[120:123]
	v_mfma_f32_16x16x32_bf16 v[124:127], v[140:143], v[172:175], v[124:127]
	ds_read_b128 v[220:223], v232 offset:7168
	s_waitcnt lgkmcnt(0)
	s_barrier
	s_setprio 1
	v_mfma_f32_16x16x32_bf16 v[0:3], v[176:179], v[192:195], v[0:3]
	v_mfma_f32_16x16x32_bf16 v[4:7], v[180:183], v[192:195], v[4:7]
	v_mfma_f32_16x16x32_bf16 v[8:11], v[184:187], v[192:195], v[8:11]
	v_mfma_f32_16x16x32_bf16 v[12:15], v[188:191], v[192:195], v[12:15]
	v_mfma_f32_16x16x32_bf16 v[16:19], v[176:179], v[196:199], v[16:19]
	v_mfma_f32_16x16x32_bf16 v[20:23], v[180:183], v[196:199], v[20:23]
	v_mfma_f32_16x16x32_bf16 v[24:27], v[184:187], v[196:199], v[24:27]
	v_mfma_f32_16x16x32_bf16 v[28:31], v[188:191], v[196:199], v[28:31]
	v_mfma_f32_16x16x32_bf16 v[32:35], v[176:179], v[200:203], v[32:35]
	v_mfma_f32_16x16x32_bf16 v[36:39], v[180:183], v[200:203], v[36:39]
	v_mfma_f32_16x16x32_bf16 v[40:43], v[184:187], v[200:203], v[40:43]
	v_mfma_f32_16x16x32_bf16 v[44:47], v[188:191], v[200:203], v[44:47]
	v_mfma_f32_16x16x32_bf16 v[48:51], v[176:179], v[204:207], v[48:51]
	v_mfma_f32_16x16x32_bf16 v[52:55], v[180:183], v[204:207], v[52:55]
	v_mfma_f32_16x16x32_bf16 v[56:59], v[184:187], v[204:207], v[56:59]
	v_mfma_f32_16x16x32_bf16 v[60:63], v[188:191], v[204:207], v[60:63]
	v_mfma_f32_16x16x32_bf16 v[64:67], v[176:179], v[208:211], v[64:67]
	v_mfma_f32_16x16x32_bf16 v[68:71], v[180:183], v[208:211], v[68:71]
	v_mfma_f32_16x16x32_bf16 v[72:75], v[184:187], v[208:211], v[72:75]
	v_mfma_f32_16x16x32_bf16 v[76:79], v[188:191], v[208:211], v[76:79]
	s_cmp_eq_u32 s18, 0
	s_cbranch_scc0 .Lg6_hi5
	s_setprio 0

; #define LWRITE(S, buf) do { bf16_t* sA_ = sbase + (buf) * BUF; bf16_t* sB_ = sA_ + 256 * PITCH; \
;     _Pragma("unroll") for (int i_ = 0; i_ < 4; ++i_) *(u32x4*)(sA_ + (sr + i_ * 64) * PITCH + scv * 8) = ra[S][i_]; \
;     _Pragma("unroll") for (int i_ = 0; i_ < 2; ++i_) *(u32x4*)(sB_ + (sr + i_ * 64) * PITCH + scv * 8) = rb[S][i_]; } while (0)
; template <class Epi>
; DI void gemm_tile(char* smem, const bf16_t* __restrict__ A0, int lda0, int ksplit, const bf16_t* __restrict__ A1, int lda1,
;                   const bf16_t* __restrict__ Bt, int K, int row0, int col0, const Epi& epi, int tid) {
;     ...
;   __syncthreads();
;   {
;     const int last = nk - 1;
;     GLOAD(0, 0);
;     __builtin_amdgcn_sched_barrier(0);
;     GLOAD(1, 1);
;     __builtin_amdgcn_sched_barrier(0);
;     LWRITE(0, 0);
;     __builtin_amdgcn_sched_barrier(0);
;     GLOAD(0, (2 < last ? 2 : last));
;     __builtin_amdgcn_sched_barrier(0);
;     __syncthreads();
;     for (int kt = 0; kt < nk; kt += 2) {
;       LWRITE(1, 1);
;       __builtin_amdgcn_sched_barrier(0);
;       GLOAD(1, (kt + 3 < last ? kt + 3 : last));
;       __builtin_amdgcn_sched_barrier(0);
;       COMPUTE(0);
;       __syncthreads();
;       LWRITE(0, 0);
;       __builtin_amdgcn_sched_barrier(0);
;       GLOAD(0, (kt + 4 < last ? kt + 4 : last));
;       __builtin_amdgcn_sched_barrier(0);
;       COMPUTE(1);
;       __syncthreads();
;     }
.Lg8_kloop:
	s_waitcnt vmcnt(6)
	s_waitcnt lgkmcnt(0)
	s_barrier
	v_add_u32_e32 v232, s98, v230
	v_add_u32_e32 v233, s98, v231
	s_add_u32 s11, s19, s101
	s_setprio 1
	v_mfma_f32_16x16x32_bf16 v[0:3], v[128:131], v[144:147], v[0:3]
	v_mfma_f32_16x16x32_bf16 v[4:7], v[132:135], v[144:147], v[4:7]
	v_mfma_f32_16x16x32_bf16 v[8:11], v[136:139], v[144:147], v[8:11]
	v_mfma_f32_16x16x32_bf16 v[12:15], v[140:143], v[144:147], v[12:15]
	ds_read_b128 v[176:179], v233 offset:0
	ds_read_b128 v[180:183], v233 offset:1024
	s_add_u32 m0, s11, 0
	s_nop 0
	global_load_lds_dwordx4 v224, s[0:1]
	v_mfma_f32_16x16x32_bf16 v[16:19], v[128:131], v[148:151], v[16:19]
	v_mfma_f32_16x16x32_bf16 v[20:23], v[132:135], v[148:151], v[20:23]
	v_mfma_f32_16x16x32_bf16 v[24:27], v[136:139], v[148:151], v[24:27]
	v_mfma_f32_16x16x32_bf16 v[28:31], v[140:143], v[148:151], v[28:31]
	ds_read_b128 v[184:187], v233 offset:2048
	ds_read_b128 v[188:191], v233 offset:3072
	s_add_u32 m0, s11, 4096
	s_nop 0
	global_load_lds_dwordx4 v225, s[0:1]
	v_mfma_f32_16x16x32_bf16 v[32:35], v[128:131], v[152:155], v[32:35]
	v_mfma_f32_16x16x32_bf16 v[36:39], v[132:135], v[152:155], v[36:39]
	v_mfma_f32_16x16x32_bf16 v[40:43], v[136:139], v[152:155], v[40:43]
	v_mfma_f32_16x16x32_bf16 v[44:47], v[140:143], v[152:155], v[44:47]
	ds_read_b128 v[192:195], v232 offset:0
	ds_read_b128 v[196:199], v232 offset:1024
	s_add_u32 m0, s11, 8192
	s_nop 0
	global_load_lds_dwordx4 v226, s[0:1]
	v_mfma_f32_16x16x32_bf16 v[48:51], v[128:131], v[156:159], v[48:51]
	v_mfma_f32_16x16x32_bf16 v[52:55], v[132:135], v[156:159], v[52:55]
	v_mfma_f32_16x16x32_bf16 v[56:59], v[136:139], v[156:159], v[56:59]
	v_mfma_f32_16x16x32_bf16 v[60:63], v[140:143], v[156:159], v[60:63]
	ds_read_b128 v[200:203], v232 offset:2048
	ds_read_b128 v[204:207], v232 offset:3072
	s_add_u32 m0, s11, 12288
	s_nop 0
	global_load_lds_dwordx4 v227, s[0:1]
	v_mfma_f32_16x16x32_bf16 v[64:67], v[128:131], v[160:163], v[64:67]
	v_mfma_f32_16x16x32_bf16 v[68:71], v[132:135], v[160:163], v[68:71]
	v_mfma_f32_16x16x32_bf16 v[72:75], v[136:139], v[160:163], v[72:75]
	v_mfma_f32_16x16x32_bf16 v[76:79], v[140:143], v[160:163], v[76:79]
	ds_read_b128 v[208:211], v232 offset:4096
	s_add_u32 m0, s11, 16384
	s_nop 0
	global_load_lds_dwordx4 v228, s[2:3]
	s_cmp_eq_u32 s10, 0
	s_cbranch_scc0 .Lg8_hi0
	s_setprio 0
.Lg8_hi0:
	v_mfma_f32_16x16x32_bf16 v[80:83], v[128:131], v[164:167], v[80:83]
	v_mfma_f32_16x16x32_bf16 v[84:87], v[132:135], v[164:167], v[84:87]
	v_mfma_f32_16x16x32_bf16 v[88:91], v[136:139], v[164:167], v[88:91]
	v_mfma_f32_16x16x32_bf16 v[92:95], v[140:143], v[164:167], v[92:95]
	ds_read_b128 v[212:215], v232 offset:5120
	s_add_u32 m0, s11, 20480
	s_nop 0
	global_load_lds_dwordx4 v229, s[2:3]
	v_mfma_f32_16x16x32_bf16 v[96:99], v[128:131], v[168:171], v[96:99]
	v_mfma_f32_16x16x32_bf16 v[100:103], v[132:135], v[168:171], v[100:103]
	v_mfma_f32_16x16x32_bf16 v[104:107], v[136:139], v[168:171], v[104:107]
	v_mfma_f32_16x16x32_bf16 v[108:111], v[140:143], v[168:171], v[108:111]
	ds_read_b128 v[216:219], v232 offset:6144
	s_add_u32 s0, s0, 64
	s_addc_u32 s1, s1, 0
	s_add_u32 s2, s2, 64
	s_addc_u32 s3, s3, 0
	s_add_u32 s100, s100, 1
	s_add_u32 s19, s19, 24576
	s_cmp_eq_u32 s19, 73728
	s_cselect_b32 s19, 0, s19
	s_add_u32 s98, s98, 24576
	s_cmp_eq_u32 s98, 73728
	s_cselect_b32 s98, 0, s98
	v_mfma_f32_16x16x32_bf16 v[112:115], v[128:131], v[172:175], v[112:115]
	v_mfma_f32_16x16x32_bf16 v[116:119], v[132:135], v[172:175], v[116:119]
	v_mfma_f32_16x16x32_bf16 v[120:123], v[136:139], v[172:175], v[120:123]
	v_mfma_f32_16x16x32_bf16 v[124:127], v[140:143], v[172:175], v[124:127]
	ds_read_b128 v[220:223], v232 offset:7168
	s_waitcnt vmcnt(6)
	s_waitcnt lgkmcnt(0)
	s_barrier
	v_add_u32_e32 v232, s98, v230
	v_add_u32_e32 v233, s98, v231
	s_add_u32 s11, s19, s101
	s_setprio 1
	v_mfma_f32_16x16x32_bf16 v[0:3], v[176:179], v[192:195], v[0:3]
	v_mfma_f32_16x16x32_bf16 v[4:7], v[180:183], v[192:195], v[4:7]
	v_mfma_f32_16x16x32_bf16 v[8:11], v[184:187], v[192:195], v[8:11]
	v_mfma_f32_16x16x32_bf16 v[12:15], v[188:191], v[192:195], v[12:15]
	ds_read_b128 v[128:131], v233 offset:0
	ds_read_b128 v[132:135], v233 offset:1024
	s_add_u32 m0, s11, 0
	s_nop 0
	global_load_lds_dwordx4 v224, s[0:1]
	v_mfma_f32_16x16x32_bf16 v[16:19], v[176:179], v[196:199], v[16:19]
	v_mfma_f32_16x16x32_bf16 v[20:23], v[180:183], v[196:199], v[20:23]
	v_mfma_f32_16x16x32_bf16 v[24:27], v[184:187], v[196:199], v[24:27]
	v_mfma_f32_16x16x32_bf16 v[28:31], v[188:191], v[196:199], v[28:31]
	ds_read_b128 v[136:139], v233 offset:2048
	ds_read_b128 v[140:143], v233 offset:3072
	s_add_u32 m0, s11, 4096
	s_nop 0
	global_load_lds_dwordx4 v225, s[0:1]
	v_mfma_f32_16x16x32_bf16 v[32:35], v[176:179], v[200:203], v[32:35]
	v_mfma_f32_16x16x32_bf16 v[36:39], v[180:183], v[200:203], v[36:39]
	v_mfma_f32_16x16x32_bf16 v[40:43], v[184:187], v[200:203], v[40:43]
	v_mfma_f32_16x16x32_bf16 v[44:47], v[188:191], v[200:203], v[44:47]
	ds_read_b128 v[144:147], v232 offset:0
	ds_read_b128 v[148:151], v232 offset:1024
	s_add_u32 m0, s11, 8192
	s_nop 0
	global_load_lds_dwordx4 v226, s[0:1]
	v_mfma_f32_16x16x32_bf16 v[48:51], v[176:179], v[204:207], v[48:51]
	v_mfma_f32_16x16x32_bf16 v[52:55], v[180:183], v[204:207], v[52:55]
	v_mfma_f32_16x16x32_bf16 v[56:59], v[184:187], v[204:207], v[56:59]
	v_mfma_f32_16x16x32_bf16 v[60:63], v[188:191], v[204:207], v[60:63]
	ds_read_b128 v[152:155], v232 offset:2048
	ds_read_b128 v[156:159], v232 offset:3072
	s_add_u32 m0, s11, 12288
	s_nop 0
	global_load_lds_dwordx4 v227, s[0:1]
	v_mfma_f32_16x16x32_bf16 v[64:67], v[176:179], v[208:211], v[64:67]
	v_mfma_f32_16x16x32_bf16 v[68:71], v[180:183], v[208:211], v[68:71]
	v_mfma_f32_16x16x32_bf16 v[72:75], v[184:187], v[208:211], v[72:75]
	v_mfma_f32_16x16x32_bf16 v[76:79], v[188:191], v[208:211], v[76:79]
	ds_read_b128 v[160:163], v232 offset:4096
	s_add_u32 m0, s11, 16384
	s_nop 0
	global_load_lds_dwordx4 v228, s[2:3]
	s_cmp_eq_u32 s10, 0
	s_cbranch_scc0 .Lg8_hi1
	s_setprio 0
; #define LWRITE(S, buf) do { bf16_t* sA_ = sbase + (buf) * BUF; bf16_t* sB_ = sA_ + 256 * PITCH; \
;     _Pragma("unroll") for (int i_ = 0; i_ < 4; ++i_) *(u32x4*)(sA_ + (sr + i_ * 64) * PITCH + scv * 8) = ra[S][i_]; \
;     _Pragma("unroll") for (int i_ = 0; i_ < 2; ++i_) *(u32x4*)(sB_ + (sr + i_ * 64) * PITCH + scv * 8) = rb[S][i_]; } while (0)
; template <class Epi>
; DI void gemm_tile(char* smem, const bf16_t* __restrict__ A0, int lda0, int ksplit, const bf16_t* __restrict__ A1, int lda1,
;                   const bf16_t* __restrict__ Bt, int K, int row0, int col0, const Epi& epi, int tid) {
;     ...
;   __syncthreads();
;   {
;     const int last = nk - 1;
;     GLOAD(0, 0);
;     __builtin_amdgcn_sched_barrier(0);
;     GLOAD(1, 1);
;     __builtin_amdgcn_sched_barrier(0);
;     LWRITE(0, 0);
;     __builtin_amdgcn_sched_barrier(0);
;     GLOAD(0, (2 < last ? 2 : last));
;     __builtin_amdgcn_sched_barrier(0);
;     __syncthreads();
;     for (int kt = 0; kt < nk; kt += 2) {
;       LWRITE(1, 1);
;       __builtin_amdgcn_sched_barrier(0);
;       GLOAD(1, (kt + 3 < last ? kt + 3 : last));
;       __builtin_amdgcn_sched_barrier(0);
;       COMPUTE(0);
;       __syncthreads();
;       LWRITE(0, 0);
;       __builtin_amdgcn_sched_barrier(0);
;       GLOAD(0, (kt + 4 < last ? kt + 4 : last));
;       __builtin_amdgcn_sched_barrier(0);
;       COMPUTE(1);
;       __syncthreads();
;     }
.Lg8_hi1:
	v_mfma_f32_16x16x32_bf16 v[80:83], v[176:179], v[212:215], v[80:83]
	v_mfma_f32_16x16x32_bf16 v[84:87], v[180:183], v[212:215], v[84:87]
	v_mfma_f32_16x16x32_bf16 v[88:91], v[184:187], v[212:215], v[88:91]
	v_mfma_f32_16x16x32_bf16 v[92:95], v[188:191], v[212:215], v[92:95]
	ds_read_b128 v[164:167], v232 offset:5120
	s_add_u32 m0, s11, 20480
	s_nop 0
	global_load_lds_dwordx4 v229, s[2:3]
	v_mfma_f32_16x16x32_bf16 v[96:99], v[176:179], v[216:219], v[96:99]
	v_mfma_f32_16x16x32_bf16 v[100:103], v[180:183], v[216:219], v[100:103]
	v_mfma_f32_16x16x32_bf16 v[104:107], v[184:187], v[216:219], v[104:107]
	v_mfma_f32_16x16x32_bf16 v[108:111], v[188:191], v[216:219], v[108:111]
	ds_read_b128 v[168:171], v232 offset:6144
	s_add_u32 s0, s0, 64
	s_addc_u32 s1, s1, 0
	s_add_u32 s2, s2, 64
	s_addc_u32 s3, s3, 0
	s_add_u32 s100, s100, 1
	s_add_u32 s19, s19, 24576
	s_cmp_eq_u32 s19, 73728
	s_cselect_b32 s19, 0, s19
	s_add_u32 s98, s98, 24576
	s_cmp_eq_u32 s98, 73728
	s_cselect_b32 s98, 0, s98
	v_mfma_f32_16x16x32_bf16 v[112:115], v[176:179], v[220:223], v[112:115]
	v_mfma_f32_16x16x32_bf16 v[116:119], v[180:183], v[220:223], v[116:119]
	v_mfma_f32_16x16x32_bf16 v[120:123], v[184:187], v[220:223], v[120:123]
	v_mfma_f32_16x16x32_bf16 v[124:127], v[188:191], v[220:223], v[124:127]
	ds_read_b128 v[172:175], v232 offset:7168
	s_add_u32 s99, s99, 2
	s_cmp_lt_u32 s99, 28
	s_cbranch_scc1 .Lg8_kloop
	s_waitcnt vmcnt(6)
	s_waitcnt lgkmcnt(0)
	s_barrier
	v_add_u32_e32 v232, s98, v230
	v_add_u32_e32 v233, s98, v231
	s_add_u32 s11, s19, s101
	s_setprio 1
	v_mfma_f32_16x16x32_bf16 v[0:3], v[128:131], v[144:147], v[0:3]
	v_mfma_f32_16x16x32_bf16 v[4:7], v[132:135], v[144:147], v[4:7]
	v_mfma_f32_16x16x32_bf16 v[8:11], v[136:139], v[144:147], v[8:11]
	v_mfma_f32_16x16x32_bf16 v[12:15], v[140:143], v[144:147], v[12:15]
	ds_read_b128 v[176:179], v233 offset:0
	ds_read_b128 v[180:183], v233 offset:1024
	s_add_u32 m0, s11, 0
	s_nop 0
	global_load_lds_dwordx4 v224, s[0:1]
	v_mfma_f32_16x16x32_bf16 v[16:19], v[128:131], v[148:151], v[16:19]
	v_mfma_f32_16x16x32_bf16 v[20:23], v[132:135], v[148:151], v[20:23]
	v_mfma_f32_16x16x32_bf16 v[24:27], v[136:139], v[148:151], v[24:27]
	v_mfma_f32_16x16x32_bf16 v[28:31], v[140:143], v[148:151], v[28:31]
	ds_read_b128 v[184:187], v233 offset:2048
	ds_read_b128 v[188:191], v233 offset:3072
	s_add_u32 m0, s11, 4096
	s_nop 0
	global_load_lds_dwordx4 v225, s[0:1]
	v_mfma_f32_16x16x32_bf16 v[32:35], v[128:131], v[152:155], v[32:35]
	v_mfma_f32_16x16x32_bf16 v[36:39], v[132:135], v[152:155], v[36:39]
	v_mfma_f32_16x16x32_bf16 v[40:43], v[136:139], v[152:155], v[40:43]
	v_mfma_f32_16x16x32_bf16 v[44:47], v[140:143], v[152:155], v[44:47]
	ds_read_b128 v[192:195], v232 offset:0
	ds_read_b128 v[196:199], v232 offset:1024
	s_add_u32 m0, s11, 8192
	s_nop 0
	global_load_lds_dwordx4 v226, s[0:1]
	v_mfma_f32_16x16x32_bf16 v[48:51], v[128:131], v[156:159], v[48:51]
	v_mfma_f32_16x16x32_bf16 v[52:55], v[132:135], v[156:159], v[52:55]
	v_mfma_f32_16x16x32_bf16 v[56:59], v[136:139], v[156:159], v[56:59]
	v_mfma_f32_16x16x32_bf16 v[60:63], v[140:143], v[156:159], v[60:63]
	ds_read_b128 v[200:203], v232 offset:2048
	ds_read_b128 v[204:207], v232 offset:3072
	s_add_u32 m0, s11, 12288
	s_nop 0
	global_load_lds_dwordx4 v227, s[0:1]
	v_mfma_f32_16x16x32_bf16 v[64:67], v[128:131], v[160:163], v[64:67]
	v_mfma_f32_16x16x32_bf16 v[68:71], v[132:135], v[160:163], v[68:71]
	v_mfma_f32_16x16x32_bf16 v[72:75], v[136:139], v[160:163], v[72:75]
	v_mfma_f32_16x16x32_bf16 v[76:79], v[140:143], v[160:163], v[76:79]
	ds_read_b128 v[208:211], v232 offset:4096
	s_add_u32 m0, s11, 16384
	s_nop 0
	global_load_lds_dwordx4 v228, s[2:3]
	s_cmp_eq_u32 s10, 0
	s_cbranch_scc0 .Lg8_hi2
	s_setprio 0
.Lg8_hi2:
	v_mfma_f32_16x16x32_bf16 v[80:83], v[128:131], v[164:167], v[80:83]
	v_mfma_f32_16x16x32_bf16 v[84:87], v[132:135], v[164:167], v[84:87]
	v_mfma_f32_16x16x32_bf16 v[88:91], v[136:139], v[164:167], v[88:91]
	v_mfma_f32_16x16x32_bf16 v[92:95], v[140:143], v[164:167], v[92:95]
	ds_read_b128 v[212:215], v232 offset:5120
	s_add_u32 m0, s11, 20480
	s_nop 0
	global_load_lds_dwordx4 v229, s[2:3]
	v_mfma_f32_16x16x32_bf16 v[96:99], v[128:131], v[168:171], v[96:99]
	v_mfma_f32_16x16x32_bf16 v[100:103], v[132:135], v[168:171], v[100:103]
	v_mfma_f32_16x16x32_bf16 v[104:107], v[136:139], v[168:171], v[104:107]
	v_mfma_f32_16x16x32_bf16 v[108:111], v[140:143], v[168:171], v[108:111]
	ds_read_b128 v[216:219], v232 offset:6144
	s_add_u32 s0, s0, 64
	s_addc_u32 s1, s1, 0
	s_add_u32 s2, s2, 64
	s_addc_u32 s3, s3, 0
	s_add_u32 s100, s100, 1
	s_add_u32 s19, s19, 24576
	s_cmp_eq_u32 s19, 73728
	s_cselect_b32 s19, 0, s19
	s_add_u32 s98, s98, 24576
	s_cmp_eq_u32 s98, 73728
	s_cselect_b32 s98, 0, s98
	v_mfma_f32_16x16x32_bf16 v[112:115], v[128:131], v[172:175], v[112:115]
	v_mfma_f32_16x16x32_bf16 v[116:119], v[132:135], v[172:175], v[116:119]
	v_mfma_f32_16x16x32_bf16 v[120:123], v[136:139], v[172:175], v[120:123]
	v_mfma_f32_16x16x32_bf16 v[124:127], v[140:143], v[172:175], v[124:127]
	ds_read_b128 v[220:223], v232 offset:7168
	s_waitcnt vmcnt(6)
	s_waitcnt lgkmcnt(0)
	s_barrier
	v_add_u32_e32 v232, s98, v230
	v_add_u32_e32 v233, s98, v231
	s_setprio 1
	v_mfma_f32_16x16x32_bf16 v[0:3], v[176:179], v[192:195], v[0:3]
	v_mfma_f32_16x16x32_bf16 v[4:7], v[180:183], v[192:195], v[4:7]
	v_mfma_f32_16x16x32_bf16 v[8:11], v[184:187], v[192:195], v[8:11]
	v_mfma_f32_16x16x32_bf16 v[12:15], v[188:191], v[192:195], v[12:15]
	ds_read_b128 v[128:131], v233 offset:0
	ds_read_b128 v[132:135], v233 offset:1024
	v_mfma_f32_16x16x32_bf16 v[16:19], v[176:179], v[196:199], v[16:19]
	v_mfma_f32_16x16x32_bf16 v[20:23], v[180:183], v[196:199], v[20:23]
	v_mfma_f32_16x16x32_bf16 v[24:27], v[184:187], v[196:199], v[24:27]
	v_mfma_f32_16x16x32_bf16 v[28:31], v[188:191], v[196:199], v[28:31]
	ds_read_b128 v[136:139], v233 offset:2048
	ds_read_b128 v[140:143], v233 offset:3072
	v_mfma_f32_16x16x32_bf16 v[32:35], v[176:179], v[200:203], v[32:35]
	v_mfma_f32_16x16x32_bf16 v[36:39], v[180:183], v[200:203], v[36:39]
	v_mfma_f32_16x16x32_bf16 v[40:43], v[184:187], v[200:203], v[40:43]
	v_mfma_f32_16x16x32_bf16 v[44:47], v[188:191], v[200:203], v[44:47]
	ds_read_b128 v[144:147], v232 offset:0
	ds_read_b128 v[148:151], v232 offset:1024
	v_mfma_f32_16x16x32_bf16 v[48:51], v[176:179], v[204:207], v[48:51]
	v_mfma_f32_16x16x32_bf16 v[52:55], v[180:183], v[204:207], v[52:55]
	v_mfma_f32_16x16x32_bf16 v[56:59], v[184:187], v[204:207], v[56:59]
	v_mfma_f32_16x16x32_bf16 v[60:63], v[188:191], v[204:207], v[60:63]
	ds_read_b128 v[152:155], v232 offset:2048
	ds_read_b128 v[156:159], v232 offset:3072
	v_mfma_f32_16x16x32_bf16 v[64:67], v[176:179], v[208:211], v[64:67]
	v_mfma_f32_16x16x32_bf16 v[68:71], v[180:183], v[208:211], v[68:71]
	v_mfma_f32_16x16x32_bf16 v[72:75], v[184:187], v[208:211], v[72:75]
	v_mfma_f32_16x16x32_bf16 v[76:79], v[188:191], v[208:211], v[76:79]
	ds_read_b128 v[160:163], v232 offset:4096
	s_cmp_eq_u32 s10, 0
	s_cbranch_scc0 .Lg8_hi3
	s_setprio 0
; #define LWRITE(S, buf) do { bf16_t* sA_ = sbase + (buf) * BUF; bf16_t* sB_ = sA_ + 256 * PITCH; \
;     _Pragma("unroll") for (int i_ = 0; i_ < 4; ++i_) *(u32x4*)(sA_ + (sr + i_ * 64) * PITCH + scv * 8) = ra[S][i_]; \
;     _Pragma("unroll") for (int i_ = 0; i_ < 2; ++i_) *(u32x4*)(sB_ + (sr + i_ * 64) * PITCH + scv * 8) = rb[S][i_]; } while (0)
; template <class Epi>
; DI void gemm_tile(char* smem, const bf16_t* __restrict__ A0, int lda0, int ksplit, const bf16_t* __restrict__ A1, int lda1,
;                   const bf16_t* __restrict__ Bt, int K, int row0, int col0, const Epi& epi, int tid) {
;     ...
;   __syncthreads();
;   {
;     const int last = nk - 1;
;     GLOAD(0, 0);
;     __builtin_amdgcn_sched_barrier(0);
;     GLOAD(1, 1);
;     __builtin_amdgcn_sched_barrier(0);
;     LWRITE(0, 0);
;     __builtin_amdgcn_sched_barrier(0);
;     GLOAD(0, (2 < last ? 2 : last));
;     __builtin_amdgcn_sched_barrier(0);
;     __syncthreads();
;     for (int kt = 0; kt < nk; kt += 2) {
;       LWRITE(1, 1);
;       __builtin_amdgcn_sched_barrier(0);
;       GLOAD(1, (kt + 3 < last ? kt + 3 : last));
;       __builtin_amdgcn_sched_barrier(0);
;       COMPUTE(0);
;       __syncthreads();
;       LWRITE(0, 0);
;       __builtin_amdgcn_sched_barrier(0);
;       GLOAD(0, (kt + 4 < last ? kt + 4 : last));
;       __builtin_amdgcn_sched_barrier(0);
;       COMPUTE(1);
;       __syncthreads();
;     }
.Lg8_hi3:
	v_mfma_f32_16x16x32_bf16 v[80:83], v[176:179], v[212:215], v[80:83]
	v_mfma_f32_16x16x32_bf16 v[84:87], v[180:183], v[212:215], v[84:87]
	v_mfma_f32_16x16x32_bf16 v[88:91], v[184:187], v[212:215], v[88:91]
	v_mfma_f32_16x16x32_bf16 v[92:95], v[188:191], v[212:215], v[92:95]
	ds_read_b128 v[164:167], v232 offset:5120
	v_mfma_f32_16x16x32_bf16 v[96:99], v[176:179], v[216:219], v[96:99]
	v_mfma_f32_16x16x32_bf16 v[100:103], v[180:183], v[216:219], v[100:103]
	v_mfma_f32_16x16x32_bf16 v[104:107], v[184:187], v[216:219], v[104:107]
	v_mfma_f32_16x16x32_bf16 v[108:111], v[188:191], v[216:219], v[108:111]
	ds_read_b128 v[168:171], v232 offset:6144
	s_add_u32 s98, s98, 24576
	s_cmp_eq_u32 s98, 73728
	s_cselect_b32 s98, 0, s98
	v_mfma_f32_16x16x32_bf16 v[112:115], v[176:179], v[220:223], v[112:115]
	v_mfma_f32_16x16x32_bf16 v[116:119], v[180:183], v[220:223], v[116:119]
	v_mfma_f32_16x16x32_bf16 v[120:123], v[184:187], v[220:223], v[120:123]
	v_mfma_f32_16x16x32_bf16 v[124:127], v[188:191], v[220:223], v[124:127]
	ds_read_b128 v[172:175], v232 offset:7168
	s_waitcnt vmcnt(0)
	s_waitcnt lgkmcnt(0)
	s_barrier
	v_add_u32_e32 v232, s98, v230
	v_add_u32_e32 v233, s98, v231
	s_setprio 1
	v_mfma_f32_16x16x32_bf16 v[0:3], v[128:131], v[144:147], v[0:3]
	v_mfma_f32_16x16x32_bf16 v[4:7], v[132:135], v[144:147], v[4:7]
	v_mfma_f32_16x16x32_bf16 v[8:11], v[136:139], v[144:147], v[8:11]
	v_mfma_f32_16x16x32_bf16 v[12:15], v[140:143], v[144:147], v[12:15]
	ds_read_b128 v[176:179], v233 offset:0
	ds_read_b128 v[180:183], v233 offset:1024
	v_mfma_f32_16x16x32_bf16 v[16:19], v[128:131], v[148:151], v[16:19]
	v_mfma_f32_16x16x32_bf16 v[20:23], v[132:135], v[148:151], v[20:23]
	v_mfma_f32_16x16x32_bf16 v[24:27], v[136:139], v[148:151], v[24:27]
	v_mfma_f32_16x16x32_bf16 v[28:31], v[140:143], v[148:151], v[28:31]
	ds_read_b128 v[184:187], v233 offset:2048
	ds_read_b128 v[188:191], v233 offset:3072
	v_mfma_f32_16x16x32_bf16 v[32:35], v[128:131], v[152:155], v[32:35]
	v_mfma_f32_16x16x32_bf16 v[36:39], v[132:135], v[152:155], v[36:39]
	v_mfma_f32_16x16x32_bf16 v[40:43], v[136:139], v[152:155], v[40:43]
	v_mfma_f32_16x16x32_bf16 v[44:47], v[140:143], v[152:155], v[44:47]
	ds_read_b128 v[192:195], v232 offset:0
	ds_read_b128 v[196:199], v232 offset:1024
	v_mfma_f32_16x16x32_bf16 v[48:51], v[128:131], v[156:159], v[48:51]
	v_mfma_f32_16x16x32_bf16 v[52:55], v[132:135], v[156:159], v[52:55]
	v_mfma_f32_16x16x32_bf16 v[56:59], v[136:139], v[156:159], v[56:59]
	v_mfma_f32_16x16x32_bf16 v[60:63], v[140:143], v[156:159], v[60:63]
	ds_read_b128 v[200:203], v232 offset:2048
	ds_read_b128 v[204:207], v232 offset:3072
	v_mfma_f32_16x16x32_bf16 v[64:67], v[128:131], v[160:163], v[64:67]
	v_mfma_f32_16x16x32_bf16 v[68:71], v[132:135], v[160:163], v[68:71]
	v_mfma_f32_16x16x32_bf16 v[72:75], v[136:139], v[160:163], v[72:75]
	v_mfma_f32_16x16x32_bf16 v[76:79], v[140:143], v[160:163], v[76:79]
	ds_read_b128 v[208:211], v232 offset:4096
	s_cmp_eq_u32 s10, 0
	s_cbranch_scc0 .Lg8_hi4
	s_setprio 0
.Lg8_hi4:
	v_mfma_f32_16x16x32_bf16 v[80:83], v[128:131], v[164:167], v[80:83]
	v_mfma_f32_16x16x32_bf16 v[84:87], v[132:135], v[164:167], v[84:87]
	v_mfma_f32_16x16x32_bf16 v[88:91], v[136:139], v[164:167], v[88:91]
	v_mfma_f32_16x16x32_bf16 v[92:95], v[140:143], v[164:167], v[92:95]
	ds_read_b128 v[212:215], v232 offset:5120
	v_mfma_f32_16x16x32_bf16 v[96:99], v[128:131], v[168:171], v[96:99]
	v_mfma_f32_16x16x32_bf16 v[100:103], v[132:135], v[168:171], v[100:103]
	v_mfma_f32_16x16x32_bf16 v[104:107], v[136:139], v[168:171], v[104:107]
	v_mfma_f32_16x16x32_bf16 v[108:111], v[140:143], v[168:171], v[108:111]
	ds_read_b128 v[216:219], v232 offset:6144
	s_add_u32 s98, s98, 24576
	s_cmp_eq_u32 s98, 73728
	s_cselect_b32 s98, 0, s98
	v_mfma_f32_16x16x32_bf16 v[112:115], v[128:131], v[172:175], v[112:115]
	v_mfma_f32_16x16x32_bf16 v[116:119], v[132:135], v[172:175], v[116:119]
	v_mfma_f32_16x16x32_bf16 v[120:123], v[136:139], v[172:175], v[120:123]
	v_mfma_f32_16x16x32_bf16 v[124:127], v[140:143], v[172:175], v[124:127]
	ds_read_b128 v[220:223], v232 offset:7168
	s_waitcnt lgkmcnt(0)
	s_barrier
	s_setprio 1
	v_mfma_f32_16x16x32_bf16 v[0:3], v[176:179], v[192:195], v[0:3]
	v_mfma_f32_16x16x32_bf16 v[4:7], v[180:183], v[192:195], v[4:7]
	v_mfma_f32_16x16x32_bf16 v[8:11], v[184:187], v[192:195], v[8:11]
	v_mfma_f32_16x16x32_bf16 v[12:15], v[188:191], v[192:195], v[12:15]
	v_mfma_f32_16x16x32_bf16 v[16:19], v[176:179], v[196:199], v[16:19]
	v_mfma_f32_16x16x32_bf16 v[20:23], v[180:183], v[196:199], v[20:23]
	v_mfma_f32_16x16x32_bf16 v[24:27], v[184:187], v[196:199], v[24:27]
	v_mfma_f32_16x16x32_bf16 v[28:31], v[188:191], v[196:199], v[28:31]
	v_mfma_f32_16x16x32_bf16 v[32:35], v[176:179], v[200:203], v[32:35]
	v_mfma_f32_16x16x32_bf16 v[36:39], v[180:183], v[200:203], v[36:39]
	v_mfma_f32_16x16x32_bf16 v[40:43], v[184:187], v[200:203], v[40:43]
	v_mfma_f32_16x16x32_bf16 v[44:47], v[188:191], v[200:203], v[44:47]
	v_mfma_f32_16x16x32_bf16 v[48:51], v[176:179], v[204:207], v[48:51]
	v_mfma_f32_16x16x32_bf16 v[52:55], v[180:183], v[204:207], v[52:55]
	v_mfma_f32_16x16x32_bf16 v[56:59], v[184:187], v[204:207], v[56:59]
	v_mfma_f32_16x16x32_bf16 v[60:63], v[188:191], v[204:207], v[60:63]
	v_mfma_f32_16x16x32_bf16 v[64:67], v[176:179], v[208:211], v[64:67]
	v_mfma_f32_16x16x32_bf16 v[68:71], v[180:183], v[208:211], v[68:71]
	v_mfma_f32_16x16x32_bf16 v[72:75], v[184:187], v[208:211], v[72:75]
	v_mfma_f32_16x16x32_bf16 v[76:79], v[188:191], v[208:211], v[76:79]
	s_cmp_eq_u32 s10, 0
	s_cbranch_scc0 .Lg8_hi5
	s_setprio 0

; #define LWRITE(S, buf) do { bf16_t* sA_ = sbase + (buf) * BUF; bf16_t* sB_ = sA_ + 256 * PITCH; \
;     _Pragma("unroll") for (int i_ = 0; i_ < 4; ++i_) *(u32x4*)(sA_ + (sr + i_ * 64) * PITCH + scv * 8) = ra[S][i_]; \
;     _Pragma("unroll") for (int i_ = 0; i_ < 2; ++i_) *(u32x4*)(sB_ + (sr + i_ * 64) * PITCH + scv * 8) = rb[S][i_]; } while (0)
; template <class Epi>
; DI void gemm_tile(char* smem, const bf16_t* __restrict__ A0, int lda0, int ksplit, const bf16_t* __restrict__ A1, int lda1,
;                   const bf16_t* __restrict__ Bt, int K, int row0, int col0, const Epi& epi, int tid) {
;     ...
;   __syncthreads();
;   {
;     const int last = nk - 1;
;     GLOAD(0, 0);
;     __builtin_amdgcn_sched_barrier(0);
;     GLOAD(1, 1);
;     __builtin_amdgcn_sched_barrier(0);
;     LWRITE(0, 0);
;     __builtin_amdgcn_sched_barrier(0);
;     GLOAD(0, (2 < last ? 2 : last));
;     __builtin_amdgcn_sched_barrier(0);
;     __syncthreads();
;     for (int kt = 0; kt < nk; kt += 2) {
;       LWRITE(1, 1);
;       __builtin_amdgcn_sched_barrier(0);
;       GLOAD(1, (kt + 3 < last ? kt + 3 : last));
;       __builtin_amdgcn_sched_barrier(0);
;       COMPUTE(0);
;       __syncthreads();
;       LWRITE(0, 0);
;       __builtin_amdgcn_sched_barrier(0);
;       GLOAD(0, (kt + 4 < last ? kt + 4 : last));
;       __builtin_amdgcn_sched_barrier(0);
;       COMPUTE(1);
;       __syncthreads();
;     }
.Lg9_kloop:
	s_waitcnt vmcnt(6)
	s_waitcnt lgkmcnt(0)
	s_barrier
	v_add_u32_e32 v232, s98, v230
	v_add_u32_e32 v233, s98, v231
	s_add_u32 s9, s17, s101
	s_setprio 1
	v_mfma_f32_16x16x32_bf16 v[0:3], v[128:131], v[144:147], v[0:3]
	v_mfma_f32_16x16x32_bf16 v[4:7], v[132:135], v[144:147], v[4:7]
	v_mfma_f32_16x16x32_bf16 v[8:11], v[136:139], v[144:147], v[8:11]
	v_mfma_f32_16x16x32_bf16 v[12:15], v[140:143], v[144:147], v[12:15]
	ds_read_b128 v[176:179], v233 offset:0
	ds_read_b128 v[180:183], v233 offset:1024
	s_add_u32 m0, s9, 0
	s_nop 0
	global_load_lds_dwordx4 v224, s[0:1]
	v_mfma_f32_16x16x32_bf16 v[16:19], v[128:131], v[148:151], v[16:19]
	v_mfma_f32_16x16x32_bf16 v[20:23], v[132:135], v[148:151], v[20:23]
	v_mfma_f32_16x16x32_bf16 v[24:27], v[136:139], v[148:151], v[24:27]
	v_mfma_f32_16x16x32_bf16 v[28:31], v[140:143], v[148:151], v[28:31]
	ds_read_b128 v[184:187], v233 offset:2048
	ds_read_b128 v[188:191], v233 offset:3072
	s_add_u32 m0, s9, 4096
	s_nop 0
	global_load_lds_dwordx4 v225, s[0:1]
	v_mfma_f32_16x16x32_bf16 v[32:35], v[128:131], v[152:155], v[32:35]
	v_mfma_f32_16x16x32_bf16 v[36:39], v[132:135], v[152:155], v[36:39]
	v_mfma_f32_16x16x32_bf16 v[40:43], v[136:139], v[152:155], v[40:43]
	v_mfma_f32_16x16x32_bf16 v[44:47], v[140:143], v[152:155], v[44:47]
	ds_read_b128 v[192:195], v232 offset:0
	ds_read_b128 v[196:199], v232 offset:1024
	s_add_u32 m0, s9, 8192
	s_nop 0
	global_load_lds_dwordx4 v226, s[0:1]
	v_mfma_f32_16x16x32_bf16 v[48:51], v[128:131], v[156:159], v[48:51]
	v_mfma_f32_16x16x32_bf16 v[52:55], v[132:135], v[156:159], v[52:55]
	v_mfma_f32_16x16x32_bf16 v[56:59], v[136:139], v[156:159], v[56:59]
	v_mfma_f32_16x16x32_bf16 v[60:63], v[140:143], v[156:159], v[60:63]
	ds_read_b128 v[200:203], v232 offset:2048
	ds_read_b128 v[204:207], v232 offset:3072
	s_add_u32 m0, s9, 12288
	s_nop 0
	global_load_lds_dwordx4 v227, s[0:1]
	v_mfma_f32_16x16x32_bf16 v[64:67], v[128:131], v[160:163], v[64:67]
	v_mfma_f32_16x16x32_bf16 v[68:71], v[132:135], v[160:163], v[68:71]
	v_mfma_f32_16x16x32_bf16 v[72:75], v[136:139], v[160:163], v[72:75]
	v_mfma_f32_16x16x32_bf16 v[76:79], v[140:143], v[160:163], v[76:79]
	ds_read_b128 v[208:211], v232 offset:4096
	s_add_u32 m0, s9, 16384
	s_nop 0
	global_load_lds_dwordx4 v228, s[2:3]
	s_cmp_eq_u32 s8, 0
	s_cbranch_scc0 .Lg9_hi0
	s_setprio 0
.Lg9_hi0:
	v_mfma_f32_16x16x32_bf16 v[80:83], v[128:131], v[164:167], v[80:83]
	v_mfma_f32_16x16x32_bf16 v[84:87], v[132:135], v[164:167], v[84:87]
	v_mfma_f32_16x16x32_bf16 v[88:91], v[136:139], v[164:167], v[88:91]
	v_mfma_f32_16x16x32_bf16 v[92:95], v[140:143], v[164:167], v[92:95]
	ds_read_b128 v[212:215], v232 offset:5120
	s_add_u32 m0, s9, 20480
	s_nop 0
	global_load_lds_dwordx4 v229, s[2:3]
	v_mfma_f32_16x16x32_bf16 v[96:99], v[128:131], v[168:171], v[96:99]
	v_mfma_f32_16x16x32_bf16 v[100:103], v[132:135], v[168:171], v[100:103]
	v_mfma_f32_16x16x32_bf16 v[104:107], v[136:139], v[168:171], v[104:107]
	v_mfma_f32_16x16x32_bf16 v[108:111], v[140:143], v[168:171], v[108:111]
	ds_read_b128 v[216:219], v232 offset:6144
	s_add_u32 s0, s0, 64
	s_addc_u32 s1, s1, 0
	s_add_u32 s2, s2, 64
	s_addc_u32 s3, s3, 0
	s_add_u32 s100, s100, 1
	s_add_u32 s17, s17, 24576
	s_cmp_eq_u32 s17, 73728
	s_cselect_b32 s17, 0, s17
	s_add_u32 s98, s98, 24576
	s_cmp_eq_u32 s98, 73728
	s_cselect_b32 s98, 0, s98
	v_mfma_f32_16x16x32_bf16 v[112:115], v[128:131], v[172:175], v[112:115]
	v_mfma_f32_16x16x32_bf16 v[116:119], v[132:135], v[172:175], v[116:119]
	v_mfma_f32_16x16x32_bf16 v[120:123], v[136:139], v[172:175], v[120:123]
	v_mfma_f32_16x16x32_bf16 v[124:127], v[140:143], v[172:175], v[124:127]
	ds_read_b128 v[220:223], v232 offset:7168
	s_waitcnt vmcnt(6)
	s_waitcnt lgkmcnt(0)
	s_barrier
	v_add_u32_e32 v232, s98, v230
	v_add_u32_e32 v233, s98, v231
	s_add_u32 s9, s17, s101
	s_setprio 1
	v_mfma_f32_16x16x32_bf16 v[0:3], v[176:179], v[192:195], v[0:3]
	v_mfma_f32_16x16x32_bf16 v[4:7], v[180:183], v[192:195], v[4:7]
	v_mfma_f32_16x16x32_bf16 v[8:11], v[184:187], v[192:195], v[8:11]
	v_mfma_f32_16x16x32_bf16 v[12:15], v[188:191], v[192:195], v[12:15]
	ds_read_b128 v[128:131], v233 offset:0
	ds_read_b128 v[132:135], v233 offset:1024
	s_add_u32 m0, s9, 0
	s_nop 0
	global_load_lds_dwordx4 v224, s[0:1]
	v_mfma_f32_16x16x32_bf16 v[16:19], v[176:179], v[196:199], v[16:19]
	v_mfma_f32_16x16x32_bf16 v[20:23], v[180:183], v[196:199], v[20:23]
	v_mfma_f32_16x16x32_bf16 v[24:27], v[184:187], v[196:199], v[24:27]
	v_mfma_f32_16x16x32_bf16 v[28:31], v[188:191], v[196:199], v[28:31]
	ds_read_b128 v[136:139], v233 offset:2048
	ds_read_b128 v[140:143], v233 offset:3072
	s_add_u32 m0, s9, 4096
	s_nop 0
	global_load_lds_dwordx4 v225, s[0:1]
	v_mfma_f32_16x16x32_bf16 v[32:35], v[176:179], v[200:203], v[32:35]
	v_mfma_f32_16x16x32_bf16 v[36:39], v[180:183], v[200:203], v[36:39]
	v_mfma_f32_16x16x32_bf16 v[40:43], v[184:187], v[200:203], v[40:43]
	v_mfma_f32_16x16x32_bf16 v[44:47], v[188:191], v[200:203], v[44:47]
	ds_read_b128 v[144:147], v232 offset:0
	ds_read_b128 v[148:151], v232 offset:1024
	s_add_u32 m0, s9, 8192
	s_nop 0
	global_load_lds_dwordx4 v226, s[0:1]
	v_mfma_f32_16x16x32_bf16 v[48:51], v[176:179], v[204:207], v[48:51]
	v_mfma_f32_16x16x32_bf16 v[52:55], v[180:183], v[204:207], v[52:55]
	v_mfma_f32_16x16x32_bf16 v[56:59], v[184:187], v[204:207], v[56:59]
	v_mfma_f32_16x16x32_bf16 v[60:63], v[188:191], v[204:207], v[60:63]
	ds_read_b128 v[152:155], v232 offset:2048
	ds_read_b128 v[156:159], v232 offset:3072
	s_add_u32 m0, s9, 12288
	s_nop 0
	global_load_lds_dwordx4 v227, s[0:1]
	v_mfma_f32_16x16x32_bf16 v[64:67], v[176:179], v[208:211], v[64:67]
	v_mfma_f32_16x16x32_bf16 v[68:71], v[180:183], v[208:211], v[68:71]
	v_mfma_f32_16x16x32_bf16 v[72:75], v[184:187], v[208:211], v[72:75]
	v_mfma_f32_16x16x32_bf16 v[76:79], v[188:191], v[208:211], v[76:79]
	ds_read_b128 v[160:163], v232 offset:4096
	s_add_u32 m0, s9, 16384
	s_nop 0
	global_load_lds_dwordx4 v228, s[2:3]
	s_cmp_eq_u32 s8, 0
	s_cbranch_scc0 .Lg9_hi1
	s_setprio 0
; #define LWRITE(S, buf) do { bf16_t* sA_ = sbase + (buf) * BUF; bf16_t* sB_ = sA_ + 256 * PITCH; \
;     _Pragma("unroll") for (int i_ = 0; i_ < 4; ++i_) *(u32x4*)(sA_ + (sr + i_ * 64) * PITCH + scv * 8) = ra[S][i_]; \
;     _Pragma("unroll") for (int i_ = 0; i_ < 2; ++i_) *(u32x4*)(sB_ + (sr + i_ * 64) * PITCH + scv * 8) = rb[S][i_]; } while (0)
; template <class Epi>
; DI void gemm_tile(char* smem, const bf16_t* __restrict__ A0, int lda0, int ksplit, const bf16_t* __restrict__ A1, int lda1,
;                   const bf16_t* __restrict__ Bt, int K, int row0, int col0, const Epi& epi, int tid) {
;     ...
;   __syncthreads();
;   {
;     const int last = nk - 1;
;     GLOAD(0, 0);
;     __builtin_amdgcn_sched_barrier(0);
;     GLOAD(1, 1);
;     __builtin_amdgcn_sched_barrier(0);
;     LWRITE(0, 0);
;     __builtin_amdgcn_sched_barrier(0);
;     GLOAD(0, (2 < last ? 2 : last));
;     __builtin_amdgcn_sched_barrier(0);
;     __syncthreads();
;     for (int kt = 0; kt < nk; kt += 2) {
;       LWRITE(1, 1);
;       __builtin_amdgcn_sched_barrier(0);
;       GLOAD(1, (kt + 3 < last ? kt + 3 : last));
;       __builtin_amdgcn_sched_barrier(0);
;       COMPUTE(0);
;       __syncthreads();
;       LWRITE(0, 0);
;       __builtin_amdgcn_sched_barrier(0);
;       GLOAD(0, (kt + 4 < last ? kt + 4 : last));
;       __builtin_amdgcn_sched_barrier(0);
;       COMPUTE(1);
;       __syncthreads();
;     }
.Lg9_hi1:
	v_mfma_f32_16x16x32_bf16 v[80:83], v[176:179], v[212:215], v[80:83]
	v_mfma_f32_16x16x32_bf16 v[84:87], v[180:183], v[212:215], v[84:87]
	v_mfma_f32_16x16x32_bf16 v[88:91], v[184:187], v[212:215], v[88:91]
	v_mfma_f32_16x16x32_bf16 v[92:95], v[188:191], v[212:215], v[92:95]
	ds_read_b128 v[164:167], v232 offset:5120
	s_add_u32 m0, s9, 20480
	s_nop 0
	global_load_lds_dwordx4 v229, s[2:3]
	v_mfma_f32_16x16x32_bf16 v[96:99], v[176:179], v[216:219], v[96:99]
	v_mfma_f32_16x16x32_bf16 v[100:103], v[180:183], v[216:219], v[100:103]
	v_mfma_f32_16x16x32_bf16 v[104:107], v[184:187], v[216:219], v[104:107]
	v_mfma_f32_16x16x32_bf16 v[108:111], v[188:191], v[216:219], v[108:111]
	ds_read_b128 v[168:171], v232 offset:6144
	s_add_u32 s0, s0, 64
	s_addc_u32 s1, s1, 0
	s_add_u32 s2, s2, 64
	s_addc_u32 s3, s3, 0
	s_add_u32 s100, s100, 1
	s_add_u32 s17, s17, 24576
	s_cmp_eq_u32 s17, 73728
	s_cselect_b32 s17, 0, s17
	s_add_u32 s98, s98, 24576
	s_cmp_eq_u32 s98, 73728
	s_cselect_b32 s98, 0, s98
	v_mfma_f32_16x16x32_bf16 v[112:115], v[176:179], v[220:223], v[112:115]
	v_mfma_f32_16x16x32_bf16 v[116:119], v[180:183], v[220:223], v[116:119]
	v_mfma_f32_16x16x32_bf16 v[120:123], v[184:187], v[220:223], v[120:123]
	v_mfma_f32_16x16x32_bf16 v[124:127], v[188:191], v[220:223], v[124:127]
	ds_read_b128 v[172:175], v232 offset:7168
	s_add_u32 s99, s99, 2
	s_cmp_lt_u32 s99, 124
	s_cbranch_scc1 .Lg9_kloop
	s_waitcnt vmcnt(6)
	s_waitcnt lgkmcnt(0)
	s_barrier
	v_add_u32_e32 v232, s98, v230
	v_add_u32_e32 v233, s98, v231
	s_add_u32 s9, s17, s101
	s_setprio 1
	v_mfma_f32_16x16x32_bf16 v[0:3], v[128:131], v[144:147], v[0:3]
	v_mfma_f32_16x16x32_bf16 v[4:7], v[132:135], v[144:147], v[4:7]
	v_mfma_f32_16x16x32_bf16 v[8:11], v[136:139], v[144:147], v[8:11]
	v_mfma_f32_16x16x32_bf16 v[12:15], v[140:143], v[144:147], v[12:15]
	ds_read_b128 v[176:179], v233 offset:0
	ds_read_b128 v[180:183], v233 offset:1024
	s_add_u32 m0, s9, 0
	s_nop 0
	global_load_lds_dwordx4 v224, s[0:1]
	v_mfma_f32_16x16x32_bf16 v[16:19], v[128:131], v[148:151], v[16:19]
	v_mfma_f32_16x16x32_bf16 v[20:23], v[132:135], v[148:151], v[20:23]
	v_mfma_f32_16x16x32_bf16 v[24:27], v[136:139], v[148:151], v[24:27]
	v_mfma_f32_16x16x32_bf16 v[28:31], v[140:143], v[148:151], v[28:31]
	ds_read_b128 v[184:187], v233 offset:2048
	ds_read_b128 v[188:191], v233 offset:3072
	s_add_u32 m0, s9, 4096
	s_nop 0
	global_load_lds_dwordx4 v225, s[0:1]
	v_mfma_f32_16x16x32_bf16 v[32:35], v[128:131], v[152:155], v[32:35]
	v_mfma_f32_16x16x32_bf16 v[36:39], v[132:135], v[152:155], v[36:39]
	v_mfma_f32_16x16x32_bf16 v[40:43], v[136:139], v[152:155], v[40:43]
	v_mfma_f32_16x16x32_bf16 v[44:47], v[140:143], v[152:155], v[44:47]
	ds_read_b128 v[192:195], v232 offset:0
	ds_read_b128 v[196:199], v232 offset:1024
	s_add_u32 m0, s9, 8192
	s_nop 0
	global_load_lds_dwordx4 v226, s[0:1]
	v_mfma_f32_16x16x32_bf16 v[48:51], v[128:131], v[156:159], v[48:51]
	v_mfma_f32_16x16x32_bf16 v[52:55], v[132:135], v[156:159], v[52:55]
	v_mfma_f32_16x16x32_bf16 v[56:59], v[136:139], v[156:159], v[56:59]
	v_mfma_f32_16x16x32_bf16 v[60:63], v[140:143], v[156:159], v[60:63]
	ds_read_b128 v[200:203], v232 offset:2048
	ds_read_b128 v[204:207], v232 offset:3072
	s_add_u32 m0, s9, 12288
	s_nop 0
	global_load_lds_dwordx4 v227, s[0:1]
	v_mfma_f32_16x16x32_bf16 v[64:67], v[128:131], v[160:163], v[64:67]
	v_mfma_f32_16x16x32_bf16 v[68:71], v[132:135], v[160:163], v[68:71]
	v_mfma_f32_16x16x32_bf16 v[72:75], v[136:139], v[160:163], v[72:75]
	v_mfma_f32_16x16x32_bf16 v[76:79], v[140:143], v[160:163], v[76:79]
	ds_read_b128 v[208:211], v232 offset:4096
	s_add_u32 m0, s9, 16384
	s_nop 0
	global_load_lds_dwordx4 v228, s[2:3]
	s_cmp_eq_u32 s8, 0
	s_cbranch_scc0 .Lg9_hi2
	s_setprio 0
.Lg9_hi2:
	v_mfma_f32_16x16x32_bf16 v[80:83], v[128:131], v[164:167], v[80:83]
	v_mfma_f32_16x16x32_bf16 v[84:87], v[132:135], v[164:167], v[84:87]
	v_mfma_f32_16x16x32_bf16 v[88:91], v[136:139], v[164:167], v[88:91]
	v_mfma_f32_16x16x32_bf16 v[92:95], v[140:143], v[164:167], v[92:95]
	ds_read_b128 v[212:215], v232 offset:5120
	s_add_u32 m0, s9, 20480
	s_nop 0
	global_load_lds_dwordx4 v229, s[2:3]
	v_mfma_f32_16x16x32_bf16 v[96:99], v[128:131], v[168:171], v[96:99]
	v_mfma_f32_16x16x32_bf16 v[100:103], v[132:135], v[168:171], v[100:103]
	v_mfma_f32_16x16x32_bf16 v[104:107], v[136:139], v[168:171], v[104:107]
	v_mfma_f32_16x16x32_bf16 v[108:111], v[140:143], v[168:171], v[108:111]
	ds_read_b128 v[216:219], v232 offset:6144
	s_add_u32 s0, s0, 64
	s_addc_u32 s1, s1, 0
	s_add_u32 s2, s2, 64
	s_addc_u32 s3, s3, 0
	s_add_u32 s100, s100, 1
	s_add_u32 s17, s17, 24576
	s_cmp_eq_u32 s17, 73728
	s_cselect_b32 s17, 0, s17
	s_add_u32 s98, s98, 24576
	s_cmp_eq_u32 s98, 73728
	s_cselect_b32 s98, 0, s98
	v_mfma_f32_16x16x32_bf16 v[112:115], v[128:131], v[172:175], v[112:115]
	v_mfma_f32_16x16x32_bf16 v[116:119], v[132:135], v[172:175], v[116:119]
	v_mfma_f32_16x16x32_bf16 v[120:123], v[136:139], v[172:175], v[120:123]
	v_mfma_f32_16x16x32_bf16 v[124:127], v[140:143], v[172:175], v[124:127]
	ds_read_b128 v[220:223], v232 offset:7168
	s_waitcnt vmcnt(6)
	s_waitcnt lgkmcnt(0)
	s_barrier
	v_add_u32_e32 v232, s98, v230
	v_add_u32_e32 v233, s98, v231
	s_setprio 1
	v_mfma_f32_16x16x32_bf16 v[0:3], v[176:179], v[192:195], v[0:3]
	v_mfma_f32_16x16x32_bf16 v[4:7], v[180:183], v[192:195], v[4:7]
	v_mfma_f32_16x16x32_bf16 v[8:11], v[184:187], v[192:195], v[8:11]
	v_mfma_f32_16x16x32_bf16 v[12:15], v[188:191], v[192:195], v[12:15]
	ds_read_b128 v[128:131], v233 offset:0
	ds_read_b128 v[132:135], v233 offset:1024
	v_mfma_f32_16x16x32_bf16 v[16:19], v[176:179], v[196:199], v[16:19]
	v_mfma_f32_16x16x32_bf16 v[20:23], v[180:183], v[196:199], v[20:23]
	v_mfma_f32_16x16x32_bf16 v[24:27], v[184:187], v[196:199], v[24:27]
	v_mfma_f32_16x16x32_bf16 v[28:31], v[188:191], v[196:199], v[28:31]
	ds_read_b128 v[136:139], v233 offset:2048
	ds_read_b128 v[140:143], v233 offset:3072
	v_mfma_f32_16x16x32_bf16 v[32:35], v[176:179], v[200:203], v[32:35]
	v_mfma_f32_16x16x32_bf16 v[36:39], v[180:183], v[200:203], v[36:39]
	v_mfma_f32_16x16x32_bf16 v[40:43], v[184:187], v[200:203], v[40:43]
	v_mfma_f32_16x16x32_bf16 v[44:47], v[188:191], v[200:203], v[44:47]
	ds_read_b128 v[144:147], v232 offset:0
	ds_read_b128 v[148:151], v232 offset:1024
	v_mfma_f32_16x16x32_bf16 v[48:51], v[176:179], v[204:207], v[48:51]
	v_mfma_f32_16x16x32_bf16 v[52:55], v[180:183], v[204:207], v[52:55]
	v_mfma_f32_16x16x32_bf16 v[56:59], v[184:187], v[204:207], v[56:59]
	v_mfma_f32_16x16x32_bf16 v[60:63], v[188:191], v[204:207], v[60:63]
	ds_read_b128 v[152:155], v232 offset:2048
	ds_read_b128 v[156:159], v232 offset:3072
	v_mfma_f32_16x16x32_bf16 v[64:67], v[176:179], v[208:211], v[64:67]
	v_mfma_f32_16x16x32_bf16 v[68:71], v[180:183], v[208:211], v[68:71]
	v_mfma_f32_16x16x32_bf16 v[72:75], v[184:187], v[208:211], v[72:75]
	v_mfma_f32_16x16x32_bf16 v[76:79], v[188:191], v[208:211], v[76:79]
	ds_read_b128 v[160:163], v232 offset:4096
	s_cmp_eq_u32 s8, 0
	s_cbranch_scc0 .Lg9_hi3
	s_setprio 0
; #define LWRITE(S, buf) do { bf16_t* sA_ = sbase + (buf) * BUF; bf16_t* sB_ = sA_ + 256 * PITCH; \
;     _Pragma("unroll") for (int i_ = 0; i_ < 4; ++i_) *(u32x4*)(sA_ + (sr + i_ * 64) * PITCH + scv * 8) = ra[S][i_]; \
;     _Pragma("unroll") for (int i_ = 0; i_ < 2; ++i_) *(u32x4*)(sB_ + (sr + i_ * 64) * PITCH + scv * 8) = rb[S][i_]; } while (0)
; template <class Epi>
; DI void gemm_tile(char* smem, const bf16_t* __restrict__ A0, int lda0, int ksplit, const bf16_t* __restrict__ A1, int lda1,
;                   const bf16_t* __restrict__ Bt, int K, int row0, int col0, const Epi& epi, int tid) {
;     ...
;   __syncthreads();
;   {
;     const int last = nk - 1;
;     GLOAD(0, 0);
;     __builtin_amdgcn_sched_barrier(0);
;     GLOAD(1, 1);
;     __builtin_amdgcn_sched_barrier(0);
;     LWRITE(0, 0);
;     __builtin_amdgcn_sched_barrier(0);
;     GLOAD(0, (2 < last ? 2 : last));
;     __builtin_amdgcn_sched_barrier(0);
;     __syncthreads();
;     for (int kt = 0; kt < nk; kt += 2) {
;       LWRITE(1, 1);
;       __builtin_amdgcn_sched_barrier(0);
;       GLOAD(1, (kt + 3 < last ? kt + 3 : last));
;       __builtin_amdgcn_sched_barrier(0);
;       COMPUTE(0);
;       __syncthreads();
;       LWRITE(0, 0);
;       __builtin_amdgcn_sched_barrier(0);
;       GLOAD(0, (kt + 4 < last ? kt + 4 : last));
;       __builtin_amdgcn_sched_barrier(0);
;       COMPUTE(1);
;       __syncthreads();
;     }
.Lg9_hi3:
	v_mfma_f32_16x16x32_bf16 v[80:83], v[176:179], v[212:215], v[80:83]
	v_mfma_f32_16x16x32_bf16 v[84:87], v[180:183], v[212:215], v[84:87]
	v_mfma_f32_16x16x32_bf16 v[88:91], v[184:187], v[212:215], v[88:91]
	v_mfma_f32_16x16x32_bf16 v[92:95], v[188:191], v[212:215], v[92:95]
	ds_read_b128 v[164:167], v232 offset:5120
	v_mfma_f32_16x16x32_bf16 v[96:99], v[176:179], v[216:219], v[96:99]
	v_mfma_f32_16x16x32_bf16 v[100:103], v[180:183], v[216:219], v[100:103]
	v_mfma_f32_16x16x32_bf16 v[104:107], v[184:187], v[216:219], v[104:107]
	v_mfma_f32_16x16x32_bf16 v[108:111], v[188:191], v[216:219], v[108:111]
	ds_read_b128 v[168:171], v232 offset:6144
	s_add_u32 s98, s98, 24576
	s_cmp_eq_u32 s98, 73728
	s_cselect_b32 s98, 0, s98
	v_mfma_f32_16x16x32_bf16 v[112:115], v[176:179], v[220:223], v[112:115]
	v_mfma_f32_16x16x32_bf16 v[116:119], v[180:183], v[220:223], v[116:119]
	v_mfma_f32_16x16x32_bf16 v[120:123], v[184:187], v[220:223], v[120:123]
	v_mfma_f32_16x16x32_bf16 v[124:127], v[188:191], v[220:223], v[124:127]
	ds_read_b128 v[172:175], v232 offset:7168
	s_waitcnt vmcnt(0)
	s_waitcnt lgkmcnt(0)
	s_barrier
	v_add_u32_e32 v232, s98, v230
	v_add_u32_e32 v233, s98, v231
	s_setprio 1
	v_mfma_f32_16x16x32_bf16 v[0:3], v[128:131], v[144:147], v[0:3]
	v_mfma_f32_16x16x32_bf16 v[4:7], v[132:135], v[144:147], v[4:7]
	v_mfma_f32_16x16x32_bf16 v[8:11], v[136:139], v[144:147], v[8:11]
	v_mfma_f32_16x16x32_bf16 v[12:15], v[140:143], v[144:147], v[12:15]
	ds_read_b128 v[176:179], v233 offset:0
	ds_read_b128 v[180:183], v233 offset:1024
	v_mfma_f32_16x16x32_bf16 v[16:19], v[128:131], v[148:151], v[16:19]
	v_mfma_f32_16x16x32_bf16 v[20:23], v[132:135], v[148:151], v[20:23]
	v_mfma_f32_16x16x32_bf16 v[24:27], v[136:139], v[148:151], v[24:27]
	v_mfma_f32_16x16x32_bf16 v[28:31], v[140:143], v[148:151], v[28:31]
	ds_read_b128 v[184:187], v233 offset:2048
	ds_read_b128 v[188:191], v233 offset:3072
	v_mfma_f32_16x16x32_bf16 v[32:35], v[128:131], v[152:155], v[32:35]
	v_mfma_f32_16x16x32_bf16 v[36:39], v[132:135], v[152:155], v[36:39]
	v_mfma_f32_16x16x32_bf16 v[40:43], v[136:139], v[152:155], v[40:43]
	v_mfma_f32_16x16x32_bf16 v[44:47], v[140:143], v[152:155], v[44:47]
	ds_read_b128 v[192:195], v232 offset:0
	ds_read_b128 v[196:199], v232 offset:1024
	v_mfma_f32_16x16x32_bf16 v[48:51], v[128:131], v[156:159], v[48:51]
	v_mfma_f32_16x16x32_bf16 v[52:55], v[132:135], v[156:159], v[52:55]
	v_mfma_f32_16x16x32_bf16 v[56:59], v[136:139], v[156:159], v[56:59]
	v_mfma_f32_16x16x32_bf16 v[60:63], v[140:143], v[156:159], v[60:63]
	ds_read_b128 v[200:203], v232 offset:2048
	ds_read_b128 v[204:207], v232 offset:3072
	v_mfma_f32_16x16x32_bf16 v[64:67], v[128:131], v[160:163], v[64:67]
	v_mfma_f32_16x16x32_bf16 v[68:71], v[132:135], v[160:163], v[68:71]
	v_mfma_f32_16x16x32_bf16 v[72:75], v[136:139], v[160:163], v[72:75]
	v_mfma_f32_16x16x32_bf16 v[76:79], v[140:143], v[160:163], v[76:79]
	ds_read_b128 v[208:211], v232 offset:4096
	s_cmp_eq_u32 s8, 0
	s_cbranch_scc0 .Lg9_hi4
	s_setprio 0
.Lg9_hi4:
	v_mfma_f32_16x16x32_bf16 v[80:83], v[128:131], v[164:167], v[80:83]
	v_mfma_f32_16x16x32_bf16 v[84:87], v[132:135], v[164:167], v[84:87]
	v_mfma_f32_16x16x32_bf16 v[88:91], v[136:139], v[164:167], v[88:91]
	v_mfma_f32_16x16x32_bf16 v[92:95], v[140:143], v[164:167], v[92:95]
	ds_read_b128 v[212:215], v232 offset:5120
	v_mfma_f32_16x16x32_bf16 v[96:99], v[128:131], v[168:171], v[96:99]
	v_mfma_f32_16x16x32_bf16 v[100:103], v[132:135], v[168:171], v[100:103]
	v_mfma_f32_16x16x32_bf16 v[104:107], v[136:139], v[168:171], v[104:107]
	v_mfma_f32_16x16x32_bf16 v[108:111], v[140:143], v[168:171], v[108:111]
	ds_read_b128 v[216:219], v232 offset:6144
	s_add_u32 s98, s98, 24576
	s_cmp_eq_u32 s98, 73728
	s_cselect_b32 s98, 0, s98
	v_mfma_f32_16x16x32_bf16 v[112:115], v[128:131], v[172:175], v[112:115]
	v_mfma_f32_16x16x32_bf16 v[116:119], v[132:135], v[172:175], v[116:119]
	v_mfma_f32_16x16x32_bf16 v[120:123], v[136:139], v[172:175], v[120:123]
	v_mfma_f32_16x16x32_bf16 v[124:127], v[140:143], v[172:175], v[124:127]
	ds_read_b128 v[220:223], v232 offset:7168
	s_waitcnt lgkmcnt(0)
	s_barrier
	s_setprio 1
	v_mfma_f32_16x16x32_bf16 v[0:3], v[176:179], v[192:195], v[0:3]
	v_mfma_f32_16x16x32_bf16 v[4:7], v[180:183], v[192:195], v[4:7]
	v_mfma_f32_16x16x32_bf16 v[8:11], v[184:187], v[192:195], v[8:11]
	v_mfma_f32_16x16x32_bf16 v[12:15], v[188:191], v[192:195], v[12:15]
	v_mfma_f32_16x16x32_bf16 v[16:19], v[176:179], v[196:199], v[16:19]
	v_mfma_f32_16x16x32_bf16 v[20:23], v[180:183], v[196:199], v[20:23]
	v_mfma_f32_16x16x32_bf16 v[24:27], v[184:187], v[196:199], v[24:27]
	v_mfma_f32_16x16x32_bf16 v[28:31], v[188:191], v[196:199], v[28:31]
	v_mfma_f32_16x16x32_bf16 v[32:35], v[176:179], v[200:203], v[32:35]
	v_mfma_f32_16x16x32_bf16 v[36:39], v[180:183], v[200:203], v[36:39]
	v_mfma_f32_16x16x32_bf16 v[40:43], v[184:187], v[200:203], v[40:43]
	v_mfma_f32_16x16x32_bf16 v[44:47], v[188:191], v[200:203], v[44:47]
	v_mfma_f32_16x16x32_bf16 v[48:51], v[176:179], v[204:207], v[48:51]
	v_mfma_f32_16x16x32_bf16 v[52:55], v[180:183], v[204:207], v[52:55]
	v_mfma_f32_16x16x32_bf16 v[56:59], v[184:187], v[204:207], v[56:59]
	v_mfma_f32_16x16x32_bf16 v[60:63], v[188:191], v[204:207], v[60:63]
	v_mfma_f32_16x16x32_bf16 v[64:67], v[176:179], v[208:211], v[64:67]
	v_mfma_f32_16x16x32_bf16 v[68:71], v[180:183], v[208:211], v[68:71]
	v_mfma_f32_16x16x32_bf16 v[72:75], v[184:187], v[208:211], v[72:75]
	v_mfma_f32_16x16x32_bf16 v[76:79], v[188:191], v[208:211], v[76:79]
	s_cmp_eq_u32 s8, 0
	s_cbranch_scc0 .Lg9_hi5
	s_setprio 0

; #define LWRITE(S, buf) do { bf16_t* sA_ = sbase + (buf) * BUF; bf16_t* sB_ = sA_ + 256 * PITCH; \
;     _Pragma("unroll") for (int i_ = 0; i_ < 4; ++i_) *(u32x4*)(sA_ + (sr + i_ * 64) * PITCH + scv * 8) = ra[S][i_]; \
;     _Pragma("unroll") for (int i_ = 0; i_ < 2; ++i_) *(u32x4*)(sB_ + (sr + i_ * 64) * PITCH + scv * 8) = rb[S][i_]; } while (0)
; template <class Epi>
; DI void gemm_tile(char* smem, const bf16_t* __restrict__ A0, int lda0, int ksplit, const bf16_t* __restrict__ A1, int lda1,
;                   const bf16_t* __restrict__ Bt, int K, int row0, int col0, const Epi& epi, int tid) {
;     ...
;   __syncthreads();
;   {
;     const int last = nk - 1;
;     GLOAD(0, 0);
;     __builtin_amdgcn_sched_barrier(0);
;     GLOAD(1, 1);
;     __builtin_amdgcn_sched_barrier(0);
;     LWRITE(0, 0);
;     __builtin_amdgcn_sched_barrier(0);
;     GLOAD(0, (2 < last ? 2 : last));
;     __builtin_amdgcn_sched_barrier(0);
;     __syncthreads();
;     for (int kt = 0; kt < nk; kt += 2) {
;       LWRITE(1, 1);
;       __builtin_amdgcn_sched_barrier(0);
;       GLOAD(1, (kt + 3 < last ? kt + 3 : last));
;       __builtin_amdgcn_sched_barrier(0);
;       COMPUTE(0);
;       __syncthreads();
;       LWRITE(0, 0);
;       __builtin_amdgcn_sched_barrier(0);
;       GLOAD(0, (kt + 4 < last ? kt + 4 : last));
;       __builtin_amdgcn_sched_barrier(0);
;       COMPUTE(1);
;       __syncthreads();
;     }
.Lg11_kloop:
	s_waitcnt vmcnt(6)
	s_waitcnt lgkmcnt(0)
	s_barrier
	v_add_u32_e32 v232, s30, v230
	v_add_u32_e32 v233, s30, v231
	s_add_u32 s25, s29, s99
	s_setprio 1
	v_mfma_f32_16x16x32_bf16 v[0:3], v[128:131], v[144:147], v[0:3]
	v_mfma_f32_16x16x32_bf16 v[4:7], v[132:135], v[144:147], v[4:7]
	v_mfma_f32_16x16x32_bf16 v[8:11], v[136:139], v[144:147], v[8:11]
	v_mfma_f32_16x16x32_bf16 v[12:15], v[140:143], v[144:147], v[12:15]
	ds_read_b128 v[176:179], v233 offset:0
	ds_read_b128 v[180:183], v233 offset:1024
	s_add_u32 m0, s25, 0
	s_nop 0
	global_load_lds_dwordx4 v224, s[0:1]
	v_mfma_f32_16x16x32_bf16 v[16:19], v[128:131], v[148:151], v[16:19]
	v_mfma_f32_16x16x32_bf16 v[20:23], v[132:135], v[148:151], v[20:23]
	v_mfma_f32_16x16x32_bf16 v[24:27], v[136:139], v[148:151], v[24:27]
	v_mfma_f32_16x16x32_bf16 v[28:31], v[140:143], v[148:151], v[28:31]
	ds_read_b128 v[184:187], v233 offset:2048
	ds_read_b128 v[188:191], v233 offset:3072
	s_add_u32 m0, s25, 4096
	s_nop 0
	global_load_lds_dwordx4 v225, s[0:1]
	v_mfma_f32_16x16x32_bf16 v[32:35], v[128:131], v[152:155], v[32:35]
	v_mfma_f32_16x16x32_bf16 v[36:39], v[132:135], v[152:155], v[36:39]
	v_mfma_f32_16x16x32_bf16 v[40:43], v[136:139], v[152:155], v[40:43]
	v_mfma_f32_16x16x32_bf16 v[44:47], v[140:143], v[152:155], v[44:47]
	ds_read_b128 v[192:195], v232 offset:0
	ds_read_b128 v[196:199], v232 offset:1024
	s_add_u32 m0, s25, 8192
	s_nop 0
	global_load_lds_dwordx4 v226, s[0:1]
	v_mfma_f32_16x16x32_bf16 v[48:51], v[128:131], v[156:159], v[48:51]
	v_mfma_f32_16x16x32_bf16 v[52:55], v[132:135], v[156:159], v[52:55]
	v_mfma_f32_16x16x32_bf16 v[56:59], v[136:139], v[156:159], v[56:59]
	v_mfma_f32_16x16x32_bf16 v[60:63], v[140:143], v[156:159], v[60:63]
	ds_read_b128 v[200:203], v232 offset:2048
	ds_read_b128 v[204:207], v232 offset:3072
	s_add_u32 m0, s25, 12288
	s_nop 0
	global_load_lds_dwordx4 v227, s[0:1]
	v_mfma_f32_16x16x32_bf16 v[64:67], v[128:131], v[160:163], v[64:67]
	v_mfma_f32_16x16x32_bf16 v[68:71], v[132:135], v[160:163], v[68:71]
	v_mfma_f32_16x16x32_bf16 v[72:75], v[136:139], v[160:163], v[72:75]
	v_mfma_f32_16x16x32_bf16 v[76:79], v[140:143], v[160:163], v[76:79]
	ds_read_b128 v[208:211], v232 offset:4096
	s_add_u32 m0, s25, 16384
	s_nop 0
	global_load_lds_dwordx4 v228, s[2:3]
	s_cmp_eq_u32 s24, 0
	s_cbranch_scc0 .Lg11_hi0
	s_setprio 0
.Lg11_hi0:
	v_mfma_f32_16x16x32_bf16 v[80:83], v[128:131], v[164:167], v[80:83]
	v_mfma_f32_16x16x32_bf16 v[84:87], v[132:135], v[164:167], v[84:87]
	v_mfma_f32_16x16x32_bf16 v[88:91], v[136:139], v[164:167], v[88:91]
	v_mfma_f32_16x16x32_bf16 v[92:95], v[140:143], v[164:167], v[92:95]
	ds_read_b128 v[212:215], v232 offset:5120
	s_add_u32 m0, s25, 20480
	s_nop 0
	global_load_lds_dwordx4 v229, s[2:3]
	v_mfma_f32_16x16x32_bf16 v[96:99], v[128:131], v[168:171], v[96:99]
	v_mfma_f32_16x16x32_bf16 v[100:103], v[132:135], v[168:171], v[100:103]
	v_mfma_f32_16x16x32_bf16 v[104:107], v[136:139], v[168:171], v[104:107]
	v_mfma_f32_16x16x32_bf16 v[108:111], v[140:143], v[168:171], v[108:111]
	ds_read_b128 v[216:219], v232 offset:6144
	s_add_u32 s0, s0, 64
	s_addc_u32 s1, s1, 0
	s_add_u32 s2, s2, 64
	s_addc_u32 s3, s3, 0
	s_add_u32 s98, s98, 1
	s_add_u32 s29, s29, 24576
	s_cmp_eq_u32 s29, 73728
	s_cselect_b32 s29, 0, s29
	s_add_u32 s30, s30, 24576
	s_cmp_eq_u32 s30, 73728
	s_cselect_b32 s30, 0, s30
	v_mfma_f32_16x16x32_bf16 v[112:115], v[128:131], v[172:175], v[112:115]
	v_mfma_f32_16x16x32_bf16 v[116:119], v[132:135], v[172:175], v[116:119]
	v_mfma_f32_16x16x32_bf16 v[120:123], v[136:139], v[172:175], v[120:123]
	v_mfma_f32_16x16x32_bf16 v[124:127], v[140:143], v[172:175], v[124:127]
	ds_read_b128 v[220:223], v232 offset:7168
	s_waitcnt vmcnt(6)
	s_waitcnt lgkmcnt(0)
	s_barrier
	v_add_u32_e32 v232, s30, v230
	v_add_u32_e32 v233, s30, v231
	s_add_u32 s25, s29, s99
	s_setprio 1
	v_mfma_f32_16x16x32_bf16 v[0:3], v[176:179], v[192:195], v[0:3]
	v_mfma_f32_16x16x32_bf16 v[4:7], v[180:183], v[192:195], v[4:7]
	v_mfma_f32_16x16x32_bf16 v[8:11], v[184:187], v[192:195], v[8:11]
	v_mfma_f32_16x16x32_bf16 v[12:15], v[188:191], v[192:195], v[12:15]
	ds_read_b128 v[128:131], v233 offset:0
	ds_read_b128 v[132:135], v233 offset:1024
	s_add_u32 m0, s25, 0
	s_nop 0
	global_load_lds_dwordx4 v224, s[0:1]
	v_mfma_f32_16x16x32_bf16 v[16:19], v[176:179], v[196:199], v[16:19]
	v_mfma_f32_16x16x32_bf16 v[20:23], v[180:183], v[196:199], v[20:23]
	v_mfma_f32_16x16x32_bf16 v[24:27], v[184:187], v[196:199], v[24:27]
	v_mfma_f32_16x16x32_bf16 v[28:31], v[188:191], v[196:199], v[28:31]
	ds_read_b128 v[136:139], v233 offset:2048
	ds_read_b128 v[140:143], v233 offset:3072
	s_add_u32 m0, s25, 4096
	s_nop 0
	global_load_lds_dwordx4 v225, s[0:1]
	v_mfma_f32_16x16x32_bf16 v[32:35], v[176:179], v[200:203], v[32:35]
	v_mfma_f32_16x16x32_bf16 v[36:39], v[180:183], v[200:203], v[36:39]
	v_mfma_f32_16x16x32_bf16 v[40:43], v[184:187], v[200:203], v[40:43]
	v_mfma_f32_16x16x32_bf16 v[44:47], v[188:191], v[200:203], v[44:47]
	ds_read_b128 v[144:147], v232 offset:0
	ds_read_b128 v[148:151], v232 offset:1024
	s_add_u32 m0, s25, 8192
	s_nop 0
	global_load_lds_dwordx4 v226, s[0:1]
	v_mfma_f32_16x16x32_bf16 v[48:51], v[176:179], v[204:207], v[48:51]
	v_mfma_f32_16x16x32_bf16 v[52:55], v[180:183], v[204:207], v[52:55]
	v_mfma_f32_16x16x32_bf16 v[56:59], v[184:187], v[204:207], v[56:59]
	v_mfma_f32_16x16x32_bf16 v[60:63], v[188:191], v[204:207], v[60:63]
	ds_read_b128 v[152:155], v232 offset:2048
	ds_read_b128 v[156:159], v232 offset:3072
	s_add_u32 m0, s25, 12288
	s_nop 0
	global_load_lds_dwordx4 v227, s[0:1]
	v_mfma_f32_16x16x32_bf16 v[64:67], v[176:179], v[208:211], v[64:67]
	v_mfma_f32_16x16x32_bf16 v[68:71], v[180:183], v[208:211], v[68:71]
	v_mfma_f32_16x16x32_bf16 v[72:75], v[184:187], v[208:211], v[72:75]
	v_mfma_f32_16x16x32_bf16 v[76:79], v[188:191], v[208:211], v[76:79]
	ds_read_b128 v[160:163], v232 offset:4096
	s_add_u32 m0, s25, 16384
	s_nop 0
	global_load_lds_dwordx4 v228, s[2:3]
	s_cmp_eq_u32 s24, 0
	s_cbranch_scc0 .Lg11_hi1
	s_setprio 0
; #define LWRITE(S, buf) do { bf16_t* sA_ = sbase + (buf) * BUF; bf16_t* sB_ = sA_ + 256 * PITCH; \
;     _Pragma("unroll") for (int i_ = 0; i_ < 4; ++i_) *(u32x4*)(sA_ + (sr + i_ * 64) * PITCH + scv * 8) = ra[S][i_]; \
;     _Pragma("unroll") for (int i_ = 0; i_ < 2; ++i_) *(u32x4*)(sB_ + (sr + i_ * 64) * PITCH + scv * 8) = rb[S][i_]; } while (0)
; template <class Epi>
; DI void gemm_tile(char* smem, const bf16_t* __restrict__ A0, int lda0, int ksplit, const bf16_t* __restrict__ A1, int lda1,
;                   const bf16_t* __restrict__ Bt, int K, int row0, int col0, const Epi& epi, int tid) {
;     ...
;     for (int kt = 0; kt < nk; kt += 2) {
;       LWRITE(1, 1);
;       __builtin_amdgcn_sched_barrier(0);
;       GLOAD(1, (kt + 3 < last ? kt + 3 : last));
;       __builtin_amdgcn_sched_barrier(0);
;       COMPUTE(0);
;       __syncthreads();
;       LWRITE(0, 0);
;       __builtin_amdgcn_sched_barrier(0);
;       GLOAD(0, (kt + 4 < last ? kt + 4 : last));
;       __builtin_amdgcn_sched_barrier(0);
;       COMPUTE(1);
;       __syncthreads();
;     }
.Lg11_hi1:
	v_mfma_f32_16x16x32_bf16 v[80:83], v[176:179], v[212:215], v[80:83]
	v_mfma_f32_16x16x32_bf16 v[84:87], v[180:183], v[212:215], v[84:87]
	v_mfma_f32_16x16x32_bf16 v[88:91], v[184:187], v[212:215], v[88:91]
	v_mfma_f32_16x16x32_bf16 v[92:95], v[188:191], v[212:215], v[92:95]
	ds_read_b128 v[164:167], v232 offset:5120
	s_add_u32 m0, s25, 20480
	s_nop 0
	global_load_lds_dwordx4 v229, s[2:3]
	v_mfma_f32_16x16x32_bf16 v[96:99], v[176:179], v[216:219], v[96:99]
	v_mfma_f32_16x16x32_bf16 v[100:103], v[180:183], v[216:219], v[100:103]
	v_mfma_f32_16x16x32_bf16 v[104:107], v[184:187], v[216:219], v[104:107]
	v_mfma_f32_16x16x32_bf16 v[108:111], v[188:191], v[216:219], v[108:111]
	ds_read_b128 v[168:171], v232 offset:6144
	s_add_u32 s0, s0, 64
	s_addc_u32 s1, s1, 0
	s_add_u32 s2, s2, 64
	s_addc_u32 s3, s3, 0
	s_add_u32 s98, s98, 1
	s_add_u32 s29, s29, 24576
	s_cmp_eq_u32 s29, 73728
	s_cselect_b32 s29, 0, s29
	s_add_u32 s30, s30, 24576
	s_cmp_eq_u32 s30, 73728
	s_cselect_b32 s30, 0, s30
	v_mfma_f32_16x16x32_bf16 v[112:115], v[176:179], v[220:223], v[112:115]
	v_mfma_f32_16x16x32_bf16 v[116:119], v[180:183], v[220:223], v[116:119]
	v_mfma_f32_16x16x32_bf16 v[120:123], v[184:187], v[220:223], v[120:123]
	v_mfma_f32_16x16x32_bf16 v[124:127], v[188:191], v[220:223], v[124:127]
	ds_read_b128 v[172:175], v232 offset:7168
	s_add_u32 s31, s31, 2
	s_cmp_lt_u32 s31, 28
	s_cbranch_scc1 .Lg11_kloop
	s_waitcnt vmcnt(6)
	s_waitcnt lgkmcnt(0)
	s_barrier
	v_add_u32_e32 v232, s30, v230
	v_add_u32_e32 v233, s30, v231
	s_add_u32 s25, s29, s99
	s_setprio 1
	v_mfma_f32_16x16x32_bf16 v[0:3], v[128:131], v[144:147], v[0:3]
	v_mfma_f32_16x16x32_bf16 v[4:7], v[132:135], v[144:147], v[4:7]
	v_mfma_f32_16x16x32_bf16 v[8:11], v[136:139], v[144:147], v[8:11]
	v_mfma_f32_16x16x32_bf16 v[12:15], v[140:143], v[144:147], v[12:15]
	ds_read_b128 v[176:179], v233 offset:0
	ds_read_b128 v[180:183], v233 offset:1024
	s_add_u32 m0, s25, 0
	s_nop 0
	global_load_lds_dwordx4 v224, s[0:1]
	v_mfma_f32_16x16x32_bf16 v[16:19], v[128:131], v[148:151], v[16:19]
	v_mfma_f32_16x16x32_bf16 v[20:23], v[132:135], v[148:151], v[20:23]
	v_mfma_f32_16x16x32_bf16 v[24:27], v[136:139], v[148:151], v[24:27]
	v_mfma_f32_16x16x32_bf16 v[28:31], v[140:143], v[148:151], v[28:31]
	ds_read_b128 v[184:187], v233 offset:2048
	ds_read_b128 v[188:191], v233 offset:3072
	s_add_u32 m0, s25, 4096
	s_nop 0
	global_load_lds_dwordx4 v225, s[0:1]
	v_mfma_f32_16x16x32_bf16 v[32:35], v[128:131], v[152:155], v[32:35]
	v_mfma_f32_16x16x32_bf16 v[36:39], v[132:135], v[152:155], v[36:39]
	v_mfma_f32_16x16x32_bf16 v[40:43], v[136:139], v[152:155], v[40:43]
	v_mfma_f32_16x16x32_bf16 v[44:47], v[140:143], v[152:155], v[44:47]
	ds_read_b128 v[192:195], v232 offset:0
	ds_read_b128 v[196:199], v232 offset:1024
	s_add_u32 m0, s25, 8192
	s_nop 0
	global_load_lds_dwordx4 v226, s[0:1]
	v_mfma_f32_16x16x32_bf16 v[48:51], v[128:131], v[156:159], v[48:51]
	v_mfma_f32_16x16x32_bf16 v[52:55], v[132:135], v[156:159], v[52:55]
	v_mfma_f32_16x16x32_bf16 v[56:59], v[136:139], v[156:159], v[56:59]
	v_mfma_f32_16x16x32_bf16 v[60:63], v[140:143], v[156:159], v[60:63]
	ds_read_b128 v[200:203], v232 offset:2048
	ds_read_b128 v[204:207], v232 offset:3072
	s_add_u32 m0, s25, 12288
	s_nop 0
	global_load_lds_dwordx4 v227, s[0:1]
	v_mfma_f32_16x16x32_bf16 v[64:67], v[128:131], v[160:163], v[64:67]
	v_mfma_f32_16x16x32_bf16 v[68:71], v[132:135], v[160:163], v[68:71]
	v_mfma_f32_16x16x32_bf16 v[72:75], v[136:139], v[160:163], v[72:75]
	v_mfma_f32_16x16x32_bf16 v[76:79], v[140:143], v[160:163], v[76:79]
	ds_read_b128 v[208:211], v232 offset:4096
	s_add_u32 m0, s25, 16384
	s_nop 0
	global_load_lds_dwordx4 v228, s[2:3]
	s_cmp_eq_u32 s24, 0
	s_cbranch_scc0 .Lg11_hi2
	s_setprio 0
.Lg11_hi2:
	v_mfma_f32_16x16x32_bf16 v[80:83], v[128:131], v[164:167], v[80:83]
	v_mfma_f32_16x16x32_bf16 v[84:87], v[132:135], v[164:167], v[84:87]
	v_mfma_f32_16x16x32_bf16 v[88:91], v[136:139], v[164:167], v[88:91]
	v_mfma_f32_16x16x32_bf16 v[92:95], v[140:143], v[164:167], v[92:95]
	ds_read_b128 v[212:215], v232 offset:5120
	s_add_u32 m0, s25, 20480
	s_nop 0
	global_load_lds_dwordx4 v229, s[2:3]
	v_mfma_f32_16x16x32_bf16 v[96:99], v[128:131], v[168:171], v[96:99]
	v_mfma_f32_16x16x32_bf16 v[100:103], v[132:135], v[168:171], v[100:103]
	v_mfma_f32_16x16x32_bf16 v[104:107], v[136:139], v[168:171], v[104:107]
	v_mfma_f32_16x16x32_bf16 v[108:111], v[140:143], v[168:171], v[108:111]
	ds_read_b128 v[216:219], v232 offset:6144
	s_add_u32 s0, s0, 64
	s_addc_u32 s1, s1, 0
	s_add_u32 s2, s2, 64
	s_addc_u32 s3, s3, 0
	s_add_u32 s98, s98, 1
	s_add_u32 s29, s29, 24576
	s_cmp_eq_u32 s29, 73728
	s_cselect_b32 s29, 0, s29
	s_add_u32 s30, s30, 24576
	s_cmp_eq_u32 s30, 73728
	s_cselect_b32 s30, 0, s30
	v_mfma_f32_16x16x32_bf16 v[112:115], v[128:131], v[172:175], v[112:115]
	v_mfma_f32_16x16x32_bf16 v[116:119], v[132:135], v[172:175], v[116:119]
	v_mfma_f32_16x16x32_bf16 v[120:123], v[136:139], v[172:175], v[120:123]
	v_mfma_f32_16x16x32_bf16 v[124:127], v[140:143], v[172:175], v[124:127]
	ds_read_b128 v[220:223], v232 offset:7168
	s_waitcnt vmcnt(6)
	s_waitcnt lgkmcnt(0)
	s_barrier
	v_add_u32_e32 v232, s30, v230
	v_add_u32_e32 v233, s30, v231
	s_setprio 1
	v_mfma_f32_16x16x32_bf16 v[0:3], v[176:179], v[192:195], v[0:3]
	v_mfma_f32_16x16x32_bf16 v[4:7], v[180:183], v[192:195], v[4:7]
	v_mfma_f32_16x16x32_bf16 v[8:11], v[184:187], v[192:195], v[8:11]
	v_mfma_f32_16x16x32_bf16 v[12:15], v[188:191], v[192:195], v[12:15]
	ds_read_b128 v[128:131], v233 offset:0
	ds_read_b128 v[132:135], v233 offset:1024
	v_mfma_f32_16x16x32_bf16 v[16:19], v[176:179], v[196:199], v[16:19]
	v_mfma_f32_16x16x32_bf16 v[20:23], v[180:183], v[196:199], v[20:23]
	v_mfma_f32_16x16x32_bf16 v[24:27], v[184:187], v[196:199], v[24:27]
	v_mfma_f32_16x16x32_bf16 v[28:31], v[188:191], v[196:199], v[28:31]
	ds_read_b128 v[136:139], v233 offset:2048
	ds_read_b128 v[140:143], v233 offset:3072
	v_mfma_f32_16x16x32_bf16 v[32:35], v[176:179], v[200:203], v[32:35]
	v_mfma_f32_16x16x32_bf16 v[36:39], v[180:183], v[200:203], v[36:39]
	v_mfma_f32_16x16x32_bf16 v[40:43], v[184:187], v[200:203], v[40:43]
	v_mfma_f32_16x16x32_bf16 v[44:47], v[188:191], v[200:203], v[44:47]
	ds_read_b128 v[144:147], v232 offset:0
	ds_read_b128 v[148:151], v232 offset:1024
	v_mfma_f32_16x16x32_bf16 v[48:51], v[176:179], v[204:207], v[48:51]
	v_mfma_f32_16x16x32_bf16 v[52:55], v[180:183], v[204:207], v[52:55]
	v_mfma_f32_16x16x32_bf16 v[56:59], v[184:187], v[204:207], v[56:59]
	v_mfma_f32_16x16x32_bf16 v[60:63], v[188:191], v[204:207], v[60:63]
	ds_read_b128 v[152:155], v232 offset:2048
	ds_read_b128 v[156:159], v232 offset:3072
	v_mfma_f32_16x16x32_bf16 v[64:67], v[176:179], v[208:211], v[64:67]
	v_mfma_f32_16x16x32_bf16 v[68:71], v[180:183], v[208:211], v[68:71]
	v_mfma_f32_16x16x32_bf16 v[72:75], v[184:187], v[208:211], v[72:75]
	v_mfma_f32_16x16x32_bf16 v[76:79], v[188:191], v[208:211], v[76:79]
	ds_read_b128 v[160:163], v232 offset:4096
	s_cmp_eq_u32 s24, 0
	s_cbranch_scc0 .Lg11_hi3
	s_setprio 0
; #define LWRITE(S, buf) do { bf16_t* sA_ = sbase + (buf) * BUF; bf16_t* sB_ = sA_ + 256 * PITCH; \
;     _Pragma("unroll") for (int i_ = 0; i_ < 4; ++i_) *(u32x4*)(sA_ + (sr + i_ * 64) * PITCH + scv * 8) = ra[S][i_]; \
;     _Pragma("unroll") for (int i_ = 0; i_ < 2; ++i_) *(u32x4*)(sB_ + (sr + i_ * 64) * PITCH + scv * 8) = rb[S][i_]; } while (0)
; template <class Epi>
; DI void gemm_tile(char* smem, const bf16_t* __restrict__ A0, int lda0, int ksplit, const bf16_t* __restrict__ A1, int lda1,
;                   const bf16_t* __restrict__ Bt, int K, int row0, int col0, const Epi& epi, int tid) {
;     ...
;     for (int kt = 0; kt < nk; kt += 2) {
;       LWRITE(1, 1);
;       __builtin_amdgcn_sched_barrier(0);
;       GLOAD(1, (kt + 3 < last ? kt + 3 : last));
;       __builtin_amdgcn_sched_barrier(0);
;       COMPUTE(0);
;       __syncthreads();
;       LWRITE(0, 0);
;       __builtin_amdgcn_sched_barrier(0);
;       GLOAD(0, (kt + 4 < last ? kt + 4 : last));
;       __builtin_amdgcn_sched_barrier(0);
;       COMPUTE(1);
;       __syncthreads();
;     }
.Lg11_hi3:
	v_mfma_f32_16x16x32_bf16 v[80:83], v[176:179], v[212:215], v[80:83]
	v_mfma_f32_16x16x32_bf16 v[84:87], v[180:183], v[212:215], v[84:87]
	v_mfma_f32_16x16x32_bf16 v[88:91], v[184:187], v[212:215], v[88:91]
	v_mfma_f32_16x16x32_bf16 v[92:95], v[188:191], v[212:215], v[92:95]
	ds_read_b128 v[164:167], v232 offset:5120
	v_mfma_f32_16x16x32_bf16 v[96:99], v[176:179], v[216:219], v[96:99]
	v_mfma_f32_16x16x32_bf16 v[100:103], v[180:183], v[216:219], v[100:103]
	v_mfma_f32_16x16x32_bf16 v[104:107], v[184:187], v[216:219], v[104:107]
	v_mfma_f32_16x16x32_bf16 v[108:111], v[188:191], v[216:219], v[108:111]
	ds_read_b128 v[168:171], v232 offset:6144
	s_add_u32 s30, s30, 24576
	s_cmp_eq_u32 s30, 73728
	s_cselect_b32 s30, 0, s30
	v_mfma_f32_16x16x32_bf16 v[112:115], v[176:179], v[220:223], v[112:115]
	v_mfma_f32_16x16x32_bf16 v[116:119], v[180:183], v[220:223], v[116:119]
	v_mfma_f32_16x16x32_bf16 v[120:123], v[184:187], v[220:223], v[120:123]
	v_mfma_f32_16x16x32_bf16 v[124:127], v[188:191], v[220:223], v[124:127]
	ds_read_b128 v[172:175], v232 offset:7168
	s_waitcnt vmcnt(0)
	s_waitcnt lgkmcnt(0)
	s_barrier
	v_add_u32_e32 v232, s30, v230
	v_add_u32_e32 v233, s30, v231
	s_setprio 1
	v_mfma_f32_16x16x32_bf16 v[0:3], v[128:131], v[144:147], v[0:3]
	v_mfma_f32_16x16x32_bf16 v[4:7], v[132:135], v[144:147], v[4:7]
	v_mfma_f32_16x16x32_bf16 v[8:11], v[136:139], v[144:147], v[8:11]
	v_mfma_f32_16x16x32_bf16 v[12:15], v[140:143], v[144:147], v[12:15]
	ds_read_b128 v[176:179], v233 offset:0
	ds_read_b128 v[180:183], v233 offset:1024
	v_mfma_f32_16x16x32_bf16 v[16:19], v[128:131], v[148:151], v[16:19]
	v_mfma_f32_16x16x32_bf16 v[20:23], v[132:135], v[148:151], v[20:23]
	v_mfma_f32_16x16x32_bf16 v[24:27], v[136:139], v[148:151], v[24:27]
	v_mfma_f32_16x16x32_bf16 v[28:31], v[140:143], v[148:151], v[28:31]
	ds_read_b128 v[184:187], v233 offset:2048
	ds_read_b128 v[188:191], v233 offset:3072
	v_mfma_f32_16x16x32_bf16 v[32:35], v[128:131], v[152:155], v[32:35]
	v_mfma_f32_16x16x32_bf16 v[36:39], v[132:135], v[152:155], v[36:39]
	v_mfma_f32_16x16x32_bf16 v[40:43], v[136:139], v[152:155], v[40:43]
	v_mfma_f32_16x16x32_bf16 v[44:47], v[140:143], v[152:155], v[44:47]
	ds_read_b128 v[192:195], v232 offset:0
	ds_read_b128 v[196:199], v232 offset:1024
	v_mfma_f32_16x16x32_bf16 v[48:51], v[128:131], v[156:159], v[48:51]
	v_mfma_f32_16x16x32_bf16 v[52:55], v[132:135], v[156:159], v[52:55]
	v_mfma_f32_16x16x32_bf16 v[56:59], v[136:139], v[156:159], v[56:59]
	v_mfma_f32_16x16x32_bf16 v[60:63], v[140:143], v[156:159], v[60:63]
	ds_read_b128 v[200:203], v232 offset:2048
	ds_read_b128 v[204:207], v232 offset:3072
	v_mfma_f32_16x16x32_bf16 v[64:67], v[128:131], v[160:163], v[64:67]
	v_mfma_f32_16x16x32_bf16 v[68:71], v[132:135], v[160:163], v[68:71]
	v_mfma_f32_16x16x32_bf16 v[72:75], v[136:139], v[160:163], v[72:75]
	v_mfma_f32_16x16x32_bf16 v[76:79], v[140:143], v[160:163], v[76:79]
	ds_read_b128 v[208:211], v232 offset:4096
	s_cmp_eq_u32 s24, 0
	s_cbranch_scc0 .Lg11_hi4
	s_setprio 0
.Lg11_hi4:
	v_mfma_f32_16x16x32_bf16 v[80:83], v[128:131], v[164:167], v[80:83]
	v_mfma_f32_16x16x32_bf16 v[84:87], v[132:135], v[164:167], v[84:87]
	v_mfma_f32_16x16x32_bf16 v[88:91], v[136:139], v[164:167], v[88:91]
	v_mfma_f32_16x16x32_bf16 v[92:95], v[140:143], v[164:167], v[92:95]
	ds_read_b128 v[212:215], v232 offset:5120
	v_mfma_f32_16x16x32_bf16 v[96:99], v[128:131], v[168:171], v[96:99]
	v_mfma_f32_16x16x32_bf16 v[100:103], v[132:135], v[168:171], v[100:103]
	v_mfma_f32_16x16x32_bf16 v[104:107], v[136:139], v[168:171], v[104:107]
	v_mfma_f32_16x16x32_bf16 v[108:111], v[140:143], v[168:171], v[108:111]
	ds_read_b128 v[216:219], v232 offset:6144
	s_add_u32 s30, s30, 24576
	s_cmp_eq_u32 s30, 73728
	s_cselect_b32 s30, 0, s30
	v_mfma_f32_16x16x32_bf16 v[112:115], v[128:131], v[172:175], v[112:115]
	v_mfma_f32_16x16x32_bf16 v[116:119], v[132:135], v[172:175], v[116:119]
	v_mfma_f32_16x16x32_bf16 v[120:123], v[136:139], v[172:175], v[120:123]
	v_mfma_f32_16x16x32_bf16 v[124:127], v[140:143], v[172:175], v[124:127]
	ds_read_b128 v[220:223], v232 offset:7168
	s_waitcnt lgkmcnt(0)
	s_barrier
	s_setprio 1
	v_mfma_f32_16x16x32_bf16 v[0:3], v[176:179], v[192:195], v[0:3]
	v_mfma_f32_16x16x32_bf16 v[4:7], v[180:183], v[192:195], v[4:7]
	v_mfma_f32_16x16x32_bf16 v[8:11], v[184:187], v[192:195], v[8:11]
	v_mfma_f32_16x16x32_bf16 v[12:15], v[188:191], v[192:195], v[12:15]
	v_mfma_f32_16x16x32_bf16 v[16:19], v[176:179], v[196:199], v[16:19]
	v_mfma_f32_16x16x32_bf16 v[20:23], v[180:183], v[196:199], v[20:23]
	v_mfma_f32_16x16x32_bf16 v[24:27], v[184:187], v[196:199], v[24:27]
	v_mfma_f32_16x16x32_bf16 v[28:31], v[188:191], v[196:199], v[28:31]
	v_mfma_f32_16x16x32_bf16 v[32:35], v[176:179], v[200:203], v[32:35]
	v_mfma_f32_16x16x32_bf16 v[36:39], v[180:183], v[200:203], v[36:39]
	v_mfma_f32_16x16x32_bf16 v[40:43], v[184:187], v[200:203], v[40:43]
	v_mfma_f32_16x16x32_bf16 v[44:47], v[188:191], v[200:203], v[44:47]
	v_mfma_f32_16x16x32_bf16 v[48:51], v[176:179], v[204:207], v[48:51]
	v_mfma_f32_16x16x32_bf16 v[52:55], v[180:183], v[204:207], v[52:55]
	v_mfma_f32_16x16x32_bf16 v[56:59], v[184:187], v[204:207], v[56:59]
	v_mfma_f32_16x16x32_bf16 v[60:63], v[188:191], v[204:207], v[60:63]
	v_mfma_f32_16x16x32_bf16 v[64:67], v[176:179], v[208:211], v[64:67]
	v_mfma_f32_16x16x32_bf16 v[68:71], v[180:183], v[208:211], v[68:71]
	v_mfma_f32_16x16x32_bf16 v[72:75], v[184:187], v[208:211], v[72:75]
	v_mfma_f32_16x16x32_bf16 v[76:79], v[188:191], v[208:211], v[76:79]
	s_cmp_eq_u32 s24, 0
	s_cbranch_scc0 .Lg11_hi5
	s_setprio 0

; #define LWRITE(S, buf) do { bf16_t* sA_ = sbase + (buf) * BUF; bf16_t* sB_ = sA_ + 256 * PITCH; \
;     _Pragma("unroll") for (int i_ = 0; i_ < 4; ++i_) *(u32x4*)(sA_ + (sr + i_ * 64) * PITCH + scv * 8) = ra[S][i_]; \
;     _Pragma("unroll") for (int i_ = 0; i_ < 2; ++i_) *(u32x4*)(sB_ + (sr + i_ * 64) * PITCH + scv * 8) = rb[S][i_]; } while (0)
; template <class Epi>
; DI void gemm_tile(char* smem, const bf16_t* __restrict__ A0, int lda0, int ksplit, const bf16_t* __restrict__ A1, int lda1,
;                   const bf16_t* __restrict__ Bt, int K, int row0, int col0, const Epi& epi, int tid) {
;     ...
;     for (int kt = 0; kt < nk; kt += 2) {
;       LWRITE(1, 1);
;       __builtin_amdgcn_sched_barrier(0);
;       GLOAD(1, (kt + 3 < last ? kt + 3 : last));
;       __builtin_amdgcn_sched_barrier(0);
;       COMPUTE(0);
;       __syncthreads();
;       LWRITE(0, 0);
;       __builtin_amdgcn_sched_barrier(0);
;       GLOAD(0, (kt + 4 < last ? kt + 4 : last));
;       __builtin_amdgcn_sched_barrier(0);
;       COMPUTE(1);
;       __syncthreads();
;     }
.Lg14_hi1:
	v_mfma_f32_16x16x32_bf16 v[80:83], v[176:179], v[212:215], v[80:83]
	v_mfma_f32_16x16x32_bf16 v[84:87], v[180:183], v[212:215], v[84:87]
	v_mfma_f32_16x16x32_bf16 v[88:91], v[184:187], v[212:215], v[88:91]
	v_mfma_f32_16x16x32_bf16 v[92:95], v[188:191], v[212:215], v[92:95]
	ds_read_b128 v[164:167], v232 offset:5120
	s_add_u32 m0, s11, 20480
	s_nop 0
	global_load_lds_dwordx4 v229, s[2:3]
	v_mfma_f32_16x16x32_bf16 v[96:99], v[176:179], v[216:219], v[96:99]
	v_mfma_f32_16x16x32_bf16 v[100:103], v[180:183], v[216:219], v[100:103]
	v_mfma_f32_16x16x32_bf16 v[104:107], v[184:187], v[216:219], v[104:107]
	v_mfma_f32_16x16x32_bf16 v[108:111], v[188:191], v[216:219], v[108:111]
	ds_read_b128 v[168:171], v232 offset:6144
	s_add_u32 s0, s0, 64
	s_addc_u32 s1, s1, 0
	s_add_u32 s2, s2, 64
	s_addc_u32 s3, s3, 0
	s_add_u32 s100, s100, 1
	s_add_u32 s19, s19, 24576
	s_cmp_eq_u32 s19, 73728
	s_cselect_b32 s19, 0, s19
	s_add_u32 s98, s98, 24576
	s_cmp_eq_u32 s98, 73728
	s_cselect_b32 s98, 0, s98
	v_mfma_f32_16x16x32_bf16 v[112:115], v[176:179], v[220:223], v[112:115]
	v_mfma_f32_16x16x32_bf16 v[116:119], v[180:183], v[220:223], v[116:119]
	v_mfma_f32_16x16x32_bf16 v[120:123], v[184:187], v[220:223], v[120:123]
	v_mfma_f32_16x16x32_bf16 v[124:127], v[188:191], v[220:223], v[124:127]
	ds_read_b128 v[172:175], v232 offset:7168
	s_add_u32 s99, s99, 2
	s_cmp_lt_u32 s99, 12
	s_cbranch_scc1 .Lg14_kloop
	s_waitcnt vmcnt(6)
	s_waitcnt lgkmcnt(0)
	s_barrier
	v_add_u32_e32 v232, s98, v230
	v_add_u32_e32 v233, s98, v231
	s_add_u32 s11, s19, s101
	s_setprio 1
	v_mfma_f32_16x16x32_bf16 v[0:3], v[128:131], v[144:147], v[0:3]
	v_mfma_f32_16x16x32_bf16 v[4:7], v[132:135], v[144:147], v[4:7]
	v_mfma_f32_16x16x32_bf16 v[8:11], v[136:139], v[144:147], v[8:11]
	v_mfma_f32_16x16x32_bf16 v[12:15], v[140:143], v[144:147], v[12:15]
	ds_read_b128 v[176:179], v233 offset:0
	ds_read_b128 v[180:183], v233 offset:1024
	s_add_u32 m0, s11, 0
	s_nop 0
	global_load_lds_dwordx4 v224, s[0:1]
	v_mfma_f32_16x16x32_bf16 v[16:19], v[128:131], v[148:151], v[16:19]
	v_mfma_f32_16x16x32_bf16 v[20:23], v[132:135], v[148:151], v[20:23]
	v_mfma_f32_16x16x32_bf16 v[24:27], v[136:139], v[148:151], v[24:27]
	v_mfma_f32_16x16x32_bf16 v[28:31], v[140:143], v[148:151], v[28:31]
	ds_read_b128 v[184:187], v233 offset:2048
	ds_read_b128 v[188:191], v233 offset:3072
	s_add_u32 m0, s11, 4096
	s_nop 0
	global_load_lds_dwordx4 v225, s[0:1]
	v_mfma_f32_16x16x32_bf16 v[32:35], v[128:131], v[152:155], v[32:35]
	v_mfma_f32_16x16x32_bf16 v[36:39], v[132:135], v[152:155], v[36:39]
	v_mfma_f32_16x16x32_bf16 v[40:43], v[136:139], v[152:155], v[40:43]
	v_mfma_f32_16x16x32_bf16 v[44:47], v[140:143], v[152:155], v[44:47]
	ds_read_b128 v[192:195], v232 offset:0
	ds_read_b128 v[196:199], v232 offset:1024
	s_add_u32 m0, s11, 8192
	s_nop 0
	global_load_lds_dwordx4 v226, s[0:1]
	v_mfma_f32_16x16x32_bf16 v[48:51], v[128:131], v[156:159], v[48:51]
	v_mfma_f32_16x16x32_bf16 v[52:55], v[132:135], v[156:159], v[52:55]
	v_mfma_f32_16x16x32_bf16 v[56:59], v[136:139], v[156:159], v[56:59]
	v_mfma_f32_16x16x32_bf16 v[60:63], v[140:143], v[156:159], v[60:63]
	ds_read_b128 v[200:203], v232 offset:2048
	ds_read_b128 v[204:207], v232 offset:3072
	s_add_u32 m0, s11, 12288
	s_nop 0
	global_load_lds_dwordx4 v227, s[0:1]
	v_mfma_f32_16x16x32_bf16 v[64:67], v[128:131], v[160:163], v[64:67]
	v_mfma_f32_16x16x32_bf16 v[68:71], v[132:135], v[160:163], v[68:71]
	v_mfma_f32_16x16x32_bf16 v[72:75], v[136:139], v[160:163], v[72:75]
	v_mfma_f32_16x16x32_bf16 v[76:79], v[140:143], v[160:163], v[76:79]
	ds_read_b128 v[208:211], v232 offset:4096
	s_add_u32 m0, s11, 16384
	s_nop 0
	global_load_lds_dwordx4 v228, s[2:3]
	s_cmp_eq_u32 s10, 0
	s_cbranch_scc0 .Lg14_hi2
	s_setprio 0
